# GLA recurrence loop hand-written (unrolled 64 steps, immediate LDS offsets, 2 operand sets in flight, setprio 3); mixer pairing back to ssd+gla / ret+lru
# baseline (speedup 1.0000x reference)
; #define LAS __attribute__((address_space(3)))
; #define GLA_LD(t_, aq, kq, qq, vq) do { const int tt_ = (t_); vq = Bs[6144 + tt_ * 64 + pp]; \
;             _Pragma("unroll") for (int u = 0; u < 2; ++u) { aq[u] = *(const LAS f32x4*)(Bs + 4096 + tt_ * 32 + k0 + 4 * u); kq[u] = *(const LAS f32x4*)(Bs + 2048 + tt_ * 32 + k0 + 4 * u); qq[u] = *(const LAS f32x4*)(Bs + tt_ * 32 + k0 + 4 * u); } } while (0)
; #define GLA_STEP(t_, aq, kq, qq, vq) do { float y = 0.f; \
;             _Pragma("unroll") for (int u = 0; u < 2; ++u) _Pragma("unroll") for (int j = 0; j < 4; ++j) { S[4 * u + j] = aq[u][j] * S[4 * u + j] + kq[u][j] * vq; y += qq[u][j] * S[4 * u + j]; } \
;             y += dpp_f(y, 0xB1); y += dpp_f(y, 0x4E); ydst[(t_) * ystride] = y; } while (0)
; __device__ __forceinline__ void gla_job(const bf16_t* P, bf16_t* Y, int l, int b, int h, LAS float* lds, int wave_s) {
;     ...
;             LAS float* ydst = (lane & 3) == 0 ? (Yl + (c & 1) * 4096 + pp) : (lds + (LDS_XB + 256) / 4 + lane); const int ystride = (lane & 3) == 0 ? 64 : 0;
;             f32x4 a0_[2], k0_[2], q0_[2], a1_[2], k1_[2], q1_[2]; float v0_, v1_;
;     ...
;             GLA_LD(0, a0_, k0_, q0_, v0_);
;             for (int t = 0; t < TC; t += 2) {
;                 GLA_LD(t + 1, a1_, k1_, q1_, v1_);
;                 GLA_STEP(t, a0_, k0_, q0_, v0_);
;                 GLA_LD(t + 2 < TC ? t + 2 : t + 1, a0_, k0_, q0_, v0_);
;                 GLA_STEP(t + 1, a1_, k1_, q1_, v1_);
;             }
.LBB0_332:
	s_andn2_b64 vcc, exec, s[6:7]
	s_cbranch_vccnz .LBB0_323
	s_waitcnt vmcnt(15)
	v_cndmask_b32_e64 v0, 0, 1, s[8:9]
	s_mov_b32 s6, 0xa000
	v_mul_lo_u32 v0, v0, s6
	v_lshl_add_u32 v173, v132, 2, s15
	v_add_u32_e32 v24, v163, v0
	v_add_u32_e32 v171, v164, v0
	v_lshl_add_u32 v35, s26, 14, v133
	v_lshl_add_u32 v172, v131, 2, s15
	v_cndmask_b32_e64 v174, v156, v35, s[4:5]
	s_setprio 3
	ds_read_b128 v[0:3], v173 offset:16384
	ds_read_b128 v[4:7], v173 offset:16400
	ds_read_b128 v[8:11], v173 offset:8192
	ds_read_b128 v[12:15], v173 offset:8208
	ds_read_b32 v33, v172 offset:24576
	ds_read_b128 v[16:19], v173
	ds_read_b128 v[20:23], v173 offset:16
	ds_read_b128 v[176:179], v173 offset:16512
	ds_read_b128 v[180:183], v173 offset:16528
	ds_read_b128 v[184:187], v173 offset:8320
	ds_read_b128 v[188:191], v173 offset:8336
	ds_read_b32 v200, v172 offset:24832
	ds_read_b128 v[192:195], v173 offset:128
	ds_read_b128 v[196:199], v173 offset:144
	s_waitcnt lgkmcnt(7)
	v_mul_f32_e32 v26, v0, v26
	v_mul_f32_e32 v27, v1, v27
	v_mul_f32_e32 v28, v2, v28
	v_mul_f32_e32 v29, v3, v29
	v_mul_f32_e32 v30, v4, v30
	v_mul_f32_e32 v31, v5, v31
	v_mul_f32_e32 v32, v6, v32
	v_mul_f32_e32 v34, v7, v34
	v_fmac_f32_e32 v26, v8, v33
	v_fmac_f32_e32 v27, v9, v33
	v_fmac_f32_e32 v28, v10, v33
	v_fmac_f32_e32 v29, v11, v33
	v_fmac_f32_e32 v30, v12, v33
	v_fmac_f32_e32 v31, v13, v33
	v_fmac_f32_e32 v32, v14, v33
	v_fmac_f32_e32 v34, v15, v33
	v_mul_f32_e32 v40, v16, v26
	v_mul_f32_e32 v41, v17, v27
	v_fmac_f32_e32 v40, v18, v28
	v_fmac_f32_e32 v41, v19, v29
	v_fmac_f32_e32 v40, v20, v30
	v_fmac_f32_e32 v41, v21, v31
	v_fmac_f32_e32 v40, v22, v32
	v_fmac_f32_e32 v41, v23, v34
	v_add_f32_e32 v35, v40, v41
	s_nop 1
	v_add_f32_dpp v35, v35, v35 quad_perm:[1,0,3,2] row_mask:0xf bank_mask:0xf bound_ctrl:1
	ds_read_b128 v[0:3], v173 offset:16640
	ds_read_b128 v[4:7], v173 offset:16656
	ds_read_b128 v[8:11], v173 offset:8448
	ds_read_b128 v[12:15], v173 offset:8464
	ds_read_b32 v33, v172 offset:25088
	ds_read_b128 v[16:19], v173 offset:256
	ds_read_b128 v[20:23], v173 offset:272
	s_waitcnt lgkmcnt(7)
	v_mul_f32_e32 v26, v176, v26
	v_mul_f32_e32 v27, v177, v27
	v_mul_f32_e32 v28, v178, v28
	v_mul_f32_e32 v29, v179, v29
	v_mul_f32_e32 v30, v180, v30
	v_mul_f32_e32 v31, v181, v31
	v_mul_f32_e32 v32, v182, v32
	v_mul_f32_e32 v34, v183, v34
	v_add_f32_dpp v35, v35, v35 quad_perm:[2,3,0,1] row_mask:0xf bank_mask:0xf bound_ctrl:1
	ds_write_b32 v174, v35
	v_add_u32_e32 v174, v174, v161
	v_fmac_f32_e32 v26, v184, v200
	v_fmac_f32_e32 v27, v185, v200
	v_fmac_f32_e32 v28, v186, v200
	v_fmac_f32_e32 v29, v187, v200
	v_fmac_f32_e32 v30, v188, v200
	v_fmac_f32_e32 v31, v189, v200
	v_fmac_f32_e32 v32, v190, v200
	v_fmac_f32_e32 v34, v191, v200
	v_mul_f32_e32 v40, v192, v26
	v_mul_f32_e32 v41, v193, v27
	v_fmac_f32_e32 v40, v194, v28
	v_fmac_f32_e32 v41, v195, v29
	v_fmac_f32_e32 v40, v196, v30
	v_fmac_f32_e32 v41, v197, v31
	v_fmac_f32_e32 v40, v198, v32
	v_fmac_f32_e32 v41, v199, v34
	v_add_f32_e32 v35, v40, v41
	s_nop 1
	v_add_f32_dpp v35, v35, v35 quad_perm:[1,0,3,2] row_mask:0xf bank_mask:0xf bound_ctrl:1
	ds_read_b128 v[176:179], v173 offset:16768
	ds_read_b128 v[180:183], v173 offset:16784
	ds_read_b128 v[184:187], v173 offset:8576
	ds_read_b128 v[188:191], v173 offset:8592
	ds_read_b32 v200, v172 offset:25344
	ds_read_b128 v[192:195], v173 offset:384
	ds_read_b128 v[196:199], v173 offset:400
	s_waitcnt lgkmcnt(8)
	v_mul_f32_e32 v26, v0, v26
	v_mul_f32_e32 v27, v1, v27
	v_mul_f32_e32 v28, v2, v28
	v_mul_f32_e32 v29, v3, v29
	v_mul_f32_e32 v30, v4, v30
	v_mul_f32_e32 v31, v5, v31
	v_mul_f32_e32 v32, v6, v32
	v_mul_f32_e32 v34, v7, v34
	v_add_f32_dpp v35, v35, v35 quad_perm:[2,3,0,1] row_mask:0xf bank_mask:0xf bound_ctrl:1
	ds_write_b32 v174, v35
	v_add_u32_e32 v174, v174, v161
	v_fmac_f32_e32 v26, v8, v33
	v_fmac_f32_e32 v27, v9, v33
	v_fmac_f32_e32 v28, v10, v33
	v_fmac_f32_e32 v29, v11, v33
	v_fmac_f32_e32 v30, v12, v33
	v_fmac_f32_e32 v31, v13, v33
	v_fmac_f32_e32 v32, v14, v33
	v_fmac_f32_e32 v34, v15, v33
	v_mul_f32_e32 v40, v16, v26
	v_mul_f32_e32 v41, v17, v27
	v_fmac_f32_e32 v40, v18, v28
	v_fmac_f32_e32 v41, v19, v29
	v_fmac_f32_e32 v40, v20, v30
	v_fmac_f32_e32 v41, v21, v31
	v_fmac_f32_e32 v40, v22, v32
	v_fmac_f32_e32 v41, v23, v34
	v_add_f32_e32 v35, v40, v41
	s_nop 1
	v_add_f32_dpp v35, v35, v35 quad_perm:[1,0,3,2] row_mask:0xf bank_mask:0xf bound_ctrl:1
	ds_read_b128 v[0:3], v173 offset:16896
	ds_read_b128 v[4:7], v173 offset:16912
	ds_read_b128 v[8:11], v173 offset:8704
	ds_read_b128 v[12:15], v173 offset:8720
	ds_read_b32 v33, v172 offset:25600
	ds_read_b128 v[16:19], v173 offset:512
	ds_read_b128 v[20:23], v173 offset:528
	s_waitcnt lgkmcnt(8)
	v_mul_f32_e32 v26, v176, v26
	v_mul_f32_e32 v27, v177, v27
	v_mul_f32_e32 v28, v178, v28
	v_mul_f32_e32 v29, v179, v29
	v_mul_f32_e32 v30, v180, v30
	v_mul_f32_e32 v31, v181, v31
	v_mul_f32_e32 v32, v182, v32
	v_mul_f32_e32 v34, v183, v34
	v_add_f32_dpp v35, v35, v35 quad_perm:[2,3,0,1] row_mask:0xf bank_mask:0xf bound_ctrl:1
	ds_write_b32 v174, v35
	v_add_u32_e32 v174, v174, v161
	v_fmac_f32_e32 v26, v184, v200
	v_fmac_f32_e32 v27, v185, v200
	v_fmac_f32_e32 v28, v186, v200
	v_fmac_f32_e32 v29, v187, v200
	v_fmac_f32_e32 v30, v188, v200
	v_fmac_f32_e32 v31, v189, v200
	v_fmac_f32_e32 v32, v190, v200
	v_fmac_f32_e32 v34, v191, v200
	v_mul_f32_e32 v40, v192, v26
	v_mul_f32_e32 v41, v193, v27
	v_fmac_f32_e32 v40, v194, v28
	v_fmac_f32_e32 v41, v195, v29
	v_fmac_f32_e32 v40, v196, v30
	v_fmac_f32_e32 v41, v197, v31
	v_fmac_f32_e32 v40, v198, v32
	v_fmac_f32_e32 v41, v199, v34
	v_add_f32_e32 v35, v40, v41
	s_nop 1
	v_add_f32_dpp v35, v35, v35 quad_perm:[1,0,3,2] row_mask:0xf bank_mask:0xf bound_ctrl:1
	ds_read_b128 v[176:179], v173 offset:17024
	ds_read_b128 v[180:183], v173 offset:17040
	ds_read_b128 v[184:187], v173 offset:8832
	ds_read_b128 v[188:191], v173 offset:8848
	ds_read_b32 v200, v172 offset:25856
	ds_read_b128 v[192:195], v173 offset:640
	ds_read_b128 v[196:199], v173 offset:656
	s_waitcnt lgkmcnt(8)
	v_mul_f32_e32 v26, v0, v26
	v_mul_f32_e32 v27, v1, v27
	v_mul_f32_e32 v28, v2, v28
	v_mul_f32_e32 v29, v3, v29
	v_mul_f32_e32 v30, v4, v30
	v_mul_f32_e32 v31, v5, v31
	v_mul_f32_e32 v32, v6, v32
	v_mul_f32_e32 v34, v7, v34
	v_add_f32_dpp v35, v35, v35 quad_perm:[2,3,0,1] row_mask:0xf bank_mask:0xf bound_ctrl:1
	ds_write_b32 v174, v35
	v_add_u32_e32 v174, v174, v161
	v_fmac_f32_e32 v26, v8, v33
	v_fmac_f32_e32 v27, v9, v33
	v_fmac_f32_e32 v28, v10, v33
	v_fmac_f32_e32 v29, v11, v33
	v_fmac_f32_e32 v30, v12, v33
	v_fmac_f32_e32 v31, v13, v33
	v_fmac_f32_e32 v32, v14, v33
	v_fmac_f32_e32 v34, v15, v33
	v_mul_f32_e32 v40, v16, v26
	v_mul_f32_e32 v41, v17, v27
	v_fmac_f32_e32 v40, v18, v28
	v_fmac_f32_e32 v41, v19, v29
	v_fmac_f32_e32 v40, v20, v30
	v_fmac_f32_e32 v41, v21, v31
	v_fmac_f32_e32 v40, v22, v32
	v_fmac_f32_e32 v41, v23, v34
	v_add_f32_e32 v35, v40, v41
	s_nop 1
	v_add_f32_dpp v35, v35, v35 quad_perm:[1,0,3,2] row_mask:0xf bank_mask:0xf bound_ctrl:1
	ds_read_b128 v[0:3], v173 offset:17152
	ds_read_b128 v[4:7], v173 offset:17168
	ds_read_b128 v[8:11], v173 offset:8960
	ds_read_b128 v[12:15], v173 offset:8976
	ds_read_b32 v33, v172 offset:26112
	ds_read_b128 v[16:19], v173 offset:768
	ds_read_b128 v[20:23], v173 offset:784
	s_waitcnt lgkmcnt(8)
	v_mul_f32_e32 v26, v176, v26
	v_mul_f32_e32 v27, v177, v27
	v_mul_f32_e32 v28, v178, v28
	v_mul_f32_e32 v29, v179, v29
	v_mul_f32_e32 v30, v180, v30
	v_mul_f32_e32 v31, v181, v31
	v_mul_f32_e32 v32, v182, v32
	v_mul_f32_e32 v34, v183, v34
	v_add_f32_dpp v35, v35, v35 quad_perm:[2,3,0,1] row_mask:0xf bank_mask:0xf bound_ctrl:1
	ds_write_b32 v174, v35
	v_add_u32_e32 v174, v174, v161
	v_fmac_f32_e32 v26, v184, v200
	v_fmac_f32_e32 v27, v185, v200
	v_fmac_f32_e32 v28, v186, v200
	v_fmac_f32_e32 v29, v187, v200
	v_fmac_f32_e32 v30, v188, v200
	v_fmac_f32_e32 v31, v189, v200
	v_fmac_f32_e32 v32, v190, v200
	v_fmac_f32_e32 v34, v191, v200
	v_mul_f32_e32 v40, v192, v26
	v_mul_f32_e32 v41, v193, v27
	v_fmac_f32_e32 v40, v194, v28
	v_fmac_f32_e32 v41, v195, v29
	v_fmac_f32_e32 v40, v196, v30
	v_fmac_f32_e32 v41, v197, v31
	v_fmac_f32_e32 v40, v198, v32
	v_fmac_f32_e32 v41, v199, v34
	v_add_f32_e32 v35, v40, v41
	s_nop 1
	v_add_f32_dpp v35, v35, v35 quad_perm:[1,0,3,2] row_mask:0xf bank_mask:0xf bound_ctrl:1
	ds_read_b128 v[176:179], v173 offset:17280
	ds_read_b128 v[180:183], v173 offset:17296
	ds_read_b128 v[184:187], v173 offset:9088
	ds_read_b128 v[188:191], v173 offset:9104
	ds_read_b32 v200, v172 offset:26368
	ds_read_b128 v[192:195], v173 offset:896
	ds_read_b128 v[196:199], v173 offset:912
	s_waitcnt lgkmcnt(8)
	v_mul_f32_e32 v26, v0, v26
	v_mul_f32_e32 v27, v1, v27
	v_mul_f32_e32 v28, v2, v28
	v_mul_f32_e32 v29, v3, v29
	v_mul_f32_e32 v30, v4, v30
	v_mul_f32_e32 v31, v5, v31
	v_mul_f32_e32 v32, v6, v32
	v_mul_f32_e32 v34, v7, v34
	v_add_f32_dpp v35, v35, v35 quad_perm:[2,3,0,1] row_mask:0xf bank_mask:0xf bound_ctrl:1
	ds_write_b32 v174, v35
	v_add_u32_e32 v174, v174, v161
	v_fmac_f32_e32 v26, v8, v33
	v_fmac_f32_e32 v27, v9, v33
	v_fmac_f32_e32 v28, v10, v33
	v_fmac_f32_e32 v29, v11, v33
	v_fmac_f32_e32 v30, v12, v33
	v_fmac_f32_e32 v31, v13, v33
	v_fmac_f32_e32 v32, v14, v33
	v_fmac_f32_e32 v34, v15, v33
	v_mul_f32_e32 v40, v16, v26
	v_mul_f32_e32 v41, v17, v27
	v_fmac_f32_e32 v40, v18, v28
	v_fmac_f32_e32 v41, v19, v29
	v_fmac_f32_e32 v40, v20, v30
	v_fmac_f32_e32 v41, v21, v31
	v_fmac_f32_e32 v40, v22, v32
	v_fmac_f32_e32 v41, v23, v34
	v_add_f32_e32 v35, v40, v41
	s_nop 1
	v_add_f32_dpp v35, v35, v35 quad_perm:[1,0,3,2] row_mask:0xf bank_mask:0xf bound_ctrl:1
	ds_read_b128 v[0:3], v173 offset:17408
	ds_read_b128 v[4:7], v173 offset:17424
	ds_read_b128 v[8:11], v173 offset:9216
	ds_read_b128 v[12:15], v173 offset:9232
	ds_read_b32 v33, v172 offset:26624
	ds_read_b128 v[16:19], v173 offset:1024
	ds_read_b128 v[20:23], v173 offset:1040
	s_waitcnt lgkmcnt(8)
	v_mul_f32_e32 v26, v176, v26
	v_mul_f32_e32 v27, v177, v27
	v_mul_f32_e32 v28, v178, v28
	v_mul_f32_e32 v29, v179, v29
	v_mul_f32_e32 v30, v180, v30
	v_mul_f32_e32 v31, v181, v31
	v_mul_f32_e32 v32, v182, v32
	v_mul_f32_e32 v34, v183, v34
	v_add_f32_dpp v35, v35, v35 quad_perm:[2,3,0,1] row_mask:0xf bank_mask:0xf bound_ctrl:1
	ds_write_b32 v174, v35
	v_add_u32_e32 v174, v174, v161
	v_fmac_f32_e32 v26, v184, v200
	v_fmac_f32_e32 v27, v185, v200
	v_fmac_f32_e32 v28, v186, v200
	v_fmac_f32_e32 v29, v187, v200
	v_fmac_f32_e32 v30, v188, v200
	v_fmac_f32_e32 v31, v189, v200
	v_fmac_f32_e32 v32, v190, v200
	v_fmac_f32_e32 v34, v191, v200
	v_mul_f32_e32 v40, v192, v26
	v_mul_f32_e32 v41, v193, v27
	v_fmac_f32_e32 v40, v194, v28
	v_fmac_f32_e32 v41, v195, v29
	v_fmac_f32_e32 v40, v196, v30
	v_fmac_f32_e32 v41, v197, v31
	v_fmac_f32_e32 v40, v198, v32
	v_fmac_f32_e32 v41, v199, v34
	v_add_f32_e32 v35, v40, v41
	s_nop 1
	v_add_f32_dpp v35, v35, v35 quad_perm:[1,0,3,2] row_mask:0xf bank_mask:0xf bound_ctrl:1
	ds_read_b128 v[176:179], v173 offset:17536
	ds_read_b128 v[180:183], v173 offset:17552
	ds_read_b128 v[184:187], v173 offset:9344
	ds_read_b128 v[188:191], v173 offset:9360
	ds_read_b32 v200, v172 offset:26880
	ds_read_b128 v[192:195], v173 offset:1152
	ds_read_b128 v[196:199], v173 offset:1168
	s_waitcnt lgkmcnt(8)
	v_mul_f32_e32 v26, v0, v26
	v_mul_f32_e32 v27, v1, v27
	v_mul_f32_e32 v28, v2, v28
	v_mul_f32_e32 v29, v3, v29
	v_mul_f32_e32 v30, v4, v30
	v_mul_f32_e32 v31, v5, v31
	v_mul_f32_e32 v32, v6, v32
	v_mul_f32_e32 v34, v7, v34
	v_add_f32_dpp v35, v35, v35 quad_perm:[2,3,0,1] row_mask:0xf bank_mask:0xf bound_ctrl:1
	ds_write_b32 v174, v35
	v_add_u32_e32 v174, v174, v161
	v_fmac_f32_e32 v26, v8, v33
	v_fmac_f32_e32 v27, v9, v33
	v_fmac_f32_e32 v28, v10, v33
	v_fmac_f32_e32 v29, v11, v33
	v_fmac_f32_e32 v30, v12, v33
	v_fmac_f32_e32 v31, v13, v33
	v_fmac_f32_e32 v32, v14, v33
	v_fmac_f32_e32 v34, v15, v33
	v_mul_f32_e32 v40, v16, v26
	v_mul_f32_e32 v41, v17, v27
	v_fmac_f32_e32 v40, v18, v28
	v_fmac_f32_e32 v41, v19, v29
	v_fmac_f32_e32 v40, v20, v30
	v_fmac_f32_e32 v41, v21, v31
	v_fmac_f32_e32 v40, v22, v32
	v_fmac_f32_e32 v41, v23, v34
	v_add_f32_e32 v35, v40, v41
	s_nop 1
	v_add_f32_dpp v35, v35, v35 quad_perm:[1,0,3,2] row_mask:0xf bank_mask:0xf bound_ctrl:1
	ds_read_b128 v[0:3], v173 offset:17664
	ds_read_b128 v[4:7], v173 offset:17680
	ds_read_b128 v[8:11], v173 offset:9472
	ds_read_b128 v[12:15], v173 offset:9488
	ds_read_b32 v33, v172 offset:27136
	ds_read_b128 v[16:19], v173 offset:1280
	ds_read_b128 v[20:23], v173 offset:1296
	s_waitcnt lgkmcnt(8)
	v_mul_f32_e32 v26, v176, v26
	v_mul_f32_e32 v27, v177, v27
	v_mul_f32_e32 v28, v178, v28
	v_mul_f32_e32 v29, v179, v29
	v_mul_f32_e32 v30, v180, v30
	v_mul_f32_e32 v31, v181, v31
	v_mul_f32_e32 v32, v182, v32
	v_mul_f32_e32 v34, v183, v34
	v_add_f32_dpp v35, v35, v35 quad_perm:[2,3,0,1] row_mask:0xf bank_mask:0xf bound_ctrl:1
	ds_write_b32 v174, v35
	v_add_u32_e32 v174, v174, v161
	v_fmac_f32_e32 v26, v184, v200
	v_fmac_f32_e32 v27, v185, v200
	v_fmac_f32_e32 v28, v186, v200
	v_fmac_f32_e32 v29, v187, v200
	v_fmac_f32_e32 v30, v188, v200
	v_fmac_f32_e32 v31, v189, v200
	v_fmac_f32_e32 v32, v190, v200
	v_fmac_f32_e32 v34, v191, v200
	v_mul_f32_e32 v40, v192, v26
	v_mul_f32_e32 v41, v193, v27
	v_fmac_f32_e32 v40, v194, v28
	v_fmac_f32_e32 v41, v195, v29
	v_fmac_f32_e32 v40, v196, v30
	v_fmac_f32_e32 v41, v197, v31
	v_fmac_f32_e32 v40, v198, v32
	v_fmac_f32_e32 v41, v199, v34
	v_add_f32_e32 v35, v40, v41
	s_nop 1
	v_add_f32_dpp v35, v35, v35 quad_perm:[1,0,3,2] row_mask:0xf bank_mask:0xf bound_ctrl:1
	ds_read_b128 v[176:179], v173 offset:17792
	ds_read_b128 v[180:183], v173 offset:17808
	ds_read_b128 v[184:187], v173 offset:9600
	ds_read_b128 v[188:191], v173 offset:9616
	ds_read_b32 v200, v172 offset:27392
	ds_read_b128 v[192:195], v173 offset:1408
	ds_read_b128 v[196:199], v173 offset:1424
	s_waitcnt lgkmcnt(8)
	v_mul_f32_e32 v26, v0, v26
	v_mul_f32_e32 v27, v1, v27
	v_mul_f32_e32 v28, v2, v28
	v_mul_f32_e32 v29, v3, v29
	v_mul_f32_e32 v30, v4, v30
	v_mul_f32_e32 v31, v5, v31
	v_mul_f32_e32 v32, v6, v32
	v_mul_f32_e32 v34, v7, v34
	v_add_f32_dpp v35, v35, v35 quad_perm:[2,3,0,1] row_mask:0xf bank_mask:0xf bound_ctrl:1
	ds_write_b32 v174, v35
	v_add_u32_e32 v174, v174, v161
	v_fmac_f32_e32 v26, v8, v33
	v_fmac_f32_e32 v27, v9, v33
	v_fmac_f32_e32 v28, v10, v33
	v_fmac_f32_e32 v29, v11, v33
	v_fmac_f32_e32 v30, v12, v33
	v_fmac_f32_e32 v31, v13, v33
	v_fmac_f32_e32 v32, v14, v33
	v_fmac_f32_e32 v34, v15, v33
	v_mul_f32_e32 v40, v16, v26
	v_mul_f32_e32 v41, v17, v27
	v_fmac_f32_e32 v40, v18, v28
	v_fmac_f32_e32 v41, v19, v29
	v_fmac_f32_e32 v40, v20, v30
	v_fmac_f32_e32 v41, v21, v31
	v_fmac_f32_e32 v40, v22, v32
	v_fmac_f32_e32 v41, v23, v34
	v_add_f32_e32 v35, v40, v41
	s_nop 1
	v_add_f32_dpp v35, v35, v35 quad_perm:[1,0,3,2] row_mask:0xf bank_mask:0xf bound_ctrl:1
	ds_read_b128 v[0:3], v173 offset:17920
	ds_read_b128 v[4:7], v173 offset:17936
	ds_read_b128 v[8:11], v173 offset:9728
	ds_read_b128 v[12:15], v173 offset:9744
	ds_read_b32 v33, v172 offset:27648
	ds_read_b128 v[16:19], v173 offset:1536
	ds_read_b128 v[20:23], v173 offset:1552
	s_waitcnt lgkmcnt(8)
	v_mul_f32_e32 v26, v176, v26
	v_mul_f32_e32 v27, v177, v27
	v_mul_f32_e32 v28, v178, v28
	v_mul_f32_e32 v29, v179, v29
	v_mul_f32_e32 v30, v180, v30
	v_mul_f32_e32 v31, v181, v31
	v_mul_f32_e32 v32, v182, v32
	v_mul_f32_e32 v34, v183, v34
	v_add_f32_dpp v35, v35, v35 quad_perm:[2,3,0,1] row_mask:0xf bank_mask:0xf bound_ctrl:1
	ds_write_b32 v174, v35
	v_add_u32_e32 v174, v174, v161
	v_fmac_f32_e32 v26, v184, v200
	v_fmac_f32_e32 v27, v185, v200
	v_fmac_f32_e32 v28, v186, v200
	v_fmac_f32_e32 v29, v187, v200
	v_fmac_f32_e32 v30, v188, v200
	v_fmac_f32_e32 v31, v189, v200
	v_fmac_f32_e32 v32, v190, v200
	v_fmac_f32_e32 v34, v191, v200
	v_mul_f32_e32 v40, v192, v26
	v_mul_f32_e32 v41, v193, v27
	v_fmac_f32_e32 v40, v194, v28
	v_fmac_f32_e32 v41, v195, v29
	v_fmac_f32_e32 v40, v196, v30
	v_fmac_f32_e32 v41, v197, v31
	v_fmac_f32_e32 v40, v198, v32
	v_fmac_f32_e32 v41, v199, v34
	v_add_f32_e32 v35, v40, v41
	s_nop 1
	v_add_f32_dpp v35, v35, v35 quad_perm:[1,0,3,2] row_mask:0xf bank_mask:0xf bound_ctrl:1
	ds_read_b128 v[176:179], v173 offset:18048
	ds_read_b128 v[180:183], v173 offset:18064
	ds_read_b128 v[184:187], v173 offset:9856
	ds_read_b128 v[188:191], v173 offset:9872
	ds_read_b32 v200, v172 offset:27904
	ds_read_b128 v[192:195], v173 offset:1664
	ds_read_b128 v[196:199], v173 offset:1680
	s_waitcnt lgkmcnt(8)
; #define GLA_LD(t_, aq, kq, qq, vq) do { const int tt_ = (t_); vq = Bs[6144 + tt_ * 64 + pp]; \
;             _Pragma("unroll") for (int u = 0; u < 2; ++u) { aq[u] = *(const LAS f32x4*)(Bs + 4096 + tt_ * 32 + k0 + 4 * u); kq[u] = *(const LAS f32x4*)(Bs + 2048 + tt_ * 32 + k0 + 4 * u); qq[u] = *(const LAS f32x4*)(Bs + tt_ * 32 + k0 + 4 * u); } } while (0)
; #define GLA_STEP(t_, aq, kq, qq, vq) do { float y = 0.f; \
;             _Pragma("unroll") for (int u = 0; u < 2; ++u) _Pragma("unroll") for (int j = 0; j < 4; ++j) { S[4 * u + j] = aq[u][j] * S[4 * u + j] + kq[u][j] * vq; y += qq[u][j] * S[4 * u + j]; } \
;             y += dpp_f(y, 0xB1); y += dpp_f(y, 0x4E); ydst[(t_) * ystride] = y; } while (0)
; __device__ __forceinline__ void gla_job(const bf16_t* P, bf16_t* Y, int l, int b, int h, LAS float* lds, int wave_s) {
;     ...
;             GLA_LD(0, a0_, k0_, q0_, v0_);
;             for (int t = 0; t < TC; t += 2) {
;                 GLA_LD(t + 1, a1_, k1_, q1_, v1_);
;                 GLA_STEP(t, a0_, k0_, q0_, v0_);
;                 GLA_LD(t + 2 < TC ? t + 2 : t + 1, a0_, k0_, q0_, v0_);
;                 GLA_STEP(t + 1, a1_, k1_, q1_, v1_);
	v_mul_f32_e32 v26, v0, v26
	v_mul_f32_e32 v27, v1, v27
	v_mul_f32_e32 v28, v2, v28
	v_mul_f32_e32 v29, v3, v29
	v_mul_f32_e32 v30, v4, v30
	v_mul_f32_e32 v31, v5, v31
	v_mul_f32_e32 v32, v6, v32
	v_mul_f32_e32 v34, v7, v34
	v_add_f32_dpp v35, v35, v35 quad_perm:[2,3,0,1] row_mask:0xf bank_mask:0xf bound_ctrl:1
	ds_write_b32 v174, v35
	v_add_u32_e32 v174, v174, v161
	v_fmac_f32_e32 v26, v8, v33
	v_fmac_f32_e32 v27, v9, v33
	v_fmac_f32_e32 v28, v10, v33
	v_fmac_f32_e32 v29, v11, v33
	v_fmac_f32_e32 v30, v12, v33
	v_fmac_f32_e32 v31, v13, v33
	v_fmac_f32_e32 v32, v14, v33
	v_fmac_f32_e32 v34, v15, v33
	v_mul_f32_e32 v40, v16, v26
	v_mul_f32_e32 v41, v17, v27
	v_fmac_f32_e32 v40, v18, v28
	v_fmac_f32_e32 v41, v19, v29
	v_fmac_f32_e32 v40, v20, v30
	v_fmac_f32_e32 v41, v21, v31
	v_fmac_f32_e32 v40, v22, v32
	v_fmac_f32_e32 v41, v23, v34
	v_add_f32_e32 v35, v40, v41
	s_nop 1
	v_add_f32_dpp v35, v35, v35 quad_perm:[1,0,3,2] row_mask:0xf bank_mask:0xf bound_ctrl:1
	ds_read_b128 v[0:3], v173 offset:18176
	ds_read_b128 v[4:7], v173 offset:18192
	ds_read_b128 v[8:11], v173 offset:9984
	ds_read_b128 v[12:15], v173 offset:10000
	ds_read_b32 v33, v172 offset:28160
	ds_read_b128 v[16:19], v173 offset:1792
	ds_read_b128 v[20:23], v173 offset:1808
	s_waitcnt lgkmcnt(8)
	v_mul_f32_e32 v26, v176, v26
	v_mul_f32_e32 v27, v177, v27
	v_mul_f32_e32 v28, v178, v28
	v_mul_f32_e32 v29, v179, v29
	v_mul_f32_e32 v30, v180, v30
	v_mul_f32_e32 v31, v181, v31
	v_mul_f32_e32 v32, v182, v32
	v_mul_f32_e32 v34, v183, v34
	v_add_f32_dpp v35, v35, v35 quad_perm:[2,3,0,1] row_mask:0xf bank_mask:0xf bound_ctrl:1
	ds_write_b32 v174, v35
	v_add_u32_e32 v174, v174, v161
	v_fmac_f32_e32 v26, v184, v200
	v_fmac_f32_e32 v27, v185, v200
	v_fmac_f32_e32 v28, v186, v200
	v_fmac_f32_e32 v29, v187, v200
	v_fmac_f32_e32 v30, v188, v200
	v_fmac_f32_e32 v31, v189, v200
	v_fmac_f32_e32 v32, v190, v200
	v_fmac_f32_e32 v34, v191, v200
	v_mul_f32_e32 v40, v192, v26
	v_mul_f32_e32 v41, v193, v27
	v_fmac_f32_e32 v40, v194, v28
	v_fmac_f32_e32 v41, v195, v29
	v_fmac_f32_e32 v40, v196, v30
	v_fmac_f32_e32 v41, v197, v31
	v_fmac_f32_e32 v40, v198, v32
	v_fmac_f32_e32 v41, v199, v34
	v_add_f32_e32 v35, v40, v41
	s_nop 1
	v_add_f32_dpp v35, v35, v35 quad_perm:[1,0,3,2] row_mask:0xf bank_mask:0xf bound_ctrl:1
	ds_read_b128 v[176:179], v173 offset:18304
	ds_read_b128 v[180:183], v173 offset:18320
	ds_read_b128 v[184:187], v173 offset:10112
	ds_read_b128 v[188:191], v173 offset:10128
	ds_read_b32 v200, v172 offset:28416
	ds_read_b128 v[192:195], v173 offset:1920
	ds_read_b128 v[196:199], v173 offset:1936
	s_waitcnt lgkmcnt(8)
	v_mul_f32_e32 v26, v0, v26
	v_mul_f32_e32 v27, v1, v27
	v_mul_f32_e32 v28, v2, v28
	v_mul_f32_e32 v29, v3, v29
	v_mul_f32_e32 v30, v4, v30
	v_mul_f32_e32 v31, v5, v31
	v_mul_f32_e32 v32, v6, v32
	v_mul_f32_e32 v34, v7, v34
	v_add_f32_dpp v35, v35, v35 quad_perm:[2,3,0,1] row_mask:0xf bank_mask:0xf bound_ctrl:1
	ds_write_b32 v174, v35
	v_add_u32_e32 v174, v174, v161
	v_fmac_f32_e32 v26, v8, v33
	v_fmac_f32_e32 v27, v9, v33
	v_fmac_f32_e32 v28, v10, v33
	v_fmac_f32_e32 v29, v11, v33
	v_fmac_f32_e32 v30, v12, v33
	v_fmac_f32_e32 v31, v13, v33
	v_fmac_f32_e32 v32, v14, v33
	v_fmac_f32_e32 v34, v15, v33
	v_mul_f32_e32 v40, v16, v26
	v_mul_f32_e32 v41, v17, v27
	v_fmac_f32_e32 v40, v18, v28
	v_fmac_f32_e32 v41, v19, v29
	v_fmac_f32_e32 v40, v20, v30
	v_fmac_f32_e32 v41, v21, v31
	v_fmac_f32_e32 v40, v22, v32
	v_fmac_f32_e32 v41, v23, v34
	v_add_f32_e32 v35, v40, v41
	s_nop 1
	v_add_f32_dpp v35, v35, v35 quad_perm:[1,0,3,2] row_mask:0xf bank_mask:0xf bound_ctrl:1
	ds_read_b128 v[0:3], v173 offset:18432
	ds_read_b128 v[4:7], v173 offset:18448
	ds_read_b128 v[8:11], v173 offset:10240
	ds_read_b128 v[12:15], v173 offset:10256
	ds_read_b32 v33, v172 offset:28672
	ds_read_b128 v[16:19], v173 offset:2048
	ds_read_b128 v[20:23], v173 offset:2064
	s_waitcnt lgkmcnt(8)
	v_mul_f32_e32 v26, v176, v26
	v_mul_f32_e32 v27, v177, v27
	v_mul_f32_e32 v28, v178, v28
	v_mul_f32_e32 v29, v179, v29
	v_mul_f32_e32 v30, v180, v30
	v_mul_f32_e32 v31, v181, v31
	v_mul_f32_e32 v32, v182, v32
	v_mul_f32_e32 v34, v183, v34
	v_add_f32_dpp v35, v35, v35 quad_perm:[2,3,0,1] row_mask:0xf bank_mask:0xf bound_ctrl:1
	ds_write_b32 v174, v35
	v_add_u32_e32 v174, v174, v161
	v_fmac_f32_e32 v26, v184, v200
	v_fmac_f32_e32 v27, v185, v200
	v_fmac_f32_e32 v28, v186, v200
	v_fmac_f32_e32 v29, v187, v200
	v_fmac_f32_e32 v30, v188, v200
	v_fmac_f32_e32 v31, v189, v200
	v_fmac_f32_e32 v32, v190, v200
	v_fmac_f32_e32 v34, v191, v200
	v_mul_f32_e32 v40, v192, v26
	v_mul_f32_e32 v41, v193, v27
	v_fmac_f32_e32 v40, v194, v28
	v_fmac_f32_e32 v41, v195, v29
	v_fmac_f32_e32 v40, v196, v30
	v_fmac_f32_e32 v41, v197, v31
	v_fmac_f32_e32 v40, v198, v32
	v_fmac_f32_e32 v41, v199, v34
	v_add_f32_e32 v35, v40, v41
	s_nop 1
	v_add_f32_dpp v35, v35, v35 quad_perm:[1,0,3,2] row_mask:0xf bank_mask:0xf bound_ctrl:1
	ds_read_b128 v[176:179], v173 offset:18560
	ds_read_b128 v[180:183], v173 offset:18576
	ds_read_b128 v[184:187], v173 offset:10368
	ds_read_b128 v[188:191], v173 offset:10384
	ds_read_b32 v200, v172 offset:28928
	ds_read_b128 v[192:195], v173 offset:2176
	ds_read_b128 v[196:199], v173 offset:2192
	s_waitcnt lgkmcnt(8)
; #define GLA_LD(t_, aq, kq, qq, vq) do { const int tt_ = (t_); vq = Bs[6144 + tt_ * 64 + pp]; \
;             _Pragma("unroll") for (int u = 0; u < 2; ++u) { aq[u] = *(const LAS f32x4*)(Bs + 4096 + tt_ * 32 + k0 + 4 * u); kq[u] = *(const LAS f32x4*)(Bs + 2048 + tt_ * 32 + k0 + 4 * u); qq[u] = *(const LAS f32x4*)(Bs + tt_ * 32 + k0 + 4 * u); } } while (0)
; #define GLA_STEP(t_, aq, kq, qq, vq) do { float y = 0.f; \
;             _Pragma("unroll") for (int u = 0; u < 2; ++u) _Pragma("unroll") for (int j = 0; j < 4; ++j) { S[4 * u + j] = aq[u][j] * S[4 * u + j] + kq[u][j] * vq; y += qq[u][j] * S[4 * u + j]; } \
;             y += dpp_f(y, 0xB1); y += dpp_f(y, 0x4E); ydst[(t_) * ystride] = y; } while (0)
; __device__ __forceinline__ void gla_job(const bf16_t* P, bf16_t* Y, int l, int b, int h, LAS float* lds, int wave_s) {
;     ...
;             GLA_LD(0, a0_, k0_, q0_, v0_);
;             for (int t = 0; t < TC; t += 2) {
;                 GLA_LD(t + 1, a1_, k1_, q1_, v1_);
;                 GLA_STEP(t, a0_, k0_, q0_, v0_);
;                 GLA_LD(t + 2 < TC ? t + 2 : t + 1, a0_, k0_, q0_, v0_);
;                 GLA_STEP(t + 1, a1_, k1_, q1_, v1_);
	v_mul_f32_e32 v26, v0, v26
	v_mul_f32_e32 v27, v1, v27
	v_mul_f32_e32 v28, v2, v28
	v_mul_f32_e32 v29, v3, v29
	v_mul_f32_e32 v30, v4, v30
	v_mul_f32_e32 v31, v5, v31
	v_mul_f32_e32 v32, v6, v32
	v_mul_f32_e32 v34, v7, v34
	v_add_f32_dpp v35, v35, v35 quad_perm:[2,3,0,1] row_mask:0xf bank_mask:0xf bound_ctrl:1
	ds_write_b32 v174, v35
	v_add_u32_e32 v174, v174, v161
	v_fmac_f32_e32 v26, v8, v33
	v_fmac_f32_e32 v27, v9, v33
	v_fmac_f32_e32 v28, v10, v33
	v_fmac_f32_e32 v29, v11, v33
	v_fmac_f32_e32 v30, v12, v33
	v_fmac_f32_e32 v31, v13, v33
	v_fmac_f32_e32 v32, v14, v33
	v_fmac_f32_e32 v34, v15, v33
	v_mul_f32_e32 v40, v16, v26
	v_mul_f32_e32 v41, v17, v27
	v_fmac_f32_e32 v40, v18, v28
	v_fmac_f32_e32 v41, v19, v29
	v_fmac_f32_e32 v40, v20, v30
	v_fmac_f32_e32 v41, v21, v31
	v_fmac_f32_e32 v40, v22, v32
	v_fmac_f32_e32 v41, v23, v34
	v_add_f32_e32 v35, v40, v41
	s_nop 1
	v_add_f32_dpp v35, v35, v35 quad_perm:[1,0,3,2] row_mask:0xf bank_mask:0xf bound_ctrl:1
	ds_read_b128 v[0:3], v173 offset:18688
	ds_read_b128 v[4:7], v173 offset:18704
	ds_read_b128 v[8:11], v173 offset:10496
	ds_read_b128 v[12:15], v173 offset:10512
	ds_read_b32 v33, v172 offset:29184
	ds_read_b128 v[16:19], v173 offset:2304
	ds_read_b128 v[20:23], v173 offset:2320
	s_waitcnt lgkmcnt(8)
	v_mul_f32_e32 v26, v176, v26
	v_mul_f32_e32 v27, v177, v27
	v_mul_f32_e32 v28, v178, v28
	v_mul_f32_e32 v29, v179, v29
	v_mul_f32_e32 v30, v180, v30
	v_mul_f32_e32 v31, v181, v31
	v_mul_f32_e32 v32, v182, v32
	v_mul_f32_e32 v34, v183, v34
	v_add_f32_dpp v35, v35, v35 quad_perm:[2,3,0,1] row_mask:0xf bank_mask:0xf bound_ctrl:1
	ds_write_b32 v174, v35
	v_add_u32_e32 v174, v174, v161
	v_fmac_f32_e32 v26, v184, v200
	v_fmac_f32_e32 v27, v185, v200
	v_fmac_f32_e32 v28, v186, v200
	v_fmac_f32_e32 v29, v187, v200
	v_fmac_f32_e32 v30, v188, v200
	v_fmac_f32_e32 v31, v189, v200
	v_fmac_f32_e32 v32, v190, v200
	v_fmac_f32_e32 v34, v191, v200
	v_mul_f32_e32 v40, v192, v26
	v_mul_f32_e32 v41, v193, v27
	v_fmac_f32_e32 v40, v194, v28
	v_fmac_f32_e32 v41, v195, v29
	v_fmac_f32_e32 v40, v196, v30
	v_fmac_f32_e32 v41, v197, v31
	v_fmac_f32_e32 v40, v198, v32
	v_fmac_f32_e32 v41, v199, v34
	v_add_f32_e32 v35, v40, v41
	s_nop 1
	v_add_f32_dpp v35, v35, v35 quad_perm:[1,0,3,2] row_mask:0xf bank_mask:0xf bound_ctrl:1
	ds_read_b128 v[176:179], v173 offset:18816
	ds_read_b128 v[180:183], v173 offset:18832
	ds_read_b128 v[184:187], v173 offset:10624
	ds_read_b128 v[188:191], v173 offset:10640
	ds_read_b32 v200, v172 offset:29440
	ds_read_b128 v[192:195], v173 offset:2432
	ds_read_b128 v[196:199], v173 offset:2448
	s_waitcnt lgkmcnt(8)
	v_mul_f32_e32 v26, v0, v26
	v_mul_f32_e32 v27, v1, v27
	v_mul_f32_e32 v28, v2, v28
	v_mul_f32_e32 v29, v3, v29
	v_mul_f32_e32 v30, v4, v30
	v_mul_f32_e32 v31, v5, v31
	v_mul_f32_e32 v32, v6, v32
	v_mul_f32_e32 v34, v7, v34
	v_add_f32_dpp v35, v35, v35 quad_perm:[2,3,0,1] row_mask:0xf bank_mask:0xf bound_ctrl:1
	ds_write_b32 v174, v35
	v_add_u32_e32 v174, v174, v161
	v_fmac_f32_e32 v26, v8, v33
	v_fmac_f32_e32 v27, v9, v33
	v_fmac_f32_e32 v28, v10, v33
	v_fmac_f32_e32 v29, v11, v33
	v_fmac_f32_e32 v30, v12, v33
	v_fmac_f32_e32 v31, v13, v33
	v_fmac_f32_e32 v32, v14, v33
	v_fmac_f32_e32 v34, v15, v33
	v_mul_f32_e32 v40, v16, v26
	v_mul_f32_e32 v41, v17, v27
	v_fmac_f32_e32 v40, v18, v28
	v_fmac_f32_e32 v41, v19, v29
	v_fmac_f32_e32 v40, v20, v30
	v_fmac_f32_e32 v41, v21, v31
	v_fmac_f32_e32 v40, v22, v32
	v_fmac_f32_e32 v41, v23, v34
	v_add_f32_e32 v35, v40, v41
	s_nop 1
	v_add_f32_dpp v35, v35, v35 quad_perm:[1,0,3,2] row_mask:0xf bank_mask:0xf bound_ctrl:1
	ds_read_b128 v[0:3], v173 offset:18944
	ds_read_b128 v[4:7], v173 offset:18960
	ds_read_b128 v[8:11], v173 offset:10752
	ds_read_b128 v[12:15], v173 offset:10768
	ds_read_b32 v33, v172 offset:29696
	ds_read_b128 v[16:19], v173 offset:2560
	ds_read_b128 v[20:23], v173 offset:2576
	s_waitcnt lgkmcnt(8)
	v_mul_f32_e32 v26, v176, v26
	v_mul_f32_e32 v27, v177, v27
	v_mul_f32_e32 v28, v178, v28
	v_mul_f32_e32 v29, v179, v29
	v_mul_f32_e32 v30, v180, v30
	v_mul_f32_e32 v31, v181, v31
	v_mul_f32_e32 v32, v182, v32
	v_mul_f32_e32 v34, v183, v34
	v_add_f32_dpp v35, v35, v35 quad_perm:[2,3,0,1] row_mask:0xf bank_mask:0xf bound_ctrl:1
	ds_write_b32 v174, v35
	v_add_u32_e32 v174, v174, v161
	v_fmac_f32_e32 v26, v184, v200
	v_fmac_f32_e32 v27, v185, v200
	v_fmac_f32_e32 v28, v186, v200
	v_fmac_f32_e32 v29, v187, v200
	v_fmac_f32_e32 v30, v188, v200
	v_fmac_f32_e32 v31, v189, v200
	v_fmac_f32_e32 v32, v190, v200
	v_fmac_f32_e32 v34, v191, v200
	v_mul_f32_e32 v40, v192, v26
	v_mul_f32_e32 v41, v193, v27
	v_fmac_f32_e32 v40, v194, v28
	v_fmac_f32_e32 v41, v195, v29
	v_fmac_f32_e32 v40, v196, v30
	v_fmac_f32_e32 v41, v197, v31
	v_fmac_f32_e32 v40, v198, v32
	v_fmac_f32_e32 v41, v199, v34
	v_add_f32_e32 v35, v40, v41
	s_nop 1
	v_add_f32_dpp v35, v35, v35 quad_perm:[1,0,3,2] row_mask:0xf bank_mask:0xf bound_ctrl:1
	ds_read_b128 v[176:179], v173 offset:19072
	ds_read_b128 v[180:183], v173 offset:19088
	ds_read_b128 v[184:187], v173 offset:10880
	ds_read_b128 v[188:191], v173 offset:10896
	ds_read_b32 v200, v172 offset:29952
	ds_read_b128 v[192:195], v173 offset:2688
	ds_read_b128 v[196:199], v173 offset:2704
	s_waitcnt lgkmcnt(8)
; #define GLA_LD(t_, aq, kq, qq, vq) do { const int tt_ = (t_); vq = Bs[6144 + tt_ * 64 + pp]; \
;             _Pragma("unroll") for (int u = 0; u < 2; ++u) { aq[u] = *(const LAS f32x4*)(Bs + 4096 + tt_ * 32 + k0 + 4 * u); kq[u] = *(const LAS f32x4*)(Bs + 2048 + tt_ * 32 + k0 + 4 * u); qq[u] = *(const LAS f32x4*)(Bs + tt_ * 32 + k0 + 4 * u); } } while (0)
; #define GLA_STEP(t_, aq, kq, qq, vq) do { float y = 0.f; \
;             _Pragma("unroll") for (int u = 0; u < 2; ++u) _Pragma("unroll") for (int j = 0; j < 4; ++j) { S[4 * u + j] = aq[u][j] * S[4 * u + j] + kq[u][j] * vq; y += qq[u][j] * S[4 * u + j]; } \
;             y += dpp_f(y, 0xB1); y += dpp_f(y, 0x4E); ydst[(t_) * ystride] = y; } while (0)
; __device__ __forceinline__ void gla_job(const bf16_t* P, bf16_t* Y, int l, int b, int h, LAS float* lds, int wave_s) {
;     ...
;             GLA_LD(0, a0_, k0_, q0_, v0_);
;             for (int t = 0; t < TC; t += 2) {
;                 GLA_LD(t + 1, a1_, k1_, q1_, v1_);
;                 GLA_STEP(t, a0_, k0_, q0_, v0_);
;                 GLA_LD(t + 2 < TC ? t + 2 : t + 1, a0_, k0_, q0_, v0_);
;                 GLA_STEP(t + 1, a1_, k1_, q1_, v1_);
	v_mul_f32_e32 v26, v0, v26
	v_mul_f32_e32 v27, v1, v27
	v_mul_f32_e32 v28, v2, v28
	v_mul_f32_e32 v29, v3, v29
	v_mul_f32_e32 v30, v4, v30
	v_mul_f32_e32 v31, v5, v31
	v_mul_f32_e32 v32, v6, v32
	v_mul_f32_e32 v34, v7, v34
	v_add_f32_dpp v35, v35, v35 quad_perm:[2,3,0,1] row_mask:0xf bank_mask:0xf bound_ctrl:1
	ds_write_b32 v174, v35
	v_add_u32_e32 v174, v174, v161
	v_fmac_f32_e32 v26, v8, v33
	v_fmac_f32_e32 v27, v9, v33
	v_fmac_f32_e32 v28, v10, v33
	v_fmac_f32_e32 v29, v11, v33
	v_fmac_f32_e32 v30, v12, v33
	v_fmac_f32_e32 v31, v13, v33
	v_fmac_f32_e32 v32, v14, v33
	v_fmac_f32_e32 v34, v15, v33
	v_mul_f32_e32 v40, v16, v26
	v_mul_f32_e32 v41, v17, v27
	v_fmac_f32_e32 v40, v18, v28
	v_fmac_f32_e32 v41, v19, v29
	v_fmac_f32_e32 v40, v20, v30
	v_fmac_f32_e32 v41, v21, v31
	v_fmac_f32_e32 v40, v22, v32
	v_fmac_f32_e32 v41, v23, v34
	v_add_f32_e32 v35, v40, v41
	s_nop 1
	v_add_f32_dpp v35, v35, v35 quad_perm:[1,0,3,2] row_mask:0xf bank_mask:0xf bound_ctrl:1
	ds_read_b128 v[0:3], v173 offset:19200
	ds_read_b128 v[4:7], v173 offset:19216
	ds_read_b128 v[8:11], v173 offset:11008
	ds_read_b128 v[12:15], v173 offset:11024
	ds_read_b32 v33, v172 offset:30208
	ds_read_b128 v[16:19], v173 offset:2816
	ds_read_b128 v[20:23], v173 offset:2832
	s_waitcnt lgkmcnt(8)
	v_mul_f32_e32 v26, v176, v26
	v_mul_f32_e32 v27, v177, v27
	v_mul_f32_e32 v28, v178, v28
	v_mul_f32_e32 v29, v179, v29
	v_mul_f32_e32 v30, v180, v30
	v_mul_f32_e32 v31, v181, v31
	v_mul_f32_e32 v32, v182, v32
	v_mul_f32_e32 v34, v183, v34
	v_add_f32_dpp v35, v35, v35 quad_perm:[2,3,0,1] row_mask:0xf bank_mask:0xf bound_ctrl:1
	ds_write_b32 v174, v35
	v_add_u32_e32 v174, v174, v161
	v_fmac_f32_e32 v26, v184, v200
	v_fmac_f32_e32 v27, v185, v200
	v_fmac_f32_e32 v28, v186, v200
	v_fmac_f32_e32 v29, v187, v200
	v_fmac_f32_e32 v30, v188, v200
	v_fmac_f32_e32 v31, v189, v200
	v_fmac_f32_e32 v32, v190, v200
	v_fmac_f32_e32 v34, v191, v200
	v_mul_f32_e32 v40, v192, v26
	v_mul_f32_e32 v41, v193, v27
	v_fmac_f32_e32 v40, v194, v28
	v_fmac_f32_e32 v41, v195, v29
	v_fmac_f32_e32 v40, v196, v30
	v_fmac_f32_e32 v41, v197, v31
	v_fmac_f32_e32 v40, v198, v32
	v_fmac_f32_e32 v41, v199, v34
	v_add_f32_e32 v35, v40, v41
	s_nop 1
	v_add_f32_dpp v35, v35, v35 quad_perm:[1,0,3,2] row_mask:0xf bank_mask:0xf bound_ctrl:1
	ds_read_b128 v[176:179], v173 offset:19328
	ds_read_b128 v[180:183], v173 offset:19344
	ds_read_b128 v[184:187], v173 offset:11136
	ds_read_b128 v[188:191], v173 offset:11152
	ds_read_b32 v200, v172 offset:30464
	ds_read_b128 v[192:195], v173 offset:2944
	ds_read_b128 v[196:199], v173 offset:2960
	s_waitcnt lgkmcnt(8)
	v_mul_f32_e32 v26, v0, v26
	v_mul_f32_e32 v27, v1, v27
	v_mul_f32_e32 v28, v2, v28
	v_mul_f32_e32 v29, v3, v29
	v_mul_f32_e32 v30, v4, v30
	v_mul_f32_e32 v31, v5, v31
	v_mul_f32_e32 v32, v6, v32
	v_mul_f32_e32 v34, v7, v34
	v_add_f32_dpp v35, v35, v35 quad_perm:[2,3,0,1] row_mask:0xf bank_mask:0xf bound_ctrl:1
	ds_write_b32 v174, v35
	v_add_u32_e32 v174, v174, v161
	v_fmac_f32_e32 v26, v8, v33
	v_fmac_f32_e32 v27, v9, v33
	v_fmac_f32_e32 v28, v10, v33
	v_fmac_f32_e32 v29, v11, v33
	v_fmac_f32_e32 v30, v12, v33
	v_fmac_f32_e32 v31, v13, v33
	v_fmac_f32_e32 v32, v14, v33
	v_fmac_f32_e32 v34, v15, v33
	v_mul_f32_e32 v40, v16, v26
	v_mul_f32_e32 v41, v17, v27
	v_fmac_f32_e32 v40, v18, v28
	v_fmac_f32_e32 v41, v19, v29
	v_fmac_f32_e32 v40, v20, v30
	v_fmac_f32_e32 v41, v21, v31
	v_fmac_f32_e32 v40, v22, v32
	v_fmac_f32_e32 v41, v23, v34
	v_add_f32_e32 v35, v40, v41
	s_nop 1
	v_add_f32_dpp v35, v35, v35 quad_perm:[1,0,3,2] row_mask:0xf bank_mask:0xf bound_ctrl:1
	ds_read_b128 v[0:3], v173 offset:19456
	ds_read_b128 v[4:7], v173 offset:19472
	ds_read_b128 v[8:11], v173 offset:11264
	ds_read_b128 v[12:15], v173 offset:11280
	ds_read_b32 v33, v172 offset:30720
	ds_read_b128 v[16:19], v173 offset:3072
	ds_read_b128 v[20:23], v173 offset:3088
	s_waitcnt lgkmcnt(8)
	v_mul_f32_e32 v26, v176, v26
	v_mul_f32_e32 v27, v177, v27
	v_mul_f32_e32 v28, v178, v28
	v_mul_f32_e32 v29, v179, v29
	v_mul_f32_e32 v30, v180, v30
	v_mul_f32_e32 v31, v181, v31
	v_mul_f32_e32 v32, v182, v32
	v_mul_f32_e32 v34, v183, v34
	v_add_f32_dpp v35, v35, v35 quad_perm:[2,3,0,1] row_mask:0xf bank_mask:0xf bound_ctrl:1
	ds_write_b32 v174, v35
	v_add_u32_e32 v174, v174, v161
	v_fmac_f32_e32 v26, v184, v200
	v_fmac_f32_e32 v27, v185, v200
	v_fmac_f32_e32 v28, v186, v200
	v_fmac_f32_e32 v29, v187, v200
	v_fmac_f32_e32 v30, v188, v200
	v_fmac_f32_e32 v31, v189, v200
	v_fmac_f32_e32 v32, v190, v200
	v_fmac_f32_e32 v34, v191, v200
	v_mul_f32_e32 v40, v192, v26
	v_mul_f32_e32 v41, v193, v27
	v_fmac_f32_e32 v40, v194, v28
	v_fmac_f32_e32 v41, v195, v29
	v_fmac_f32_e32 v40, v196, v30
	v_fmac_f32_e32 v41, v197, v31
	v_fmac_f32_e32 v40, v198, v32
	v_fmac_f32_e32 v41, v199, v34
	v_add_f32_e32 v35, v40, v41
	s_nop 1
	v_add_f32_dpp v35, v35, v35 quad_perm:[1,0,3,2] row_mask:0xf bank_mask:0xf bound_ctrl:1
	ds_read_b128 v[176:179], v173 offset:19584
	ds_read_b128 v[180:183], v173 offset:19600
	ds_read_b128 v[184:187], v173 offset:11392
	ds_read_b128 v[188:191], v173 offset:11408
	ds_read_b32 v200, v172 offset:30976
	ds_read_b128 v[192:195], v173 offset:3200
	ds_read_b128 v[196:199], v173 offset:3216
	s_waitcnt lgkmcnt(8)
; #define GLA_LD(t_, aq, kq, qq, vq) do { const int tt_ = (t_); vq = Bs[6144 + tt_ * 64 + pp]; \
;             _Pragma("unroll") for (int u = 0; u < 2; ++u) { aq[u] = *(const LAS f32x4*)(Bs + 4096 + tt_ * 32 + k0 + 4 * u); kq[u] = *(const LAS f32x4*)(Bs + 2048 + tt_ * 32 + k0 + 4 * u); qq[u] = *(const LAS f32x4*)(Bs + tt_ * 32 + k0 + 4 * u); } } while (0)
; #define GLA_STEP(t_, aq, kq, qq, vq) do { float y = 0.f; \
;             _Pragma("unroll") for (int u = 0; u < 2; ++u) _Pragma("unroll") for (int j = 0; j < 4; ++j) { S[4 * u + j] = aq[u][j] * S[4 * u + j] + kq[u][j] * vq; y += qq[u][j] * S[4 * u + j]; } \
;             y += dpp_f(y, 0xB1); y += dpp_f(y, 0x4E); ydst[(t_) * ystride] = y; } while (0)
; __device__ __forceinline__ void gla_job(const bf16_t* P, bf16_t* Y, int l, int b, int h, LAS float* lds, int wave_s) {
;     ...
;             GLA_LD(0, a0_, k0_, q0_, v0_);
;             for (int t = 0; t < TC; t += 2) {
;                 GLA_LD(t + 1, a1_, k1_, q1_, v1_);
;                 GLA_STEP(t, a0_, k0_, q0_, v0_);
;                 GLA_LD(t + 2 < TC ? t + 2 : t + 1, a0_, k0_, q0_, v0_);
;                 GLA_STEP(t + 1, a1_, k1_, q1_, v1_);
	v_mul_f32_e32 v26, v0, v26
	v_mul_f32_e32 v27, v1, v27
	v_mul_f32_e32 v28, v2, v28
	v_mul_f32_e32 v29, v3, v29
	v_mul_f32_e32 v30, v4, v30
	v_mul_f32_e32 v31, v5, v31
	v_mul_f32_e32 v32, v6, v32
	v_mul_f32_e32 v34, v7, v34
	v_add_f32_dpp v35, v35, v35 quad_perm:[2,3,0,1] row_mask:0xf bank_mask:0xf bound_ctrl:1
	ds_write_b32 v174, v35
	v_add_u32_e32 v174, v174, v161
	v_fmac_f32_e32 v26, v8, v33
	v_fmac_f32_e32 v27, v9, v33
	v_fmac_f32_e32 v28, v10, v33
	v_fmac_f32_e32 v29, v11, v33
	v_fmac_f32_e32 v30, v12, v33
	v_fmac_f32_e32 v31, v13, v33
	v_fmac_f32_e32 v32, v14, v33
	v_fmac_f32_e32 v34, v15, v33
	v_mul_f32_e32 v40, v16, v26
	v_mul_f32_e32 v41, v17, v27
	v_fmac_f32_e32 v40, v18, v28
	v_fmac_f32_e32 v41, v19, v29
	v_fmac_f32_e32 v40, v20, v30
	v_fmac_f32_e32 v41, v21, v31
	v_fmac_f32_e32 v40, v22, v32
	v_fmac_f32_e32 v41, v23, v34
	v_add_f32_e32 v35, v40, v41
	s_nop 1
	v_add_f32_dpp v35, v35, v35 quad_perm:[1,0,3,2] row_mask:0xf bank_mask:0xf bound_ctrl:1
	ds_read_b128 v[0:3], v173 offset:19712
	ds_read_b128 v[4:7], v173 offset:19728
	ds_read_b128 v[8:11], v173 offset:11520
	ds_read_b128 v[12:15], v173 offset:11536
	ds_read_b32 v33, v172 offset:31232
	ds_read_b128 v[16:19], v173 offset:3328
	ds_read_b128 v[20:23], v173 offset:3344
	s_waitcnt lgkmcnt(8)
	v_mul_f32_e32 v26, v176, v26
	v_mul_f32_e32 v27, v177, v27
	v_mul_f32_e32 v28, v178, v28
	v_mul_f32_e32 v29, v179, v29
	v_mul_f32_e32 v30, v180, v30
	v_mul_f32_e32 v31, v181, v31
	v_mul_f32_e32 v32, v182, v32
	v_mul_f32_e32 v34, v183, v34
	v_add_f32_dpp v35, v35, v35 quad_perm:[2,3,0,1] row_mask:0xf bank_mask:0xf bound_ctrl:1
	ds_write_b32 v174, v35
	v_add_u32_e32 v174, v174, v161
	v_fmac_f32_e32 v26, v184, v200
	v_fmac_f32_e32 v27, v185, v200
	v_fmac_f32_e32 v28, v186, v200
	v_fmac_f32_e32 v29, v187, v200
	v_fmac_f32_e32 v30, v188, v200
	v_fmac_f32_e32 v31, v189, v200
	v_fmac_f32_e32 v32, v190, v200
	v_fmac_f32_e32 v34, v191, v200
	v_mul_f32_e32 v40, v192, v26
	v_mul_f32_e32 v41, v193, v27
	v_fmac_f32_e32 v40, v194, v28
	v_fmac_f32_e32 v41, v195, v29
	v_fmac_f32_e32 v40, v196, v30
	v_fmac_f32_e32 v41, v197, v31
	v_fmac_f32_e32 v40, v198, v32
	v_fmac_f32_e32 v41, v199, v34
	v_add_f32_e32 v35, v40, v41
	s_nop 1
	v_add_f32_dpp v35, v35, v35 quad_perm:[1,0,3,2] row_mask:0xf bank_mask:0xf bound_ctrl:1
	ds_read_b128 v[176:179], v173 offset:19840
	ds_read_b128 v[180:183], v173 offset:19856
	ds_read_b128 v[184:187], v173 offset:11648
	ds_read_b128 v[188:191], v173 offset:11664
	ds_read_b32 v200, v172 offset:31488
	ds_read_b128 v[192:195], v173 offset:3456
	ds_read_b128 v[196:199], v173 offset:3472
	s_waitcnt lgkmcnt(8)
	v_mul_f32_e32 v26, v0, v26
	v_mul_f32_e32 v27, v1, v27
	v_mul_f32_e32 v28, v2, v28
	v_mul_f32_e32 v29, v3, v29
	v_mul_f32_e32 v30, v4, v30
	v_mul_f32_e32 v31, v5, v31
	v_mul_f32_e32 v32, v6, v32
	v_mul_f32_e32 v34, v7, v34
	v_add_f32_dpp v35, v35, v35 quad_perm:[2,3,0,1] row_mask:0xf bank_mask:0xf bound_ctrl:1
	ds_write_b32 v174, v35
	v_add_u32_e32 v174, v174, v161
	v_fmac_f32_e32 v26, v8, v33
	v_fmac_f32_e32 v27, v9, v33
	v_fmac_f32_e32 v28, v10, v33
	v_fmac_f32_e32 v29, v11, v33
	v_fmac_f32_e32 v30, v12, v33
	v_fmac_f32_e32 v31, v13, v33
	v_fmac_f32_e32 v32, v14, v33
	v_fmac_f32_e32 v34, v15, v33
	v_mul_f32_e32 v40, v16, v26
	v_mul_f32_e32 v41, v17, v27
	v_fmac_f32_e32 v40, v18, v28
	v_fmac_f32_e32 v41, v19, v29
	v_fmac_f32_e32 v40, v20, v30
	v_fmac_f32_e32 v41, v21, v31
	v_fmac_f32_e32 v40, v22, v32
	v_fmac_f32_e32 v41, v23, v34
	v_add_f32_e32 v35, v40, v41
	s_nop 1
	v_add_f32_dpp v35, v35, v35 quad_perm:[1,0,3,2] row_mask:0xf bank_mask:0xf bound_ctrl:1
	ds_read_b128 v[0:3], v173 offset:19968
	ds_read_b128 v[4:7], v173 offset:19984
	ds_read_b128 v[8:11], v173 offset:11776
	ds_read_b128 v[12:15], v173 offset:11792
	ds_read_b32 v33, v172 offset:31744
	ds_read_b128 v[16:19], v173 offset:3584
	ds_read_b128 v[20:23], v173 offset:3600
	s_waitcnt lgkmcnt(8)
	v_mul_f32_e32 v26, v176, v26
	v_mul_f32_e32 v27, v177, v27
	v_mul_f32_e32 v28, v178, v28
	v_mul_f32_e32 v29, v179, v29
	v_mul_f32_e32 v30, v180, v30
	v_mul_f32_e32 v31, v181, v31
	v_mul_f32_e32 v32, v182, v32
	v_mul_f32_e32 v34, v183, v34
	v_add_f32_dpp v35, v35, v35 quad_perm:[2,3,0,1] row_mask:0xf bank_mask:0xf bound_ctrl:1
	ds_write_b32 v174, v35
	v_add_u32_e32 v174, v174, v161
	v_fmac_f32_e32 v26, v184, v200
	v_fmac_f32_e32 v27, v185, v200
	v_fmac_f32_e32 v28, v186, v200
	v_fmac_f32_e32 v29, v187, v200
	v_fmac_f32_e32 v30, v188, v200
	v_fmac_f32_e32 v31, v189, v200
	v_fmac_f32_e32 v32, v190, v200
	v_fmac_f32_e32 v34, v191, v200
	v_mul_f32_e32 v40, v192, v26
	v_mul_f32_e32 v41, v193, v27
	v_fmac_f32_e32 v40, v194, v28
	v_fmac_f32_e32 v41, v195, v29
	v_fmac_f32_e32 v40, v196, v30
	v_fmac_f32_e32 v41, v197, v31
	v_fmac_f32_e32 v40, v198, v32
	v_fmac_f32_e32 v41, v199, v34
	v_add_f32_e32 v35, v40, v41
	s_nop 1
	v_add_f32_dpp v35, v35, v35 quad_perm:[1,0,3,2] row_mask:0xf bank_mask:0xf bound_ctrl:1
	ds_read_b128 v[176:179], v173 offset:20096
	ds_read_b128 v[180:183], v173 offset:20112
	ds_read_b128 v[184:187], v173 offset:11904
	ds_read_b128 v[188:191], v173 offset:11920
	ds_read_b32 v200, v172 offset:32000
	ds_read_b128 v[192:195], v173 offset:3712
	ds_read_b128 v[196:199], v173 offset:3728
	s_waitcnt lgkmcnt(8)
; #define GLA_LD(t_, aq, kq, qq, vq) do { const int tt_ = (t_); vq = Bs[6144 + tt_ * 64 + pp]; \
;             _Pragma("unroll") for (int u = 0; u < 2; ++u) { aq[u] = *(const LAS f32x4*)(Bs + 4096 + tt_ * 32 + k0 + 4 * u); kq[u] = *(const LAS f32x4*)(Bs + 2048 + tt_ * 32 + k0 + 4 * u); qq[u] = *(const LAS f32x4*)(Bs + tt_ * 32 + k0 + 4 * u); } } while (0)
; #define GLA_STEP(t_, aq, kq, qq, vq) do { float y = 0.f; \
;             _Pragma("unroll") for (int u = 0; u < 2; ++u) _Pragma("unroll") for (int j = 0; j < 4; ++j) { S[4 * u + j] = aq[u][j] * S[4 * u + j] + kq[u][j] * vq; y += qq[u][j] * S[4 * u + j]; } \
;             y += dpp_f(y, 0xB1); y += dpp_f(y, 0x4E); ydst[(t_) * ystride] = y; } while (0)
; __device__ __forceinline__ void gla_job(const bf16_t* P, bf16_t* Y, int l, int b, int h, LAS float* lds, int wave_s) {
;     ...
;             GLA_LD(0, a0_, k0_, q0_, v0_);
;             for (int t = 0; t < TC; t += 2) {
;                 GLA_LD(t + 1, a1_, k1_, q1_, v1_);
;                 GLA_STEP(t, a0_, k0_, q0_, v0_);
;                 GLA_LD(t + 2 < TC ? t + 2 : t + 1, a0_, k0_, q0_, v0_);
;                 GLA_STEP(t + 1, a1_, k1_, q1_, v1_);
	v_mul_f32_e32 v26, v0, v26
	v_mul_f32_e32 v27, v1, v27
	v_mul_f32_e32 v28, v2, v28
	v_mul_f32_e32 v29, v3, v29
	v_mul_f32_e32 v30, v4, v30
	v_mul_f32_e32 v31, v5, v31
	v_mul_f32_e32 v32, v6, v32
	v_mul_f32_e32 v34, v7, v34
	v_add_f32_dpp v35, v35, v35 quad_perm:[2,3,0,1] row_mask:0xf bank_mask:0xf bound_ctrl:1
	ds_write_b32 v174, v35
	v_add_u32_e32 v174, v174, v161
	v_fmac_f32_e32 v26, v8, v33
	v_fmac_f32_e32 v27, v9, v33
	v_fmac_f32_e32 v28, v10, v33
	v_fmac_f32_e32 v29, v11, v33
	v_fmac_f32_e32 v30, v12, v33
	v_fmac_f32_e32 v31, v13, v33
	v_fmac_f32_e32 v32, v14, v33
	v_fmac_f32_e32 v34, v15, v33
	v_mul_f32_e32 v40, v16, v26
	v_mul_f32_e32 v41, v17, v27
	v_fmac_f32_e32 v40, v18, v28
	v_fmac_f32_e32 v41, v19, v29
	v_fmac_f32_e32 v40, v20, v30
	v_fmac_f32_e32 v41, v21, v31
	v_fmac_f32_e32 v40, v22, v32
	v_fmac_f32_e32 v41, v23, v34
	v_add_f32_e32 v35, v40, v41
	s_nop 1
	v_add_f32_dpp v35, v35, v35 quad_perm:[1,0,3,2] row_mask:0xf bank_mask:0xf bound_ctrl:1
	ds_read_b128 v[0:3], v173 offset:20224
	ds_read_b128 v[4:7], v173 offset:20240
	ds_read_b128 v[8:11], v173 offset:12032
	ds_read_b128 v[12:15], v173 offset:12048
	ds_read_b32 v33, v172 offset:32256
	ds_read_b128 v[16:19], v173 offset:3840
	ds_read_b128 v[20:23], v173 offset:3856
	s_waitcnt lgkmcnt(8)
	v_mul_f32_e32 v26, v176, v26
	v_mul_f32_e32 v27, v177, v27
	v_mul_f32_e32 v28, v178, v28
	v_mul_f32_e32 v29, v179, v29
	v_mul_f32_e32 v30, v180, v30
	v_mul_f32_e32 v31, v181, v31
	v_mul_f32_e32 v32, v182, v32
	v_mul_f32_e32 v34, v183, v34
	v_add_f32_dpp v35, v35, v35 quad_perm:[2,3,0,1] row_mask:0xf bank_mask:0xf bound_ctrl:1
	ds_write_b32 v174, v35
	v_add_u32_e32 v174, v174, v161
	v_fmac_f32_e32 v26, v184, v200
	v_fmac_f32_e32 v27, v185, v200
	v_fmac_f32_e32 v28, v186, v200
	v_fmac_f32_e32 v29, v187, v200
	v_fmac_f32_e32 v30, v188, v200
	v_fmac_f32_e32 v31, v189, v200
	v_fmac_f32_e32 v32, v190, v200
	v_fmac_f32_e32 v34, v191, v200
	v_mul_f32_e32 v40, v192, v26
	v_mul_f32_e32 v41, v193, v27
	v_fmac_f32_e32 v40, v194, v28
	v_fmac_f32_e32 v41, v195, v29
	v_fmac_f32_e32 v40, v196, v30
	v_fmac_f32_e32 v41, v197, v31
	v_fmac_f32_e32 v40, v198, v32
	v_fmac_f32_e32 v41, v199, v34
	v_add_f32_e32 v35, v40, v41
	s_nop 1
	v_add_f32_dpp v35, v35, v35 quad_perm:[1,0,3,2] row_mask:0xf bank_mask:0xf bound_ctrl:1
	ds_read_b128 v[176:179], v173 offset:20352
	ds_read_b128 v[180:183], v173 offset:20368
	ds_read_b128 v[184:187], v173 offset:12160
	ds_read_b128 v[188:191], v173 offset:12176
	ds_read_b32 v200, v172 offset:32512
	ds_read_b128 v[192:195], v173 offset:3968
	ds_read_b128 v[196:199], v173 offset:3984
	s_waitcnt lgkmcnt(8)
	v_mul_f32_e32 v26, v0, v26
	v_mul_f32_e32 v27, v1, v27
	v_mul_f32_e32 v28, v2, v28
	v_mul_f32_e32 v29, v3, v29
	v_mul_f32_e32 v30, v4, v30
	v_mul_f32_e32 v31, v5, v31
	v_mul_f32_e32 v32, v6, v32
	v_mul_f32_e32 v34, v7, v34
	v_add_f32_dpp v35, v35, v35 quad_perm:[2,3,0,1] row_mask:0xf bank_mask:0xf bound_ctrl:1
	ds_write_b32 v174, v35
	v_add_u32_e32 v174, v174, v161
	v_fmac_f32_e32 v26, v8, v33
	v_fmac_f32_e32 v27, v9, v33
	v_fmac_f32_e32 v28, v10, v33
	v_fmac_f32_e32 v29, v11, v33
	v_fmac_f32_e32 v30, v12, v33
	v_fmac_f32_e32 v31, v13, v33
	v_fmac_f32_e32 v32, v14, v33
	v_fmac_f32_e32 v34, v15, v33
	v_mul_f32_e32 v40, v16, v26
	v_mul_f32_e32 v41, v17, v27
	v_fmac_f32_e32 v40, v18, v28
	v_fmac_f32_e32 v41, v19, v29
	v_fmac_f32_e32 v40, v20, v30
	v_fmac_f32_e32 v41, v21, v31
	v_fmac_f32_e32 v40, v22, v32
	v_fmac_f32_e32 v41, v23, v34
	v_add_f32_e32 v35, v40, v41
	s_nop 1
	v_add_f32_dpp v35, v35, v35 quad_perm:[1,0,3,2] row_mask:0xf bank_mask:0xf bound_ctrl:1
	ds_read_b128 v[0:3], v173 offset:20480
	ds_read_b128 v[4:7], v173 offset:20496
	ds_read_b128 v[8:11], v173 offset:12288
	ds_read_b128 v[12:15], v173 offset:12304
	ds_read_b32 v33, v172 offset:32768
	ds_read_b128 v[16:19], v173 offset:4096
	ds_read_b128 v[20:23], v173 offset:4112
	s_waitcnt lgkmcnt(8)
	v_mul_f32_e32 v26, v176, v26
	v_mul_f32_e32 v27, v177, v27
	v_mul_f32_e32 v28, v178, v28
	v_mul_f32_e32 v29, v179, v29
	v_mul_f32_e32 v30, v180, v30
	v_mul_f32_e32 v31, v181, v31
	v_mul_f32_e32 v32, v182, v32
	v_mul_f32_e32 v34, v183, v34
	v_add_f32_dpp v35, v35, v35 quad_perm:[2,3,0,1] row_mask:0xf bank_mask:0xf bound_ctrl:1
	ds_write_b32 v174, v35
	v_add_u32_e32 v174, v174, v161
	v_fmac_f32_e32 v26, v184, v200
	v_fmac_f32_e32 v27, v185, v200
	v_fmac_f32_e32 v28, v186, v200
	v_fmac_f32_e32 v29, v187, v200
	v_fmac_f32_e32 v30, v188, v200
	v_fmac_f32_e32 v31, v189, v200
	v_fmac_f32_e32 v32, v190, v200
	v_fmac_f32_e32 v34, v191, v200
	v_mul_f32_e32 v40, v192, v26
	v_mul_f32_e32 v41, v193, v27
	v_fmac_f32_e32 v40, v194, v28
	v_fmac_f32_e32 v41, v195, v29
	v_fmac_f32_e32 v40, v196, v30
	v_fmac_f32_e32 v41, v197, v31
	v_fmac_f32_e32 v40, v198, v32
	v_fmac_f32_e32 v41, v199, v34
	v_add_f32_e32 v35, v40, v41
	s_nop 1
	v_add_f32_dpp v35, v35, v35 quad_perm:[1,0,3,2] row_mask:0xf bank_mask:0xf bound_ctrl:1
	ds_read_b128 v[176:179], v173 offset:20608
	ds_read_b128 v[180:183], v173 offset:20624
	ds_read_b128 v[184:187], v173 offset:12416
	ds_read_b128 v[188:191], v173 offset:12432
	ds_read_b32 v200, v172 offset:33024
	ds_read_b128 v[192:195], v173 offset:4224
	ds_read_b128 v[196:199], v173 offset:4240
	s_waitcnt lgkmcnt(8)
; #define GLA_LD(t_, aq, kq, qq, vq) do { const int tt_ = (t_); vq = Bs[6144 + tt_ * 64 + pp]; \
;             _Pragma("unroll") for (int u = 0; u < 2; ++u) { aq[u] = *(const LAS f32x4*)(Bs + 4096 + tt_ * 32 + k0 + 4 * u); kq[u] = *(const LAS f32x4*)(Bs + 2048 + tt_ * 32 + k0 + 4 * u); qq[u] = *(const LAS f32x4*)(Bs + tt_ * 32 + k0 + 4 * u); } } while (0)
; #define GLA_STEP(t_, aq, kq, qq, vq) do { float y = 0.f; \
;             _Pragma("unroll") for (int u = 0; u < 2; ++u) _Pragma("unroll") for (int j = 0; j < 4; ++j) { S[4 * u + j] = aq[u][j] * S[4 * u + j] + kq[u][j] * vq; y += qq[u][j] * S[4 * u + j]; } \
;             y += dpp_f(y, 0xB1); y += dpp_f(y, 0x4E); ydst[(t_) * ystride] = y; } while (0)
; __device__ __forceinline__ void gla_job(const bf16_t* P, bf16_t* Y, int l, int b, int h, LAS float* lds, int wave_s) {
;     ...
;             GLA_LD(0, a0_, k0_, q0_, v0_);
;             for (int t = 0; t < TC; t += 2) {
;                 GLA_LD(t + 1, a1_, k1_, q1_, v1_);
;                 GLA_STEP(t, a0_, k0_, q0_, v0_);
;                 GLA_LD(t + 2 < TC ? t + 2 : t + 1, a0_, k0_, q0_, v0_);
;                 GLA_STEP(t + 1, a1_, k1_, q1_, v1_);
	v_mul_f32_e32 v26, v0, v26
	v_mul_f32_e32 v27, v1, v27
	v_mul_f32_e32 v28, v2, v28
	v_mul_f32_e32 v29, v3, v29
	v_mul_f32_e32 v30, v4, v30
	v_mul_f32_e32 v31, v5, v31
	v_mul_f32_e32 v32, v6, v32
	v_mul_f32_e32 v34, v7, v34
	v_add_f32_dpp v35, v35, v35 quad_perm:[2,3,0,1] row_mask:0xf bank_mask:0xf bound_ctrl:1
	ds_write_b32 v174, v35
	v_add_u32_e32 v174, v174, v161
	v_fmac_f32_e32 v26, v8, v33
	v_fmac_f32_e32 v27, v9, v33
	v_fmac_f32_e32 v28, v10, v33
	v_fmac_f32_e32 v29, v11, v33
	v_fmac_f32_e32 v30, v12, v33
	v_fmac_f32_e32 v31, v13, v33
	v_fmac_f32_e32 v32, v14, v33
	v_fmac_f32_e32 v34, v15, v33
	v_mul_f32_e32 v40, v16, v26
	v_mul_f32_e32 v41, v17, v27
	v_fmac_f32_e32 v40, v18, v28
	v_fmac_f32_e32 v41, v19, v29
	v_fmac_f32_e32 v40, v20, v30
	v_fmac_f32_e32 v41, v21, v31
	v_fmac_f32_e32 v40, v22, v32
	v_fmac_f32_e32 v41, v23, v34
	v_add_f32_e32 v35, v40, v41
	s_nop 1
	v_add_f32_dpp v35, v35, v35 quad_perm:[1,0,3,2] row_mask:0xf bank_mask:0xf bound_ctrl:1
	ds_read_b128 v[0:3], v173 offset:20736
	ds_read_b128 v[4:7], v173 offset:20752
	ds_read_b128 v[8:11], v173 offset:12544
	ds_read_b128 v[12:15], v173 offset:12560
	ds_read_b32 v33, v172 offset:33280
	ds_read_b128 v[16:19], v173 offset:4352
	ds_read_b128 v[20:23], v173 offset:4368
	s_waitcnt lgkmcnt(8)
	v_mul_f32_e32 v26, v176, v26
	v_mul_f32_e32 v27, v177, v27
	v_mul_f32_e32 v28, v178, v28
	v_mul_f32_e32 v29, v179, v29
	v_mul_f32_e32 v30, v180, v30
	v_mul_f32_e32 v31, v181, v31
	v_mul_f32_e32 v32, v182, v32
	v_mul_f32_e32 v34, v183, v34
	v_add_f32_dpp v35, v35, v35 quad_perm:[2,3,0,1] row_mask:0xf bank_mask:0xf bound_ctrl:1
	ds_write_b32 v174, v35
	v_add_u32_e32 v174, v174, v161
	v_fmac_f32_e32 v26, v184, v200
	v_fmac_f32_e32 v27, v185, v200
	v_fmac_f32_e32 v28, v186, v200
	v_fmac_f32_e32 v29, v187, v200
	v_fmac_f32_e32 v30, v188, v200
	v_fmac_f32_e32 v31, v189, v200
	v_fmac_f32_e32 v32, v190, v200
	v_fmac_f32_e32 v34, v191, v200
	v_mul_f32_e32 v40, v192, v26
	v_mul_f32_e32 v41, v193, v27
	v_fmac_f32_e32 v40, v194, v28
	v_fmac_f32_e32 v41, v195, v29
	v_fmac_f32_e32 v40, v196, v30
	v_fmac_f32_e32 v41, v197, v31
	v_fmac_f32_e32 v40, v198, v32
	v_fmac_f32_e32 v41, v199, v34
	v_add_f32_e32 v35, v40, v41
	s_nop 1
	v_add_f32_dpp v35, v35, v35 quad_perm:[1,0,3,2] row_mask:0xf bank_mask:0xf bound_ctrl:1
	ds_read_b128 v[176:179], v173 offset:20864
	ds_read_b128 v[180:183], v173 offset:20880
	ds_read_b128 v[184:187], v173 offset:12672
	ds_read_b128 v[188:191], v173 offset:12688
	ds_read_b32 v200, v172 offset:33536
	ds_read_b128 v[192:195], v173 offset:4480
	ds_read_b128 v[196:199], v173 offset:4496
	s_waitcnt lgkmcnt(8)
	v_mul_f32_e32 v26, v0, v26
	v_mul_f32_e32 v27, v1, v27
	v_mul_f32_e32 v28, v2, v28
	v_mul_f32_e32 v29, v3, v29
	v_mul_f32_e32 v30, v4, v30
	v_mul_f32_e32 v31, v5, v31
	v_mul_f32_e32 v32, v6, v32
	v_mul_f32_e32 v34, v7, v34
	v_add_f32_dpp v35, v35, v35 quad_perm:[2,3,0,1] row_mask:0xf bank_mask:0xf bound_ctrl:1
	ds_write_b32 v174, v35
	v_add_u32_e32 v174, v174, v161
	v_fmac_f32_e32 v26, v8, v33
	v_fmac_f32_e32 v27, v9, v33
	v_fmac_f32_e32 v28, v10, v33
	v_fmac_f32_e32 v29, v11, v33
	v_fmac_f32_e32 v30, v12, v33
	v_fmac_f32_e32 v31, v13, v33
	v_fmac_f32_e32 v32, v14, v33
	v_fmac_f32_e32 v34, v15, v33
	v_mul_f32_e32 v40, v16, v26
	v_mul_f32_e32 v41, v17, v27
	v_fmac_f32_e32 v40, v18, v28
	v_fmac_f32_e32 v41, v19, v29
	v_fmac_f32_e32 v40, v20, v30
	v_fmac_f32_e32 v41, v21, v31
	v_fmac_f32_e32 v40, v22, v32
	v_fmac_f32_e32 v41, v23, v34
	v_add_f32_e32 v35, v40, v41
	s_nop 1
	v_add_f32_dpp v35, v35, v35 quad_perm:[1,0,3,2] row_mask:0xf bank_mask:0xf bound_ctrl:1
	ds_read_b128 v[0:3], v173 offset:20992
	ds_read_b128 v[4:7], v173 offset:21008
	ds_read_b128 v[8:11], v173 offset:12800
	ds_read_b128 v[12:15], v173 offset:12816
	ds_read_b32 v33, v172 offset:33792
	ds_read_b128 v[16:19], v173 offset:4608
	ds_read_b128 v[20:23], v173 offset:4624
	s_waitcnt lgkmcnt(8)
	v_mul_f32_e32 v26, v176, v26
	v_mul_f32_e32 v27, v177, v27
	v_mul_f32_e32 v28, v178, v28
	v_mul_f32_e32 v29, v179, v29
	v_mul_f32_e32 v30, v180, v30
	v_mul_f32_e32 v31, v181, v31
	v_mul_f32_e32 v32, v182, v32
	v_mul_f32_e32 v34, v183, v34
	v_add_f32_dpp v35, v35, v35 quad_perm:[2,3,0,1] row_mask:0xf bank_mask:0xf bound_ctrl:1
	ds_write_b32 v174, v35
	v_add_u32_e32 v174, v174, v161
	v_fmac_f32_e32 v26, v184, v200
	v_fmac_f32_e32 v27, v185, v200
	v_fmac_f32_e32 v28, v186, v200
	v_fmac_f32_e32 v29, v187, v200
	v_fmac_f32_e32 v30, v188, v200
	v_fmac_f32_e32 v31, v189, v200
	v_fmac_f32_e32 v32, v190, v200
	v_fmac_f32_e32 v34, v191, v200
	v_mul_f32_e32 v40, v192, v26
	v_mul_f32_e32 v41, v193, v27
	v_fmac_f32_e32 v40, v194, v28
	v_fmac_f32_e32 v41, v195, v29
	v_fmac_f32_e32 v40, v196, v30
	v_fmac_f32_e32 v41, v197, v31
	v_fmac_f32_e32 v40, v198, v32
	v_fmac_f32_e32 v41, v199, v34
	v_add_f32_e32 v35, v40, v41
	s_nop 1
	v_add_f32_dpp v35, v35, v35 quad_perm:[1,0,3,2] row_mask:0xf bank_mask:0xf bound_ctrl:1
	ds_read_b128 v[176:179], v173 offset:21120
	ds_read_b128 v[180:183], v173 offset:21136
	ds_read_b128 v[184:187], v173 offset:12928
	ds_read_b128 v[188:191], v173 offset:12944
	ds_read_b32 v200, v172 offset:34048
	ds_read_b128 v[192:195], v173 offset:4736
	ds_read_b128 v[196:199], v173 offset:4752
	s_waitcnt lgkmcnt(8)
; #define GLA_LD(t_, aq, kq, qq, vq) do { const int tt_ = (t_); vq = Bs[6144 + tt_ * 64 + pp]; \
;             _Pragma("unroll") for (int u = 0; u < 2; ++u) { aq[u] = *(const LAS f32x4*)(Bs + 4096 + tt_ * 32 + k0 + 4 * u); kq[u] = *(const LAS f32x4*)(Bs + 2048 + tt_ * 32 + k0 + 4 * u); qq[u] = *(const LAS f32x4*)(Bs + tt_ * 32 + k0 + 4 * u); } } while (0)
; #define GLA_STEP(t_, aq, kq, qq, vq) do { float y = 0.f; \
;             _Pragma("unroll") for (int u = 0; u < 2; ++u) _Pragma("unroll") for (int j = 0; j < 4; ++j) { S[4 * u + j] = aq[u][j] * S[4 * u + j] + kq[u][j] * vq; y += qq[u][j] * S[4 * u + j]; } \
;             y += dpp_f(y, 0xB1); y += dpp_f(y, 0x4E); ydst[(t_) * ystride] = y; } while (0)
; __device__ __forceinline__ void gla_job(const bf16_t* P, bf16_t* Y, int l, int b, int h, LAS float* lds, int wave_s) {
;     ...
;             GLA_LD(0, a0_, k0_, q0_, v0_);
;             for (int t = 0; t < TC; t += 2) {
;                 GLA_LD(t + 1, a1_, k1_, q1_, v1_);
;                 GLA_STEP(t, a0_, k0_, q0_, v0_);
;                 GLA_LD(t + 2 < TC ? t + 2 : t + 1, a0_, k0_, q0_, v0_);
;                 GLA_STEP(t + 1, a1_, k1_, q1_, v1_);
	v_mul_f32_e32 v26, v0, v26
	v_mul_f32_e32 v27, v1, v27
	v_mul_f32_e32 v28, v2, v28
	v_mul_f32_e32 v29, v3, v29
	v_mul_f32_e32 v30, v4, v30
	v_mul_f32_e32 v31, v5, v31
	v_mul_f32_e32 v32, v6, v32
	v_mul_f32_e32 v34, v7, v34
	v_add_f32_dpp v35, v35, v35 quad_perm:[2,3,0,1] row_mask:0xf bank_mask:0xf bound_ctrl:1
	ds_write_b32 v174, v35
	v_add_u32_e32 v174, v174, v161
	v_fmac_f32_e32 v26, v8, v33
	v_fmac_f32_e32 v27, v9, v33
	v_fmac_f32_e32 v28, v10, v33
	v_fmac_f32_e32 v29, v11, v33
	v_fmac_f32_e32 v30, v12, v33
	v_fmac_f32_e32 v31, v13, v33
	v_fmac_f32_e32 v32, v14, v33
	v_fmac_f32_e32 v34, v15, v33
	v_mul_f32_e32 v40, v16, v26
	v_mul_f32_e32 v41, v17, v27
	v_fmac_f32_e32 v40, v18, v28
	v_fmac_f32_e32 v41, v19, v29
	v_fmac_f32_e32 v40, v20, v30
	v_fmac_f32_e32 v41, v21, v31
	v_fmac_f32_e32 v40, v22, v32
	v_fmac_f32_e32 v41, v23, v34
	v_add_f32_e32 v35, v40, v41
	s_nop 1
	v_add_f32_dpp v35, v35, v35 quad_perm:[1,0,3,2] row_mask:0xf bank_mask:0xf bound_ctrl:1
	ds_read_b128 v[0:3], v173 offset:21248
	ds_read_b128 v[4:7], v173 offset:21264
	ds_read_b128 v[8:11], v173 offset:13056
	ds_read_b128 v[12:15], v173 offset:13072
	ds_read_b32 v33, v172 offset:34304
	ds_read_b128 v[16:19], v173 offset:4864
	ds_read_b128 v[20:23], v173 offset:4880
	s_waitcnt lgkmcnt(8)
	v_mul_f32_e32 v26, v176, v26
	v_mul_f32_e32 v27, v177, v27
	v_mul_f32_e32 v28, v178, v28
	v_mul_f32_e32 v29, v179, v29
	v_mul_f32_e32 v30, v180, v30
	v_mul_f32_e32 v31, v181, v31
	v_mul_f32_e32 v32, v182, v32
	v_mul_f32_e32 v34, v183, v34
	v_add_f32_dpp v35, v35, v35 quad_perm:[2,3,0,1] row_mask:0xf bank_mask:0xf bound_ctrl:1
	ds_write_b32 v174, v35
	v_add_u32_e32 v174, v174, v161
	v_fmac_f32_e32 v26, v184, v200
	v_fmac_f32_e32 v27, v185, v200
	v_fmac_f32_e32 v28, v186, v200
	v_fmac_f32_e32 v29, v187, v200
	v_fmac_f32_e32 v30, v188, v200
	v_fmac_f32_e32 v31, v189, v200
	v_fmac_f32_e32 v32, v190, v200
	v_fmac_f32_e32 v34, v191, v200
	v_mul_f32_e32 v40, v192, v26
	v_mul_f32_e32 v41, v193, v27
	v_fmac_f32_e32 v40, v194, v28
	v_fmac_f32_e32 v41, v195, v29
	v_fmac_f32_e32 v40, v196, v30
	v_fmac_f32_e32 v41, v197, v31
	v_fmac_f32_e32 v40, v198, v32
	v_fmac_f32_e32 v41, v199, v34
	v_add_f32_e32 v35, v40, v41
	s_nop 1
	v_add_f32_dpp v35, v35, v35 quad_perm:[1,0,3,2] row_mask:0xf bank_mask:0xf bound_ctrl:1
	ds_read_b128 v[176:179], v173 offset:21376
	ds_read_b128 v[180:183], v173 offset:21392
	ds_read_b128 v[184:187], v173 offset:13184
	ds_read_b128 v[188:191], v173 offset:13200
	ds_read_b32 v200, v172 offset:34560
	ds_read_b128 v[192:195], v173 offset:4992
	ds_read_b128 v[196:199], v173 offset:5008
	s_waitcnt lgkmcnt(8)
	v_mul_f32_e32 v26, v0, v26
	v_mul_f32_e32 v27, v1, v27
	v_mul_f32_e32 v28, v2, v28
	v_mul_f32_e32 v29, v3, v29
	v_mul_f32_e32 v30, v4, v30
	v_mul_f32_e32 v31, v5, v31
	v_mul_f32_e32 v32, v6, v32
	v_mul_f32_e32 v34, v7, v34
	v_add_f32_dpp v35, v35, v35 quad_perm:[2,3,0,1] row_mask:0xf bank_mask:0xf bound_ctrl:1
	ds_write_b32 v174, v35
	v_add_u32_e32 v174, v174, v161
	v_fmac_f32_e32 v26, v8, v33
	v_fmac_f32_e32 v27, v9, v33
	v_fmac_f32_e32 v28, v10, v33
	v_fmac_f32_e32 v29, v11, v33
	v_fmac_f32_e32 v30, v12, v33
	v_fmac_f32_e32 v31, v13, v33
	v_fmac_f32_e32 v32, v14, v33
	v_fmac_f32_e32 v34, v15, v33
	v_mul_f32_e32 v40, v16, v26
	v_mul_f32_e32 v41, v17, v27
	v_fmac_f32_e32 v40, v18, v28
	v_fmac_f32_e32 v41, v19, v29
	v_fmac_f32_e32 v40, v20, v30
	v_fmac_f32_e32 v41, v21, v31
	v_fmac_f32_e32 v40, v22, v32
	v_fmac_f32_e32 v41, v23, v34
	v_add_f32_e32 v35, v40, v41
	s_nop 1
	v_add_f32_dpp v35, v35, v35 quad_perm:[1,0,3,2] row_mask:0xf bank_mask:0xf bound_ctrl:1
	ds_read_b128 v[0:3], v173 offset:21504
	ds_read_b128 v[4:7], v173 offset:21520
	ds_read_b128 v[8:11], v173 offset:13312
	ds_read_b128 v[12:15], v173 offset:13328
	ds_read_b32 v33, v172 offset:34816
	ds_read_b128 v[16:19], v173 offset:5120
	ds_read_b128 v[20:23], v173 offset:5136
	s_waitcnt lgkmcnt(8)
	v_mul_f32_e32 v26, v176, v26
	v_mul_f32_e32 v27, v177, v27
	v_mul_f32_e32 v28, v178, v28
	v_mul_f32_e32 v29, v179, v29
	v_mul_f32_e32 v30, v180, v30
	v_mul_f32_e32 v31, v181, v31
	v_mul_f32_e32 v32, v182, v32
	v_mul_f32_e32 v34, v183, v34
	v_add_f32_dpp v35, v35, v35 quad_perm:[2,3,0,1] row_mask:0xf bank_mask:0xf bound_ctrl:1
	ds_write_b32 v174, v35
	v_add_u32_e32 v174, v174, v161
	v_fmac_f32_e32 v26, v184, v200
	v_fmac_f32_e32 v27, v185, v200
	v_fmac_f32_e32 v28, v186, v200
	v_fmac_f32_e32 v29, v187, v200
	v_fmac_f32_e32 v30, v188, v200
	v_fmac_f32_e32 v31, v189, v200
	v_fmac_f32_e32 v32, v190, v200
	v_fmac_f32_e32 v34, v191, v200
	v_mul_f32_e32 v40, v192, v26
	v_mul_f32_e32 v41, v193, v27
	v_fmac_f32_e32 v40, v194, v28
	v_fmac_f32_e32 v41, v195, v29
	v_fmac_f32_e32 v40, v196, v30
	v_fmac_f32_e32 v41, v197, v31
	v_fmac_f32_e32 v40, v198, v32
	v_fmac_f32_e32 v41, v199, v34
	v_add_f32_e32 v35, v40, v41
	s_nop 1
	v_add_f32_dpp v35, v35, v35 quad_perm:[1,0,3,2] row_mask:0xf bank_mask:0xf bound_ctrl:1
	ds_read_b128 v[176:179], v173 offset:21632
	ds_read_b128 v[180:183], v173 offset:21648
	ds_read_b128 v[184:187], v173 offset:13440
	ds_read_b128 v[188:191], v173 offset:13456
	ds_read_b32 v200, v172 offset:35072
	ds_read_b128 v[192:195], v173 offset:5248
	ds_read_b128 v[196:199], v173 offset:5264
	s_waitcnt lgkmcnt(8)
; #define GLA_LD(t_, aq, kq, qq, vq) do { const int tt_ = (t_); vq = Bs[6144 + tt_ * 64 + pp]; \
;             _Pragma("unroll") for (int u = 0; u < 2; ++u) { aq[u] = *(const LAS f32x4*)(Bs + 4096 + tt_ * 32 + k0 + 4 * u); kq[u] = *(const LAS f32x4*)(Bs + 2048 + tt_ * 32 + k0 + 4 * u); qq[u] = *(const LAS f32x4*)(Bs + tt_ * 32 + k0 + 4 * u); } } while (0)
; #define GLA_STEP(t_, aq, kq, qq, vq) do { float y = 0.f; \
;             _Pragma("unroll") for (int u = 0; u < 2; ++u) _Pragma("unroll") for (int j = 0; j < 4; ++j) { S[4 * u + j] = aq[u][j] * S[4 * u + j] + kq[u][j] * vq; y += qq[u][j] * S[4 * u + j]; } \
;             y += dpp_f(y, 0xB1); y += dpp_f(y, 0x4E); ydst[(t_) * ystride] = y; } while (0)
; __device__ __forceinline__ void gla_job(const bf16_t* P, bf16_t* Y, int l, int b, int h, LAS float* lds, int wave_s) {
;     ...
;             GLA_LD(0, a0_, k0_, q0_, v0_);
;             for (int t = 0; t < TC; t += 2) {
;                 GLA_LD(t + 1, a1_, k1_, q1_, v1_);
;                 GLA_STEP(t, a0_, k0_, q0_, v0_);
;                 GLA_LD(t + 2 < TC ? t + 2 : t + 1, a0_, k0_, q0_, v0_);
;                 GLA_STEP(t + 1, a1_, k1_, q1_, v1_);
	v_mul_f32_e32 v26, v0, v26
	v_mul_f32_e32 v27, v1, v27
	v_mul_f32_e32 v28, v2, v28
	v_mul_f32_e32 v29, v3, v29
	v_mul_f32_e32 v30, v4, v30
	v_mul_f32_e32 v31, v5, v31
	v_mul_f32_e32 v32, v6, v32
	v_mul_f32_e32 v34, v7, v34
	v_add_f32_dpp v35, v35, v35 quad_perm:[2,3,0,1] row_mask:0xf bank_mask:0xf bound_ctrl:1
	ds_write_b32 v174, v35
	v_add_u32_e32 v174, v174, v161
	v_fmac_f32_e32 v26, v8, v33
	v_fmac_f32_e32 v27, v9, v33
	v_fmac_f32_e32 v28, v10, v33
	v_fmac_f32_e32 v29, v11, v33
	v_fmac_f32_e32 v30, v12, v33
	v_fmac_f32_e32 v31, v13, v33
	v_fmac_f32_e32 v32, v14, v33
	v_fmac_f32_e32 v34, v15, v33
	v_mul_f32_e32 v40, v16, v26
	v_mul_f32_e32 v41, v17, v27
	v_fmac_f32_e32 v40, v18, v28
	v_fmac_f32_e32 v41, v19, v29
	v_fmac_f32_e32 v40, v20, v30
	v_fmac_f32_e32 v41, v21, v31
	v_fmac_f32_e32 v40, v22, v32
	v_fmac_f32_e32 v41, v23, v34
	v_add_f32_e32 v35, v40, v41
	s_nop 1
	v_add_f32_dpp v35, v35, v35 quad_perm:[1,0,3,2] row_mask:0xf bank_mask:0xf bound_ctrl:1
	ds_read_b128 v[0:3], v173 offset:21760
	ds_read_b128 v[4:7], v173 offset:21776
	ds_read_b128 v[8:11], v173 offset:13568
	ds_read_b128 v[12:15], v173 offset:13584
	ds_read_b32 v33, v172 offset:35328
	ds_read_b128 v[16:19], v173 offset:5376
	ds_read_b128 v[20:23], v173 offset:5392
	s_waitcnt lgkmcnt(8)
	v_mul_f32_e32 v26, v176, v26
	v_mul_f32_e32 v27, v177, v27
	v_mul_f32_e32 v28, v178, v28
	v_mul_f32_e32 v29, v179, v29
	v_mul_f32_e32 v30, v180, v30
	v_mul_f32_e32 v31, v181, v31
	v_mul_f32_e32 v32, v182, v32
	v_mul_f32_e32 v34, v183, v34
	v_add_f32_dpp v35, v35, v35 quad_perm:[2,3,0,1] row_mask:0xf bank_mask:0xf bound_ctrl:1
	ds_write_b32 v174, v35
	v_add_u32_e32 v174, v174, v161
	v_fmac_f32_e32 v26, v184, v200
	v_fmac_f32_e32 v27, v185, v200
	v_fmac_f32_e32 v28, v186, v200
	v_fmac_f32_e32 v29, v187, v200
	v_fmac_f32_e32 v30, v188, v200
	v_fmac_f32_e32 v31, v189, v200
	v_fmac_f32_e32 v32, v190, v200
	v_fmac_f32_e32 v34, v191, v200
	v_mul_f32_e32 v40, v192, v26
	v_mul_f32_e32 v41, v193, v27
	v_fmac_f32_e32 v40, v194, v28
	v_fmac_f32_e32 v41, v195, v29
	v_fmac_f32_e32 v40, v196, v30
	v_fmac_f32_e32 v41, v197, v31
	v_fmac_f32_e32 v40, v198, v32
	v_fmac_f32_e32 v41, v199, v34
	v_add_f32_e32 v35, v40, v41
	s_nop 1
	v_add_f32_dpp v35, v35, v35 quad_perm:[1,0,3,2] row_mask:0xf bank_mask:0xf bound_ctrl:1
	ds_read_b128 v[176:179], v173 offset:21888
	ds_read_b128 v[180:183], v173 offset:21904
	ds_read_b128 v[184:187], v173 offset:13696
	ds_read_b128 v[188:191], v173 offset:13712
	ds_read_b32 v200, v172 offset:35584
	ds_read_b128 v[192:195], v173 offset:5504
	ds_read_b128 v[196:199], v173 offset:5520
	s_waitcnt lgkmcnt(8)
	v_mul_f32_e32 v26, v0, v26
	v_mul_f32_e32 v27, v1, v27
	v_mul_f32_e32 v28, v2, v28
	v_mul_f32_e32 v29, v3, v29
	v_mul_f32_e32 v30, v4, v30
	v_mul_f32_e32 v31, v5, v31
	v_mul_f32_e32 v32, v6, v32
	v_mul_f32_e32 v34, v7, v34
	v_add_f32_dpp v35, v35, v35 quad_perm:[2,3,0,1] row_mask:0xf bank_mask:0xf bound_ctrl:1
	ds_write_b32 v174, v35
	v_add_u32_e32 v174, v174, v161
	v_fmac_f32_e32 v26, v8, v33
	v_fmac_f32_e32 v27, v9, v33
	v_fmac_f32_e32 v28, v10, v33
	v_fmac_f32_e32 v29, v11, v33
	v_fmac_f32_e32 v30, v12, v33
	v_fmac_f32_e32 v31, v13, v33
	v_fmac_f32_e32 v32, v14, v33
	v_fmac_f32_e32 v34, v15, v33
	v_mul_f32_e32 v40, v16, v26
	v_mul_f32_e32 v41, v17, v27
	v_fmac_f32_e32 v40, v18, v28
	v_fmac_f32_e32 v41, v19, v29
	v_fmac_f32_e32 v40, v20, v30
	v_fmac_f32_e32 v41, v21, v31
	v_fmac_f32_e32 v40, v22, v32
	v_fmac_f32_e32 v41, v23, v34
	v_add_f32_e32 v35, v40, v41
	s_nop 1
	v_add_f32_dpp v35, v35, v35 quad_perm:[1,0,3,2] row_mask:0xf bank_mask:0xf bound_ctrl:1
	ds_read_b128 v[0:3], v173 offset:22016
	ds_read_b128 v[4:7], v173 offset:22032
	ds_read_b128 v[8:11], v173 offset:13824
	ds_read_b128 v[12:15], v173 offset:13840
	ds_read_b32 v33, v172 offset:35840
	ds_read_b128 v[16:19], v173 offset:5632
	ds_read_b128 v[20:23], v173 offset:5648
	s_waitcnt lgkmcnt(8)
	v_mul_f32_e32 v26, v176, v26
	v_mul_f32_e32 v27, v177, v27
	v_mul_f32_e32 v28, v178, v28
	v_mul_f32_e32 v29, v179, v29
	v_mul_f32_e32 v30, v180, v30
	v_mul_f32_e32 v31, v181, v31
	v_mul_f32_e32 v32, v182, v32
	v_mul_f32_e32 v34, v183, v34
	v_add_f32_dpp v35, v35, v35 quad_perm:[2,3,0,1] row_mask:0xf bank_mask:0xf bound_ctrl:1
	ds_write_b32 v174, v35
	v_add_u32_e32 v174, v174, v161
	v_fmac_f32_e32 v26, v184, v200
	v_fmac_f32_e32 v27, v185, v200
	v_fmac_f32_e32 v28, v186, v200
	v_fmac_f32_e32 v29, v187, v200
	v_fmac_f32_e32 v30, v188, v200
	v_fmac_f32_e32 v31, v189, v200
	v_fmac_f32_e32 v32, v190, v200
	v_fmac_f32_e32 v34, v191, v200
	v_mul_f32_e32 v40, v192, v26
	v_mul_f32_e32 v41, v193, v27
	v_fmac_f32_e32 v40, v194, v28
	v_fmac_f32_e32 v41, v195, v29
	v_fmac_f32_e32 v40, v196, v30
	v_fmac_f32_e32 v41, v197, v31
	v_fmac_f32_e32 v40, v198, v32
	v_fmac_f32_e32 v41, v199, v34
	v_add_f32_e32 v35, v40, v41
	s_nop 1
	v_add_f32_dpp v35, v35, v35 quad_perm:[1,0,3,2] row_mask:0xf bank_mask:0xf bound_ctrl:1
	ds_read_b128 v[176:179], v173 offset:22144
	ds_read_b128 v[180:183], v173 offset:22160
	ds_read_b128 v[184:187], v173 offset:13952
	ds_read_b128 v[188:191], v173 offset:13968
	ds_read_b32 v200, v172 offset:36096
	ds_read_b128 v[192:195], v173 offset:5760
	ds_read_b128 v[196:199], v173 offset:5776
	s_waitcnt lgkmcnt(8)
; #define GLA_LD(t_, aq, kq, qq, vq) do { const int tt_ = (t_); vq = Bs[6144 + tt_ * 64 + pp]; \
;             _Pragma("unroll") for (int u = 0; u < 2; ++u) { aq[u] = *(const LAS f32x4*)(Bs + 4096 + tt_ * 32 + k0 + 4 * u); kq[u] = *(const LAS f32x4*)(Bs + 2048 + tt_ * 32 + k0 + 4 * u); qq[u] = *(const LAS f32x4*)(Bs + tt_ * 32 + k0 + 4 * u); } } while (0)
; #define GLA_STEP(t_, aq, kq, qq, vq) do { float y = 0.f; \
;             _Pragma("unroll") for (int u = 0; u < 2; ++u) _Pragma("unroll") for (int j = 0; j < 4; ++j) { S[4 * u + j] = aq[u][j] * S[4 * u + j] + kq[u][j] * vq; y += qq[u][j] * S[4 * u + j]; } \
;             y += dpp_f(y, 0xB1); y += dpp_f(y, 0x4E); ydst[(t_) * ystride] = y; } while (0)
; __device__ __forceinline__ void gla_job(const bf16_t* P, bf16_t* Y, int l, int b, int h, LAS float* lds, int wave_s) {
;     ...
;             GLA_LD(0, a0_, k0_, q0_, v0_);
;             for (int t = 0; t < TC; t += 2) {
;                 GLA_LD(t + 1, a1_, k1_, q1_, v1_);
;                 GLA_STEP(t, a0_, k0_, q0_, v0_);
;                 GLA_LD(t + 2 < TC ? t + 2 : t + 1, a0_, k0_, q0_, v0_);
;                 GLA_STEP(t + 1, a1_, k1_, q1_, v1_);
	v_mul_f32_e32 v26, v0, v26
	v_mul_f32_e32 v27, v1, v27
	v_mul_f32_e32 v28, v2, v28
	v_mul_f32_e32 v29, v3, v29
	v_mul_f32_e32 v30, v4, v30
	v_mul_f32_e32 v31, v5, v31
	v_mul_f32_e32 v32, v6, v32
	v_mul_f32_e32 v34, v7, v34
	v_add_f32_dpp v35, v35, v35 quad_perm:[2,3,0,1] row_mask:0xf bank_mask:0xf bound_ctrl:1
	ds_write_b32 v174, v35
	v_add_u32_e32 v174, v174, v161
	v_fmac_f32_e32 v26, v8, v33
	v_fmac_f32_e32 v27, v9, v33
	v_fmac_f32_e32 v28, v10, v33
	v_fmac_f32_e32 v29, v11, v33
	v_fmac_f32_e32 v30, v12, v33
	v_fmac_f32_e32 v31, v13, v33
	v_fmac_f32_e32 v32, v14, v33
	v_fmac_f32_e32 v34, v15, v33
	v_mul_f32_e32 v40, v16, v26
	v_mul_f32_e32 v41, v17, v27
	v_fmac_f32_e32 v40, v18, v28
	v_fmac_f32_e32 v41, v19, v29
	v_fmac_f32_e32 v40, v20, v30
	v_fmac_f32_e32 v41, v21, v31
	v_fmac_f32_e32 v40, v22, v32
	v_fmac_f32_e32 v41, v23, v34
	v_add_f32_e32 v35, v40, v41
	s_nop 1
	v_add_f32_dpp v35, v35, v35 quad_perm:[1,0,3,2] row_mask:0xf bank_mask:0xf bound_ctrl:1
	ds_read_b128 v[0:3], v173 offset:22272
	ds_read_b128 v[4:7], v173 offset:22288
	ds_read_b128 v[8:11], v173 offset:14080
	ds_read_b128 v[12:15], v173 offset:14096
	ds_read_b32 v33, v172 offset:36352
	ds_read_b128 v[16:19], v173 offset:5888
	ds_read_b128 v[20:23], v173 offset:5904
	s_waitcnt lgkmcnt(8)
	v_mul_f32_e32 v26, v176, v26
	v_mul_f32_e32 v27, v177, v27
	v_mul_f32_e32 v28, v178, v28
	v_mul_f32_e32 v29, v179, v29
	v_mul_f32_e32 v30, v180, v30
	v_mul_f32_e32 v31, v181, v31
	v_mul_f32_e32 v32, v182, v32
	v_mul_f32_e32 v34, v183, v34
	v_add_f32_dpp v35, v35, v35 quad_perm:[2,3,0,1] row_mask:0xf bank_mask:0xf bound_ctrl:1
	ds_write_b32 v174, v35
	v_add_u32_e32 v174, v174, v161
	v_fmac_f32_e32 v26, v184, v200
	v_fmac_f32_e32 v27, v185, v200
	v_fmac_f32_e32 v28, v186, v200
	v_fmac_f32_e32 v29, v187, v200
	v_fmac_f32_e32 v30, v188, v200
	v_fmac_f32_e32 v31, v189, v200
	v_fmac_f32_e32 v32, v190, v200
	v_fmac_f32_e32 v34, v191, v200
	v_mul_f32_e32 v40, v192, v26
	v_mul_f32_e32 v41, v193, v27
	v_fmac_f32_e32 v40, v194, v28
	v_fmac_f32_e32 v41, v195, v29
	v_fmac_f32_e32 v40, v196, v30
	v_fmac_f32_e32 v41, v197, v31
	v_fmac_f32_e32 v40, v198, v32
	v_fmac_f32_e32 v41, v199, v34
	v_add_f32_e32 v35, v40, v41
	s_nop 1
	v_add_f32_dpp v35, v35, v35 quad_perm:[1,0,3,2] row_mask:0xf bank_mask:0xf bound_ctrl:1
	ds_read_b128 v[176:179], v173 offset:22400
	ds_read_b128 v[180:183], v173 offset:22416
	ds_read_b128 v[184:187], v173 offset:14208
	ds_read_b128 v[188:191], v173 offset:14224
	ds_read_b32 v200, v172 offset:36608
	ds_read_b128 v[192:195], v173 offset:6016
	ds_read_b128 v[196:199], v173 offset:6032
	s_waitcnt lgkmcnt(8)
	v_mul_f32_e32 v26, v0, v26
	v_mul_f32_e32 v27, v1, v27
	v_mul_f32_e32 v28, v2, v28
	v_mul_f32_e32 v29, v3, v29
	v_mul_f32_e32 v30, v4, v30
	v_mul_f32_e32 v31, v5, v31
	v_mul_f32_e32 v32, v6, v32
	v_mul_f32_e32 v34, v7, v34
	v_add_f32_dpp v35, v35, v35 quad_perm:[2,3,0,1] row_mask:0xf bank_mask:0xf bound_ctrl:1
	ds_write_b32 v174, v35
	v_add_u32_e32 v174, v174, v161
	v_fmac_f32_e32 v26, v8, v33
	v_fmac_f32_e32 v27, v9, v33
	v_fmac_f32_e32 v28, v10, v33
	v_fmac_f32_e32 v29, v11, v33
	v_fmac_f32_e32 v30, v12, v33
	v_fmac_f32_e32 v31, v13, v33
	v_fmac_f32_e32 v32, v14, v33
	v_fmac_f32_e32 v34, v15, v33
	v_mul_f32_e32 v40, v16, v26
	v_mul_f32_e32 v41, v17, v27
	v_fmac_f32_e32 v40, v18, v28
	v_fmac_f32_e32 v41, v19, v29
	v_fmac_f32_e32 v40, v20, v30
	v_fmac_f32_e32 v41, v21, v31
	v_fmac_f32_e32 v40, v22, v32
	v_fmac_f32_e32 v41, v23, v34
	v_add_f32_e32 v35, v40, v41
	s_nop 1
	v_add_f32_dpp v35, v35, v35 quad_perm:[1,0,3,2] row_mask:0xf bank_mask:0xf bound_ctrl:1
	ds_read_b128 v[0:3], v173 offset:22528
	ds_read_b128 v[4:7], v173 offset:22544
	ds_read_b128 v[8:11], v173 offset:14336
	ds_read_b128 v[12:15], v173 offset:14352
	ds_read_b32 v33, v172 offset:36864
	ds_read_b128 v[16:19], v173 offset:6144
	ds_read_b128 v[20:23], v173 offset:6160
	s_waitcnt lgkmcnt(8)
	v_mul_f32_e32 v26, v176, v26
	v_mul_f32_e32 v27, v177, v27
	v_mul_f32_e32 v28, v178, v28
	v_mul_f32_e32 v29, v179, v29
	v_mul_f32_e32 v30, v180, v30
	v_mul_f32_e32 v31, v181, v31
	v_mul_f32_e32 v32, v182, v32
	v_mul_f32_e32 v34, v183, v34
	v_add_f32_dpp v35, v35, v35 quad_perm:[2,3,0,1] row_mask:0xf bank_mask:0xf bound_ctrl:1
	ds_write_b32 v174, v35
	v_add_u32_e32 v174, v174, v161
	v_fmac_f32_e32 v26, v184, v200
	v_fmac_f32_e32 v27, v185, v200
	v_fmac_f32_e32 v28, v186, v200
	v_fmac_f32_e32 v29, v187, v200
	v_fmac_f32_e32 v30, v188, v200
	v_fmac_f32_e32 v31, v189, v200
	v_fmac_f32_e32 v32, v190, v200
	v_fmac_f32_e32 v34, v191, v200
	v_mul_f32_e32 v40, v192, v26
	v_mul_f32_e32 v41, v193, v27
	v_fmac_f32_e32 v40, v194, v28
	v_fmac_f32_e32 v41, v195, v29
	v_fmac_f32_e32 v40, v196, v30
	v_fmac_f32_e32 v41, v197, v31
	v_fmac_f32_e32 v40, v198, v32
	v_fmac_f32_e32 v41, v199, v34
	v_add_f32_e32 v35, v40, v41
	s_nop 1
	v_add_f32_dpp v35, v35, v35 quad_perm:[1,0,3,2] row_mask:0xf bank_mask:0xf bound_ctrl:1
	ds_read_b128 v[176:179], v173 offset:22656
	ds_read_b128 v[180:183], v173 offset:22672
	ds_read_b128 v[184:187], v173 offset:14464
	ds_read_b128 v[188:191], v173 offset:14480
	ds_read_b32 v200, v172 offset:37120
	ds_read_b128 v[192:195], v173 offset:6272
	ds_read_b128 v[196:199], v173 offset:6288
	s_waitcnt lgkmcnt(8)
; #define GLA_LD(t_, aq, kq, qq, vq) do { const int tt_ = (t_); vq = Bs[6144 + tt_ * 64 + pp]; \
;             _Pragma("unroll") for (int u = 0; u < 2; ++u) { aq[u] = *(const LAS f32x4*)(Bs + 4096 + tt_ * 32 + k0 + 4 * u); kq[u] = *(const LAS f32x4*)(Bs + 2048 + tt_ * 32 + k0 + 4 * u); qq[u] = *(const LAS f32x4*)(Bs + tt_ * 32 + k0 + 4 * u); } } while (0)
; #define GLA_STEP(t_, aq, kq, qq, vq) do { float y = 0.f; \
;             _Pragma("unroll") for (int u = 0; u < 2; ++u) _Pragma("unroll") for (int j = 0; j < 4; ++j) { S[4 * u + j] = aq[u][j] * S[4 * u + j] + kq[u][j] * vq; y += qq[u][j] * S[4 * u + j]; } \
;             y += dpp_f(y, 0xB1); y += dpp_f(y, 0x4E); ydst[(t_) * ystride] = y; } while (0)
; __device__ __forceinline__ void gla_job(const bf16_t* P, bf16_t* Y, int l, int b, int h, LAS float* lds, int wave_s) {
;     ...
;             GLA_LD(0, a0_, k0_, q0_, v0_);
;             for (int t = 0; t < TC; t += 2) {
;                 GLA_LD(t + 1, a1_, k1_, q1_, v1_);
;                 GLA_STEP(t, a0_, k0_, q0_, v0_);
;                 GLA_LD(t + 2 < TC ? t + 2 : t + 1, a0_, k0_, q0_, v0_);
;                 GLA_STEP(t + 1, a1_, k1_, q1_, v1_);
	v_mul_f32_e32 v26, v0, v26
	v_mul_f32_e32 v27, v1, v27
	v_mul_f32_e32 v28, v2, v28
	v_mul_f32_e32 v29, v3, v29
	v_mul_f32_e32 v30, v4, v30
	v_mul_f32_e32 v31, v5, v31
	v_mul_f32_e32 v32, v6, v32
	v_mul_f32_e32 v34, v7, v34
	v_add_f32_dpp v35, v35, v35 quad_perm:[2,3,0,1] row_mask:0xf bank_mask:0xf bound_ctrl:1
	ds_write_b32 v174, v35
	v_add_u32_e32 v174, v174, v161
	v_fmac_f32_e32 v26, v8, v33
	v_fmac_f32_e32 v27, v9, v33
	v_fmac_f32_e32 v28, v10, v33
	v_fmac_f32_e32 v29, v11, v33
	v_fmac_f32_e32 v30, v12, v33
	v_fmac_f32_e32 v31, v13, v33
	v_fmac_f32_e32 v32, v14, v33
	v_fmac_f32_e32 v34, v15, v33
	v_mul_f32_e32 v40, v16, v26
	v_mul_f32_e32 v41, v17, v27
	v_fmac_f32_e32 v40, v18, v28
	v_fmac_f32_e32 v41, v19, v29
	v_fmac_f32_e32 v40, v20, v30
	v_fmac_f32_e32 v41, v21, v31
	v_fmac_f32_e32 v40, v22, v32
	v_fmac_f32_e32 v41, v23, v34
	v_add_f32_e32 v35, v40, v41
	s_nop 1
	v_add_f32_dpp v35, v35, v35 quad_perm:[1,0,3,2] row_mask:0xf bank_mask:0xf bound_ctrl:1
	ds_read_b128 v[0:3], v173 offset:22784
	ds_read_b128 v[4:7], v173 offset:22800
	ds_read_b128 v[8:11], v173 offset:14592
	ds_read_b128 v[12:15], v173 offset:14608
	ds_read_b32 v33, v172 offset:37376
	ds_read_b128 v[16:19], v173 offset:6400
	ds_read_b128 v[20:23], v173 offset:6416
	s_waitcnt lgkmcnt(8)
	v_mul_f32_e32 v26, v176, v26
	v_mul_f32_e32 v27, v177, v27
	v_mul_f32_e32 v28, v178, v28
	v_mul_f32_e32 v29, v179, v29
	v_mul_f32_e32 v30, v180, v30
	v_mul_f32_e32 v31, v181, v31
	v_mul_f32_e32 v32, v182, v32
	v_mul_f32_e32 v34, v183, v34
	v_add_f32_dpp v35, v35, v35 quad_perm:[2,3,0,1] row_mask:0xf bank_mask:0xf bound_ctrl:1
	ds_write_b32 v174, v35
	v_add_u32_e32 v174, v174, v161
	v_fmac_f32_e32 v26, v184, v200
	v_fmac_f32_e32 v27, v185, v200
	v_fmac_f32_e32 v28, v186, v200
	v_fmac_f32_e32 v29, v187, v200
	v_fmac_f32_e32 v30, v188, v200
	v_fmac_f32_e32 v31, v189, v200
	v_fmac_f32_e32 v32, v190, v200
	v_fmac_f32_e32 v34, v191, v200
	v_mul_f32_e32 v40, v192, v26
	v_mul_f32_e32 v41, v193, v27
	v_fmac_f32_e32 v40, v194, v28
	v_fmac_f32_e32 v41, v195, v29
	v_fmac_f32_e32 v40, v196, v30
	v_fmac_f32_e32 v41, v197, v31
	v_fmac_f32_e32 v40, v198, v32
	v_fmac_f32_e32 v41, v199, v34
	v_add_f32_e32 v35, v40, v41
	s_nop 1
	v_add_f32_dpp v35, v35, v35 quad_perm:[1,0,3,2] row_mask:0xf bank_mask:0xf bound_ctrl:1
	ds_read_b128 v[176:179], v173 offset:22912
	ds_read_b128 v[180:183], v173 offset:22928
	ds_read_b128 v[184:187], v173 offset:14720
	ds_read_b128 v[188:191], v173 offset:14736
	ds_read_b32 v200, v172 offset:37632
	ds_read_b128 v[192:195], v173 offset:6528
	ds_read_b128 v[196:199], v173 offset:6544
	s_waitcnt lgkmcnt(8)
	v_mul_f32_e32 v26, v0, v26
	v_mul_f32_e32 v27, v1, v27
	v_mul_f32_e32 v28, v2, v28
	v_mul_f32_e32 v29, v3, v29
	v_mul_f32_e32 v30, v4, v30
	v_mul_f32_e32 v31, v5, v31
	v_mul_f32_e32 v32, v6, v32
	v_mul_f32_e32 v34, v7, v34
	v_add_f32_dpp v35, v35, v35 quad_perm:[2,3,0,1] row_mask:0xf bank_mask:0xf bound_ctrl:1
	ds_write_b32 v174, v35
	v_add_u32_e32 v174, v174, v161
	v_fmac_f32_e32 v26, v8, v33
	v_fmac_f32_e32 v27, v9, v33
	v_fmac_f32_e32 v28, v10, v33
	v_fmac_f32_e32 v29, v11, v33
	v_fmac_f32_e32 v30, v12, v33
	v_fmac_f32_e32 v31, v13, v33
	v_fmac_f32_e32 v32, v14, v33
	v_fmac_f32_e32 v34, v15, v33
	v_mul_f32_e32 v40, v16, v26
	v_mul_f32_e32 v41, v17, v27
	v_fmac_f32_e32 v40, v18, v28
	v_fmac_f32_e32 v41, v19, v29
	v_fmac_f32_e32 v40, v20, v30
	v_fmac_f32_e32 v41, v21, v31
	v_fmac_f32_e32 v40, v22, v32
	v_fmac_f32_e32 v41, v23, v34
	v_add_f32_e32 v35, v40, v41
	s_nop 1
	v_add_f32_dpp v35, v35, v35 quad_perm:[1,0,3,2] row_mask:0xf bank_mask:0xf bound_ctrl:1
	ds_read_b128 v[0:3], v173 offset:23040
	ds_read_b128 v[4:7], v173 offset:23056
	ds_read_b128 v[8:11], v173 offset:14848
	ds_read_b128 v[12:15], v173 offset:14864
	ds_read_b32 v33, v172 offset:37888
	ds_read_b128 v[16:19], v173 offset:6656
	ds_read_b128 v[20:23], v173 offset:6672
	s_waitcnt lgkmcnt(8)
	v_mul_f32_e32 v26, v176, v26
	v_mul_f32_e32 v27, v177, v27
	v_mul_f32_e32 v28, v178, v28
	v_mul_f32_e32 v29, v179, v29
	v_mul_f32_e32 v30, v180, v30
	v_mul_f32_e32 v31, v181, v31
	v_mul_f32_e32 v32, v182, v32
	v_mul_f32_e32 v34, v183, v34
	v_add_f32_dpp v35, v35, v35 quad_perm:[2,3,0,1] row_mask:0xf bank_mask:0xf bound_ctrl:1
	ds_write_b32 v174, v35
	v_add_u32_e32 v174, v174, v161
	v_fmac_f32_e32 v26, v184, v200
	v_fmac_f32_e32 v27, v185, v200
	v_fmac_f32_e32 v28, v186, v200
	v_fmac_f32_e32 v29, v187, v200
	v_fmac_f32_e32 v30, v188, v200
	v_fmac_f32_e32 v31, v189, v200
	v_fmac_f32_e32 v32, v190, v200
	v_fmac_f32_e32 v34, v191, v200
	v_mul_f32_e32 v40, v192, v26
	v_mul_f32_e32 v41, v193, v27
	v_fmac_f32_e32 v40, v194, v28
	v_fmac_f32_e32 v41, v195, v29
	v_fmac_f32_e32 v40, v196, v30
	v_fmac_f32_e32 v41, v197, v31
	v_fmac_f32_e32 v40, v198, v32
	v_fmac_f32_e32 v41, v199, v34
	v_add_f32_e32 v35, v40, v41
	s_nop 1
	v_add_f32_dpp v35, v35, v35 quad_perm:[1,0,3,2] row_mask:0xf bank_mask:0xf bound_ctrl:1
	ds_read_b128 v[176:179], v173 offset:23168
	ds_read_b128 v[180:183], v173 offset:23184
	ds_read_b128 v[184:187], v173 offset:14976
	ds_read_b128 v[188:191], v173 offset:14992
	ds_read_b32 v200, v172 offset:38144
	ds_read_b128 v[192:195], v173 offset:6784
	ds_read_b128 v[196:199], v173 offset:6800
	s_waitcnt lgkmcnt(8)
; #define GLA_LD(t_, aq, kq, qq, vq) do { const int tt_ = (t_); vq = Bs[6144 + tt_ * 64 + pp]; \
;             _Pragma("unroll") for (int u = 0; u < 2; ++u) { aq[u] = *(const LAS f32x4*)(Bs + 4096 + tt_ * 32 + k0 + 4 * u); kq[u] = *(const LAS f32x4*)(Bs + 2048 + tt_ * 32 + k0 + 4 * u); qq[u] = *(const LAS f32x4*)(Bs + tt_ * 32 + k0 + 4 * u); } } while (0)
; #define GLA_STEP(t_, aq, kq, qq, vq) do { float y = 0.f; \
;             _Pragma("unroll") for (int u = 0; u < 2; ++u) _Pragma("unroll") for (int j = 0; j < 4; ++j) { S[4 * u + j] = aq[u][j] * S[4 * u + j] + kq[u][j] * vq; y += qq[u][j] * S[4 * u + j]; } \
;             y += dpp_f(y, 0xB1); y += dpp_f(y, 0x4E); ydst[(t_) * ystride] = y; } while (0)
; __device__ __forceinline__ void gla_job(const bf16_t* P, bf16_t* Y, int l, int b, int h, LAS float* lds, int wave_s) {
;     ...
;             GLA_LD(0, a0_, k0_, q0_, v0_);
;             for (int t = 0; t < TC; t += 2) {
;                 GLA_LD(t + 1, a1_, k1_, q1_, v1_);
;                 GLA_STEP(t, a0_, k0_, q0_, v0_);
;                 GLA_LD(t + 2 < TC ? t + 2 : t + 1, a0_, k0_, q0_, v0_);
;                 GLA_STEP(t + 1, a1_, k1_, q1_, v1_);
	v_mul_f32_e32 v26, v0, v26
	v_mul_f32_e32 v27, v1, v27
	v_mul_f32_e32 v28, v2, v28
	v_mul_f32_e32 v29, v3, v29
	v_mul_f32_e32 v30, v4, v30
	v_mul_f32_e32 v31, v5, v31
	v_mul_f32_e32 v32, v6, v32
	v_mul_f32_e32 v34, v7, v34
	v_add_f32_dpp v35, v35, v35 quad_perm:[2,3,0,1] row_mask:0xf bank_mask:0xf bound_ctrl:1
	ds_write_b32 v174, v35
	v_add_u32_e32 v174, v174, v161
	v_fmac_f32_e32 v26, v8, v33
	v_fmac_f32_e32 v27, v9, v33
	v_fmac_f32_e32 v28, v10, v33
	v_fmac_f32_e32 v29, v11, v33
	v_fmac_f32_e32 v30, v12, v33
	v_fmac_f32_e32 v31, v13, v33
	v_fmac_f32_e32 v32, v14, v33
	v_fmac_f32_e32 v34, v15, v33
	v_mul_f32_e32 v40, v16, v26
	v_mul_f32_e32 v41, v17, v27
	v_fmac_f32_e32 v40, v18, v28
	v_fmac_f32_e32 v41, v19, v29
	v_fmac_f32_e32 v40, v20, v30
	v_fmac_f32_e32 v41, v21, v31
	v_fmac_f32_e32 v40, v22, v32
	v_fmac_f32_e32 v41, v23, v34
	v_add_f32_e32 v35, v40, v41
	s_nop 1
	v_add_f32_dpp v35, v35, v35 quad_perm:[1,0,3,2] row_mask:0xf bank_mask:0xf bound_ctrl:1
	ds_read_b128 v[0:3], v173 offset:23296
	ds_read_b128 v[4:7], v173 offset:23312
	ds_read_b128 v[8:11], v173 offset:15104
	ds_read_b128 v[12:15], v173 offset:15120
	ds_read_b32 v33, v172 offset:38400
	ds_read_b128 v[16:19], v173 offset:6912
	ds_read_b128 v[20:23], v173 offset:6928
	s_waitcnt lgkmcnt(8)
	v_mul_f32_e32 v26, v176, v26
	v_mul_f32_e32 v27, v177, v27
	v_mul_f32_e32 v28, v178, v28
	v_mul_f32_e32 v29, v179, v29
	v_mul_f32_e32 v30, v180, v30
	v_mul_f32_e32 v31, v181, v31
	v_mul_f32_e32 v32, v182, v32
	v_mul_f32_e32 v34, v183, v34
	v_add_f32_dpp v35, v35, v35 quad_perm:[2,3,0,1] row_mask:0xf bank_mask:0xf bound_ctrl:1
	ds_write_b32 v174, v35
	v_add_u32_e32 v174, v174, v161
	v_fmac_f32_e32 v26, v184, v200
	v_fmac_f32_e32 v27, v185, v200
	v_fmac_f32_e32 v28, v186, v200
	v_fmac_f32_e32 v29, v187, v200
	v_fmac_f32_e32 v30, v188, v200
	v_fmac_f32_e32 v31, v189, v200
	v_fmac_f32_e32 v32, v190, v200
	v_fmac_f32_e32 v34, v191, v200
	v_mul_f32_e32 v40, v192, v26
	v_mul_f32_e32 v41, v193, v27
	v_fmac_f32_e32 v40, v194, v28
	v_fmac_f32_e32 v41, v195, v29
	v_fmac_f32_e32 v40, v196, v30
	v_fmac_f32_e32 v41, v197, v31
	v_fmac_f32_e32 v40, v198, v32
	v_fmac_f32_e32 v41, v199, v34
	v_add_f32_e32 v35, v40, v41
	s_nop 1
	v_add_f32_dpp v35, v35, v35 quad_perm:[1,0,3,2] row_mask:0xf bank_mask:0xf bound_ctrl:1
	ds_read_b128 v[176:179], v173 offset:23424
	ds_read_b128 v[180:183], v173 offset:23440
	ds_read_b128 v[184:187], v173 offset:15232
	ds_read_b128 v[188:191], v173 offset:15248
	ds_read_b32 v200, v172 offset:38656
	ds_read_b128 v[192:195], v173 offset:7040
	ds_read_b128 v[196:199], v173 offset:7056
	s_waitcnt lgkmcnt(8)
	v_mul_f32_e32 v26, v0, v26
	v_mul_f32_e32 v27, v1, v27
	v_mul_f32_e32 v28, v2, v28
	v_mul_f32_e32 v29, v3, v29
	v_mul_f32_e32 v30, v4, v30
	v_mul_f32_e32 v31, v5, v31
	v_mul_f32_e32 v32, v6, v32
	v_mul_f32_e32 v34, v7, v34
	v_add_f32_dpp v35, v35, v35 quad_perm:[2,3,0,1] row_mask:0xf bank_mask:0xf bound_ctrl:1
	ds_write_b32 v174, v35
	v_add_u32_e32 v174, v174, v161
	v_fmac_f32_e32 v26, v8, v33
	v_fmac_f32_e32 v27, v9, v33
	v_fmac_f32_e32 v28, v10, v33
	v_fmac_f32_e32 v29, v11, v33
	v_fmac_f32_e32 v30, v12, v33
	v_fmac_f32_e32 v31, v13, v33
	v_fmac_f32_e32 v32, v14, v33
	v_fmac_f32_e32 v34, v15, v33
	v_mul_f32_e32 v40, v16, v26
	v_mul_f32_e32 v41, v17, v27
	v_fmac_f32_e32 v40, v18, v28
	v_fmac_f32_e32 v41, v19, v29
	v_fmac_f32_e32 v40, v20, v30
	v_fmac_f32_e32 v41, v21, v31
	v_fmac_f32_e32 v40, v22, v32
	v_fmac_f32_e32 v41, v23, v34
	v_add_f32_e32 v35, v40, v41
	s_nop 1
	v_add_f32_dpp v35, v35, v35 quad_perm:[1,0,3,2] row_mask:0xf bank_mask:0xf bound_ctrl:1
	ds_read_b128 v[0:3], v173 offset:23552
	ds_read_b128 v[4:7], v173 offset:23568
	ds_read_b128 v[8:11], v173 offset:15360
	ds_read_b128 v[12:15], v173 offset:15376
	ds_read_b32 v33, v172 offset:38912
	ds_read_b128 v[16:19], v173 offset:7168
	ds_read_b128 v[20:23], v173 offset:7184
	s_waitcnt lgkmcnt(8)
	v_mul_f32_e32 v26, v176, v26
	v_mul_f32_e32 v27, v177, v27
	v_mul_f32_e32 v28, v178, v28
	v_mul_f32_e32 v29, v179, v29
	v_mul_f32_e32 v30, v180, v30
	v_mul_f32_e32 v31, v181, v31
	v_mul_f32_e32 v32, v182, v32
	v_mul_f32_e32 v34, v183, v34
	v_add_f32_dpp v35, v35, v35 quad_perm:[2,3,0,1] row_mask:0xf bank_mask:0xf bound_ctrl:1
	ds_write_b32 v174, v35
	v_add_u32_e32 v174, v174, v161
	v_fmac_f32_e32 v26, v184, v200
	v_fmac_f32_e32 v27, v185, v200
	v_fmac_f32_e32 v28, v186, v200
	v_fmac_f32_e32 v29, v187, v200
	v_fmac_f32_e32 v30, v188, v200
	v_fmac_f32_e32 v31, v189, v200
	v_fmac_f32_e32 v32, v190, v200
	v_fmac_f32_e32 v34, v191, v200
	v_mul_f32_e32 v40, v192, v26
	v_mul_f32_e32 v41, v193, v27
	v_fmac_f32_e32 v40, v194, v28
	v_fmac_f32_e32 v41, v195, v29
	v_fmac_f32_e32 v40, v196, v30
	v_fmac_f32_e32 v41, v197, v31
	v_fmac_f32_e32 v40, v198, v32
	v_fmac_f32_e32 v41, v199, v34
	v_add_f32_e32 v35, v40, v41
	s_nop 1
	v_add_f32_dpp v35, v35, v35 quad_perm:[1,0,3,2] row_mask:0xf bank_mask:0xf bound_ctrl:1
	ds_read_b128 v[176:179], v173 offset:23680
	ds_read_b128 v[180:183], v173 offset:23696
	ds_read_b128 v[184:187], v173 offset:15488
	ds_read_b128 v[188:191], v173 offset:15504
	ds_read_b32 v200, v172 offset:39168
	ds_read_b128 v[192:195], v173 offset:7296
	ds_read_b128 v[196:199], v173 offset:7312
	s_waitcnt lgkmcnt(8)
; #define GLA_LD(t_, aq, kq, qq, vq) do { const int tt_ = (t_); vq = Bs[6144 + tt_ * 64 + pp]; \
;             _Pragma("unroll") for (int u = 0; u < 2; ++u) { aq[u] = *(const LAS f32x4*)(Bs + 4096 + tt_ * 32 + k0 + 4 * u); kq[u] = *(const LAS f32x4*)(Bs + 2048 + tt_ * 32 + k0 + 4 * u); qq[u] = *(const LAS f32x4*)(Bs + tt_ * 32 + k0 + 4 * u); } } while (0)
; #define GLA_STEP(t_, aq, kq, qq, vq) do { float y = 0.f; \
;             _Pragma("unroll") for (int u = 0; u < 2; ++u) _Pragma("unroll") for (int j = 0; j < 4; ++j) { S[4 * u + j] = aq[u][j] * S[4 * u + j] + kq[u][j] * vq; y += qq[u][j] * S[4 * u + j]; } \
;             y += dpp_f(y, 0xB1); y += dpp_f(y, 0x4E); ydst[(t_) * ystride] = y; } while (0)
; __device__ __forceinline__ void gla_job(const bf16_t* P, bf16_t* Y, int l, int b, int h, LAS float* lds, int wave_s) {
;     ...
;             GLA_LD(0, a0_, k0_, q0_, v0_);
;             for (int t = 0; t < TC; t += 2) {
;                 GLA_LD(t + 1, a1_, k1_, q1_, v1_);
;                 GLA_STEP(t, a0_, k0_, q0_, v0_);
;                 GLA_LD(t + 2 < TC ? t + 2 : t + 1, a0_, k0_, q0_, v0_);
;                 GLA_STEP(t + 1, a1_, k1_, q1_, v1_);
	v_mul_f32_e32 v26, v0, v26
	v_mul_f32_e32 v27, v1, v27
	v_mul_f32_e32 v28, v2, v28
	v_mul_f32_e32 v29, v3, v29
	v_mul_f32_e32 v30, v4, v30
	v_mul_f32_e32 v31, v5, v31
	v_mul_f32_e32 v32, v6, v32
	v_mul_f32_e32 v34, v7, v34
	v_add_f32_dpp v35, v35, v35 quad_perm:[2,3,0,1] row_mask:0xf bank_mask:0xf bound_ctrl:1
	ds_write_b32 v174, v35
	v_add_u32_e32 v174, v174, v161
	v_fmac_f32_e32 v26, v8, v33
	v_fmac_f32_e32 v27, v9, v33
	v_fmac_f32_e32 v28, v10, v33
	v_fmac_f32_e32 v29, v11, v33
	v_fmac_f32_e32 v30, v12, v33
	v_fmac_f32_e32 v31, v13, v33
	v_fmac_f32_e32 v32, v14, v33
	v_fmac_f32_e32 v34, v15, v33
	v_mul_f32_e32 v40, v16, v26
	v_mul_f32_e32 v41, v17, v27
	v_fmac_f32_e32 v40, v18, v28
	v_fmac_f32_e32 v41, v19, v29
	v_fmac_f32_e32 v40, v20, v30
	v_fmac_f32_e32 v41, v21, v31
	v_fmac_f32_e32 v40, v22, v32
	v_fmac_f32_e32 v41, v23, v34
	v_add_f32_e32 v35, v40, v41
	s_nop 1
	v_add_f32_dpp v35, v35, v35 quad_perm:[1,0,3,2] row_mask:0xf bank_mask:0xf bound_ctrl:1
	ds_read_b128 v[0:3], v173 offset:23808
	ds_read_b128 v[4:7], v173 offset:23824
	ds_read_b128 v[8:11], v173 offset:15616
	ds_read_b128 v[12:15], v173 offset:15632
	ds_read_b32 v33, v172 offset:39424
	ds_read_b128 v[16:19], v173 offset:7424
	ds_read_b128 v[20:23], v173 offset:7440
	s_waitcnt lgkmcnt(8)
	v_mul_f32_e32 v26, v176, v26
	v_mul_f32_e32 v27, v177, v27
	v_mul_f32_e32 v28, v178, v28
	v_mul_f32_e32 v29, v179, v29
	v_mul_f32_e32 v30, v180, v30
	v_mul_f32_e32 v31, v181, v31
	v_mul_f32_e32 v32, v182, v32
	v_mul_f32_e32 v34, v183, v34
	v_add_f32_dpp v35, v35, v35 quad_perm:[2,3,0,1] row_mask:0xf bank_mask:0xf bound_ctrl:1
	ds_write_b32 v174, v35
	v_add_u32_e32 v174, v174, v161
	v_fmac_f32_e32 v26, v184, v200
	v_fmac_f32_e32 v27, v185, v200
	v_fmac_f32_e32 v28, v186, v200
	v_fmac_f32_e32 v29, v187, v200
	v_fmac_f32_e32 v30, v188, v200
	v_fmac_f32_e32 v31, v189, v200
	v_fmac_f32_e32 v32, v190, v200
	v_fmac_f32_e32 v34, v191, v200
	v_mul_f32_e32 v40, v192, v26
	v_mul_f32_e32 v41, v193, v27
	v_fmac_f32_e32 v40, v194, v28
	v_fmac_f32_e32 v41, v195, v29
	v_fmac_f32_e32 v40, v196, v30
	v_fmac_f32_e32 v41, v197, v31
	v_fmac_f32_e32 v40, v198, v32
	v_fmac_f32_e32 v41, v199, v34
	v_add_f32_e32 v35, v40, v41
	s_nop 1
	v_add_f32_dpp v35, v35, v35 quad_perm:[1,0,3,2] row_mask:0xf bank_mask:0xf bound_ctrl:1
	ds_read_b128 v[176:179], v173 offset:23936
	ds_read_b128 v[180:183], v173 offset:23952
	ds_read_b128 v[184:187], v173 offset:15744
	ds_read_b128 v[188:191], v173 offset:15760
	ds_read_b32 v200, v172 offset:39680
	ds_read_b128 v[192:195], v173 offset:7552
	ds_read_b128 v[196:199], v173 offset:7568
	s_waitcnt lgkmcnt(8)
	v_mul_f32_e32 v26, v0, v26
	v_mul_f32_e32 v27, v1, v27
	v_mul_f32_e32 v28, v2, v28
	v_mul_f32_e32 v29, v3, v29
	v_mul_f32_e32 v30, v4, v30
	v_mul_f32_e32 v31, v5, v31
	v_mul_f32_e32 v32, v6, v32
	v_mul_f32_e32 v34, v7, v34
	v_add_f32_dpp v35, v35, v35 quad_perm:[2,3,0,1] row_mask:0xf bank_mask:0xf bound_ctrl:1
	ds_write_b32 v174, v35
	v_add_u32_e32 v174, v174, v161
	v_fmac_f32_e32 v26, v8, v33
	v_fmac_f32_e32 v27, v9, v33
	v_fmac_f32_e32 v28, v10, v33
	v_fmac_f32_e32 v29, v11, v33
	v_fmac_f32_e32 v30, v12, v33
	v_fmac_f32_e32 v31, v13, v33
	v_fmac_f32_e32 v32, v14, v33
	v_fmac_f32_e32 v34, v15, v33
	v_mul_f32_e32 v40, v16, v26
	v_mul_f32_e32 v41, v17, v27
	v_fmac_f32_e32 v40, v18, v28
	v_fmac_f32_e32 v41, v19, v29
	v_fmac_f32_e32 v40, v20, v30
	v_fmac_f32_e32 v41, v21, v31
	v_fmac_f32_e32 v40, v22, v32
	v_fmac_f32_e32 v41, v23, v34
	v_add_f32_e32 v35, v40, v41
	s_nop 1
	v_add_f32_dpp v35, v35, v35 quad_perm:[1,0,3,2] row_mask:0xf bank_mask:0xf bound_ctrl:1
	ds_read_b128 v[0:3], v173 offset:24064
	ds_read_b128 v[4:7], v173 offset:24080
	ds_read_b128 v[8:11], v173 offset:15872
	ds_read_b128 v[12:15], v173 offset:15888
	ds_read_b32 v33, v172 offset:39936
	ds_read_b128 v[16:19], v173 offset:7680
	ds_read_b128 v[20:23], v173 offset:7696
	s_waitcnt lgkmcnt(8)
	v_mul_f32_e32 v26, v176, v26
	v_mul_f32_e32 v27, v177, v27
	v_mul_f32_e32 v28, v178, v28
	v_mul_f32_e32 v29, v179, v29
	v_mul_f32_e32 v30, v180, v30
	v_mul_f32_e32 v31, v181, v31
	v_mul_f32_e32 v32, v182, v32
	v_mul_f32_e32 v34, v183, v34
	v_add_f32_dpp v35, v35, v35 quad_perm:[2,3,0,1] row_mask:0xf bank_mask:0xf bound_ctrl:1
	ds_write_b32 v174, v35
	v_add_u32_e32 v174, v174, v161
	v_fmac_f32_e32 v26, v184, v200
	v_fmac_f32_e32 v27, v185, v200
	v_fmac_f32_e32 v28, v186, v200
	v_fmac_f32_e32 v29, v187, v200
	v_fmac_f32_e32 v30, v188, v200
	v_fmac_f32_e32 v31, v189, v200
	v_fmac_f32_e32 v32, v190, v200
	v_fmac_f32_e32 v34, v191, v200
	v_mul_f32_e32 v40, v192, v26
	v_mul_f32_e32 v41, v193, v27
	v_fmac_f32_e32 v40, v194, v28
	v_fmac_f32_e32 v41, v195, v29
	v_fmac_f32_e32 v40, v196, v30
	v_fmac_f32_e32 v41, v197, v31
	v_fmac_f32_e32 v40, v198, v32
	v_fmac_f32_e32 v41, v199, v34
	v_add_f32_e32 v35, v40, v41
	s_nop 1
	v_add_f32_dpp v35, v35, v35 quad_perm:[1,0,3,2] row_mask:0xf bank_mask:0xf bound_ctrl:1
	ds_read_b128 v[176:179], v173 offset:24192
	ds_read_b128 v[180:183], v173 offset:24208
	ds_read_b128 v[184:187], v173 offset:16000
	ds_read_b128 v[188:191], v173 offset:16016
	ds_read_b32 v200, v172 offset:40192
	ds_read_b128 v[192:195], v173 offset:7808
	ds_read_b128 v[196:199], v173 offset:7824
	s_waitcnt lgkmcnt(8)
; #define GLA_LD(t_, aq, kq, qq, vq) do { const int tt_ = (t_); vq = Bs[6144 + tt_ * 64 + pp]; \
;             _Pragma("unroll") for (int u = 0; u < 2; ++u) { aq[u] = *(const LAS f32x4*)(Bs + 4096 + tt_ * 32 + k0 + 4 * u); kq[u] = *(const LAS f32x4*)(Bs + 2048 + tt_ * 32 + k0 + 4 * u); qq[u] = *(const LAS f32x4*)(Bs + tt_ * 32 + k0 + 4 * u); } } while (0)
; #define GLA_STEP(t_, aq, kq, qq, vq) do { float y = 0.f; \
;             _Pragma("unroll") for (int u = 0; u < 2; ++u) _Pragma("unroll") for (int j = 0; j < 4; ++j) { S[4 * u + j] = aq[u][j] * S[4 * u + j] + kq[u][j] * vq; y += qq[u][j] * S[4 * u + j]; } \
;             y += dpp_f(y, 0xB1); y += dpp_f(y, 0x4E); ydst[(t_) * ystride] = y; } while (0)
; __device__ __forceinline__ void gla_job(const bf16_t* P, bf16_t* Y, int l, int b, int h, LAS float* lds, int wave_s) {
;     ...
;             GLA_LD(0, a0_, k0_, q0_, v0_);
;             for (int t = 0; t < TC; t += 2) {
;                 GLA_LD(t + 1, a1_, k1_, q1_, v1_);
;                 GLA_STEP(t, a0_, k0_, q0_, v0_);
;                 GLA_LD(t + 2 < TC ? t + 2 : t + 1, a0_, k0_, q0_, v0_);
;                 GLA_STEP(t + 1, a1_, k1_, q1_, v1_);
;             }
	v_mul_f32_e32 v26, v0, v26
	v_mul_f32_e32 v27, v1, v27
	v_mul_f32_e32 v28, v2, v28
	v_mul_f32_e32 v29, v3, v29
	v_mul_f32_e32 v30, v4, v30
	v_mul_f32_e32 v31, v5, v31
	v_mul_f32_e32 v32, v6, v32
	v_mul_f32_e32 v34, v7, v34
	v_add_f32_dpp v35, v35, v35 quad_perm:[2,3,0,1] row_mask:0xf bank_mask:0xf bound_ctrl:1
	ds_write_b32 v174, v35
	v_add_u32_e32 v174, v174, v161
	v_fmac_f32_e32 v26, v8, v33
	v_fmac_f32_e32 v27, v9, v33
	v_fmac_f32_e32 v28, v10, v33
	v_fmac_f32_e32 v29, v11, v33
	v_fmac_f32_e32 v30, v12, v33
	v_fmac_f32_e32 v31, v13, v33
	v_fmac_f32_e32 v32, v14, v33
	v_fmac_f32_e32 v34, v15, v33
	v_mul_f32_e32 v40, v16, v26
	v_mul_f32_e32 v41, v17, v27
	v_fmac_f32_e32 v40, v18, v28
	v_fmac_f32_e32 v41, v19, v29
	v_fmac_f32_e32 v40, v20, v30
	v_fmac_f32_e32 v41, v21, v31
	v_fmac_f32_e32 v40, v22, v32
	v_fmac_f32_e32 v41, v23, v34
	v_add_f32_e32 v35, v40, v41
	s_nop 1
	v_add_f32_dpp v35, v35, v35 quad_perm:[1,0,3,2] row_mask:0xf bank_mask:0xf bound_ctrl:1
	ds_read_b128 v[0:3], v173 offset:24320
	ds_read_b128 v[4:7], v173 offset:24336
	ds_read_b128 v[8:11], v173 offset:16128
	ds_read_b128 v[12:15], v173 offset:16144
	ds_read_b32 v33, v172 offset:40448
	ds_read_b128 v[16:19], v173 offset:7936
	ds_read_b128 v[20:23], v173 offset:7952
	s_waitcnt lgkmcnt(8)
	v_mul_f32_e32 v26, v176, v26
	v_mul_f32_e32 v27, v177, v27
	v_mul_f32_e32 v28, v178, v28
	v_mul_f32_e32 v29, v179, v29
	v_mul_f32_e32 v30, v180, v30
	v_mul_f32_e32 v31, v181, v31
	v_mul_f32_e32 v32, v182, v32
	v_mul_f32_e32 v34, v183, v34
	v_add_f32_dpp v35, v35, v35 quad_perm:[2,3,0,1] row_mask:0xf bank_mask:0xf bound_ctrl:1
	ds_write_b32 v174, v35
	v_add_u32_e32 v174, v174, v161
	v_fmac_f32_e32 v26, v184, v200
	v_fmac_f32_e32 v27, v185, v200
	v_fmac_f32_e32 v28, v186, v200
	v_fmac_f32_e32 v29, v187, v200
	v_fmac_f32_e32 v30, v188, v200
	v_fmac_f32_e32 v31, v189, v200
	v_fmac_f32_e32 v32, v190, v200
	v_fmac_f32_e32 v34, v191, v200
	v_mul_f32_e32 v40, v192, v26
	v_mul_f32_e32 v41, v193, v27
	v_fmac_f32_e32 v40, v194, v28
	v_fmac_f32_e32 v41, v195, v29
	v_fmac_f32_e32 v40, v196, v30
	v_fmac_f32_e32 v41, v197, v31
	v_fmac_f32_e32 v40, v198, v32
	v_fmac_f32_e32 v41, v199, v34
	v_add_f32_e32 v35, v40, v41
	s_nop 1
	v_add_f32_dpp v35, v35, v35 quad_perm:[1,0,3,2] row_mask:0xf bank_mask:0xf bound_ctrl:1
	ds_read_b128 v[176:179], v173 offset:24448
	ds_read_b128 v[180:183], v173 offset:24464
	ds_read_b128 v[184:187], v173 offset:16256
	ds_read_b128 v[188:191], v173 offset:16272
	ds_read_b32 v200, v172 offset:40704
	ds_read_b128 v[192:195], v173 offset:8064
	ds_read_b128 v[196:199], v173 offset:8080
	s_waitcnt lgkmcnt(8)
	v_mul_f32_e32 v26, v0, v26
	v_mul_f32_e32 v27, v1, v27
	v_mul_f32_e32 v28, v2, v28
	v_mul_f32_e32 v29, v3, v29
	v_mul_f32_e32 v30, v4, v30
	v_mul_f32_e32 v31, v5, v31
	v_mul_f32_e32 v32, v6, v32
	v_mul_f32_e32 v34, v7, v34
	v_add_f32_dpp v35, v35, v35 quad_perm:[2,3,0,1] row_mask:0xf bank_mask:0xf bound_ctrl:1
	ds_write_b32 v174, v35
	v_add_u32_e32 v174, v174, v161
	v_fmac_f32_e32 v26, v8, v33
	v_fmac_f32_e32 v27, v9, v33
	v_fmac_f32_e32 v28, v10, v33
	v_fmac_f32_e32 v29, v11, v33
	v_fmac_f32_e32 v30, v12, v33
	v_fmac_f32_e32 v31, v13, v33
	v_fmac_f32_e32 v32, v14, v33
	v_fmac_f32_e32 v34, v15, v33
	v_mul_f32_e32 v40, v16, v26
	v_mul_f32_e32 v41, v17, v27
	v_fmac_f32_e32 v40, v18, v28
	v_fmac_f32_e32 v41, v19, v29
	v_fmac_f32_e32 v40, v20, v30
	v_fmac_f32_e32 v41, v21, v31
	v_fmac_f32_e32 v40, v22, v32
	v_fmac_f32_e32 v41, v23, v34
	v_add_f32_e32 v35, v40, v41
	s_nop 1
	v_add_f32_dpp v35, v35, v35 quad_perm:[1,0,3,2] row_mask:0xf bank_mask:0xf bound_ctrl:1
	s_waitcnt lgkmcnt(1)
	v_mul_f32_e32 v26, v176, v26
	v_mul_f32_e32 v27, v177, v27
	v_mul_f32_e32 v28, v178, v28
	v_mul_f32_e32 v29, v179, v29
	v_mul_f32_e32 v30, v180, v30
	v_mul_f32_e32 v31, v181, v31
	v_mul_f32_e32 v32, v182, v32
	v_mul_f32_e32 v34, v183, v34
	v_add_f32_dpp v35, v35, v35 quad_perm:[2,3,0,1] row_mask:0xf bank_mask:0xf bound_ctrl:1
	ds_write_b32 v174, v35
	v_add_u32_e32 v174, v174, v161
	v_fmac_f32_e32 v26, v184, v200
	v_fmac_f32_e32 v27, v185, v200
	v_fmac_f32_e32 v28, v186, v200
	v_fmac_f32_e32 v29, v187, v200
	v_fmac_f32_e32 v30, v188, v200
	v_fmac_f32_e32 v31, v189, v200
	v_fmac_f32_e32 v32, v190, v200
	v_fmac_f32_e32 v34, v191, v200
	v_mul_f32_e32 v40, v192, v26
	v_mul_f32_e32 v41, v193, v27
	v_fmac_f32_e32 v40, v194, v28
	v_fmac_f32_e32 v41, v195, v29
	v_fmac_f32_e32 v40, v196, v30
	v_fmac_f32_e32 v41, v197, v31
	v_fmac_f32_e32 v40, v198, v32
	v_fmac_f32_e32 v41, v199, v34
	v_add_f32_e32 v35, v40, v41
	s_nop 1
	v_add_f32_dpp v35, v35, v35 quad_perm:[1,0,3,2] row_mask:0xf bank_mask:0xf bound_ctrl:1
	s_nop 1
	v_add_f32_dpp v35, v35, v35 quad_perm:[2,3,0,1] row_mask:0xf bank_mask:0xf bound_ctrl:1
	ds_write_b32 v174, v35
	s_setprio 0
	s_branch .LBB0_324

; #define LAS __attribute__((address_space(3)))
; #define GLA_LD(t_, aq, kq, qq, vq) do { const int tt_ = (t_); vq = Bs[6144 + tt_ * 64 + pp]; \
;             _Pragma("unroll") for (int u = 0; u < 2; ++u) { aq[u] = *(const LAS f32x4*)(Bs + 4096 + tt_ * 32 + k0 + 4 * u); kq[u] = *(const LAS f32x4*)(Bs + 2048 + tt_ * 32 + k0 + 4 * u); qq[u] = *(const LAS f32x4*)(Bs + tt_ * 32 + k0 + 4 * u); } } while (0)
; #define GLA_STEP(t_, aq, kq, qq, vq) do { float y = 0.f; \
;             _Pragma("unroll") for (int u = 0; u < 2; ++u) _Pragma("unroll") for (int j = 0; j < 4; ++j) { S[4 * u + j] = aq[u][j] * S[4 * u + j] + kq[u][j] * vq; y += qq[u][j] * S[4 * u + j]; } \
;             y += dpp_f(y, 0xB1); y += dpp_f(y, 0x4E); ydst[(t_) * ystride] = y; } while (0)
; __device__ __forceinline__ void gla_job(const bf16_t* P, bf16_t* Y, int l, int b, int h, LAS float* lds, int wave_s) {
;     ...
;             LAS float* ydst = (lane & 3) == 0 ? (Yl + (c & 1) * 4096 + pp) : (lds + (LDS_XB + 256) / 4 + lane); const int ystride = (lane & 3) == 0 ? 64 : 0;
;             f32x4 a0_[2], k0_[2], q0_[2], a1_[2], k1_[2], q1_[2]; float v0_, v1_;
;     ...
;             GLA_LD(0, a0_, k0_, q0_, v0_);
;             for (int t = 0; t < TC; t += 2) {
;                 GLA_LD(t + 1, a1_, k1_, q1_, v1_);
;                 GLA_STEP(t, a0_, k0_, q0_, v0_);
;                 GLA_LD(t + 2 < TC ? t + 2 : t + 1, a0_, k0_, q0_, v0_);
;                 GLA_STEP(t + 1, a1_, k1_, q1_, v1_);
.LBB0_1045:
	s_andn2_b64 vcc, exec, s[6:7]
	s_cbranch_vccnz .LBB0_1036
	s_waitcnt vmcnt(15)
	v_cndmask_b32_e64 v0, 0, 1, s[8:9]
	s_mov_b32 s6, 0xa000
	v_mul_lo_u32 v0, v0, s6
	v_lshl_add_u32 v174, v132, 2, s14
	v_add_u32_e32 v24, v164, v0
	v_add_u32_e32 v172, v165, v0
	v_lshl_add_u32 v35, s15, 14, v133
	v_lshl_add_u32 v173, v131, 2, s14
	v_cndmask_b32_e64 v175, v157, v35, s[4:5]
	s_setprio 3
	ds_read_b128 v[0:3], v174 offset:16384
	ds_read_b128 v[4:7], v174 offset:16400
	ds_read_b128 v[8:11], v174 offset:8192
	ds_read_b128 v[12:15], v174 offset:8208
	ds_read_b32 v33, v173 offset:24576
	ds_read_b128 v[16:19], v174
	ds_read_b128 v[20:23], v174 offset:16
	ds_read_b128 v[176:179], v174 offset:16512
	ds_read_b128 v[180:183], v174 offset:16528
	ds_read_b128 v[184:187], v174 offset:8320
	ds_read_b128 v[188:191], v174 offset:8336
	ds_read_b32 v200, v173 offset:24832
	ds_read_b128 v[192:195], v174 offset:128
	ds_read_b128 v[196:199], v174 offset:144
	s_waitcnt lgkmcnt(7)
	v_mul_f32_e32 v26, v0, v26
	v_mul_f32_e32 v27, v1, v27
	v_mul_f32_e32 v28, v2, v28
	v_mul_f32_e32 v29, v3, v29
	v_mul_f32_e32 v30, v4, v30
	v_mul_f32_e32 v31, v5, v31
	v_mul_f32_e32 v32, v6, v32
	v_mul_f32_e32 v34, v7, v34
	v_fmac_f32_e32 v26, v8, v33
	v_fmac_f32_e32 v27, v9, v33
	v_fmac_f32_e32 v28, v10, v33
	v_fmac_f32_e32 v29, v11, v33
	v_fmac_f32_e32 v30, v12, v33
	v_fmac_f32_e32 v31, v13, v33
	v_fmac_f32_e32 v32, v14, v33
	v_fmac_f32_e32 v34, v15, v33
	v_mul_f32_e32 v40, v16, v26
	v_mul_f32_e32 v41, v17, v27
	v_fmac_f32_e32 v40, v18, v28
	v_fmac_f32_e32 v41, v19, v29
	v_fmac_f32_e32 v40, v20, v30
	v_fmac_f32_e32 v41, v21, v31
	v_fmac_f32_e32 v40, v22, v32
	v_fmac_f32_e32 v41, v23, v34
	v_add_f32_e32 v35, v40, v41
	s_nop 1
	v_add_f32_dpp v35, v35, v35 quad_perm:[1,0,3,2] row_mask:0xf bank_mask:0xf bound_ctrl:1
	ds_read_b128 v[0:3], v174 offset:16640
	ds_read_b128 v[4:7], v174 offset:16656
	ds_read_b128 v[8:11], v174 offset:8448
	ds_read_b128 v[12:15], v174 offset:8464
	ds_read_b32 v33, v173 offset:25088
	ds_read_b128 v[16:19], v174 offset:256
	ds_read_b128 v[20:23], v174 offset:272
	s_waitcnt lgkmcnt(7)
	v_mul_f32_e32 v26, v176, v26
	v_mul_f32_e32 v27, v177, v27
	v_mul_f32_e32 v28, v178, v28
	v_mul_f32_e32 v29, v179, v29
	v_mul_f32_e32 v30, v180, v30
	v_mul_f32_e32 v31, v181, v31
	v_mul_f32_e32 v32, v182, v32
	v_mul_f32_e32 v34, v183, v34
	v_add_f32_dpp v35, v35, v35 quad_perm:[2,3,0,1] row_mask:0xf bank_mask:0xf bound_ctrl:1
	ds_write_b32 v175, v35
	v_add_u32_e32 v175, v175, v162
	v_fmac_f32_e32 v26, v184, v200
	v_fmac_f32_e32 v27, v185, v200
	v_fmac_f32_e32 v28, v186, v200
	v_fmac_f32_e32 v29, v187, v200
	v_fmac_f32_e32 v30, v188, v200
	v_fmac_f32_e32 v31, v189, v200
	v_fmac_f32_e32 v32, v190, v200
	v_fmac_f32_e32 v34, v191, v200
	v_mul_f32_e32 v40, v192, v26
	v_mul_f32_e32 v41, v193, v27
	v_fmac_f32_e32 v40, v194, v28
	v_fmac_f32_e32 v41, v195, v29
	v_fmac_f32_e32 v40, v196, v30
	v_fmac_f32_e32 v41, v197, v31
	v_fmac_f32_e32 v40, v198, v32
	v_fmac_f32_e32 v41, v199, v34
	v_add_f32_e32 v35, v40, v41
	s_nop 1
	v_add_f32_dpp v35, v35, v35 quad_perm:[1,0,3,2] row_mask:0xf bank_mask:0xf bound_ctrl:1
	ds_read_b128 v[176:179], v174 offset:16768
	ds_read_b128 v[180:183], v174 offset:16784
	ds_read_b128 v[184:187], v174 offset:8576
	ds_read_b128 v[188:191], v174 offset:8592
	ds_read_b32 v200, v173 offset:25344
	ds_read_b128 v[192:195], v174 offset:384
	ds_read_b128 v[196:199], v174 offset:400
	s_waitcnt lgkmcnt(8)
	v_mul_f32_e32 v26, v0, v26
	v_mul_f32_e32 v27, v1, v27
	v_mul_f32_e32 v28, v2, v28
	v_mul_f32_e32 v29, v3, v29
	v_mul_f32_e32 v30, v4, v30
	v_mul_f32_e32 v31, v5, v31
	v_mul_f32_e32 v32, v6, v32
	v_mul_f32_e32 v34, v7, v34
	v_add_f32_dpp v35, v35, v35 quad_perm:[2,3,0,1] row_mask:0xf bank_mask:0xf bound_ctrl:1
	ds_write_b32 v175, v35
	v_add_u32_e32 v175, v175, v162
	v_fmac_f32_e32 v26, v8, v33
	v_fmac_f32_e32 v27, v9, v33
	v_fmac_f32_e32 v28, v10, v33
	v_fmac_f32_e32 v29, v11, v33
	v_fmac_f32_e32 v30, v12, v33
	v_fmac_f32_e32 v31, v13, v33
	v_fmac_f32_e32 v32, v14, v33
	v_fmac_f32_e32 v34, v15, v33
	v_mul_f32_e32 v40, v16, v26
	v_mul_f32_e32 v41, v17, v27
	v_fmac_f32_e32 v40, v18, v28
	v_fmac_f32_e32 v41, v19, v29
	v_fmac_f32_e32 v40, v20, v30
	v_fmac_f32_e32 v41, v21, v31
	v_fmac_f32_e32 v40, v22, v32
	v_fmac_f32_e32 v41, v23, v34
	v_add_f32_e32 v35, v40, v41
	s_nop 1
	v_add_f32_dpp v35, v35, v35 quad_perm:[1,0,3,2] row_mask:0xf bank_mask:0xf bound_ctrl:1
	ds_read_b128 v[0:3], v174 offset:16896
	ds_read_b128 v[4:7], v174 offset:16912
	ds_read_b128 v[8:11], v174 offset:8704
	ds_read_b128 v[12:15], v174 offset:8720
	ds_read_b32 v33, v173 offset:25600
	ds_read_b128 v[16:19], v174 offset:512
	ds_read_b128 v[20:23], v174 offset:528
	s_waitcnt lgkmcnt(8)
	v_mul_f32_e32 v26, v176, v26
	v_mul_f32_e32 v27, v177, v27
	v_mul_f32_e32 v28, v178, v28
	v_mul_f32_e32 v29, v179, v29
	v_mul_f32_e32 v30, v180, v30
	v_mul_f32_e32 v31, v181, v31
	v_mul_f32_e32 v32, v182, v32
	v_mul_f32_e32 v34, v183, v34
	v_add_f32_dpp v35, v35, v35 quad_perm:[2,3,0,1] row_mask:0xf bank_mask:0xf bound_ctrl:1
	ds_write_b32 v175, v35
	v_add_u32_e32 v175, v175, v162
	v_fmac_f32_e32 v26, v184, v200
	v_fmac_f32_e32 v27, v185, v200
	v_fmac_f32_e32 v28, v186, v200
	v_fmac_f32_e32 v29, v187, v200
	v_fmac_f32_e32 v30, v188, v200
	v_fmac_f32_e32 v31, v189, v200
	v_fmac_f32_e32 v32, v190, v200
	v_fmac_f32_e32 v34, v191, v200
	v_mul_f32_e32 v40, v192, v26
	v_mul_f32_e32 v41, v193, v27
	v_fmac_f32_e32 v40, v194, v28
	v_fmac_f32_e32 v41, v195, v29
	v_fmac_f32_e32 v40, v196, v30
	v_fmac_f32_e32 v41, v197, v31
	v_fmac_f32_e32 v40, v198, v32
	v_fmac_f32_e32 v41, v199, v34
	v_add_f32_e32 v35, v40, v41
	s_nop 1
	v_add_f32_dpp v35, v35, v35 quad_perm:[1,0,3,2] row_mask:0xf bank_mask:0xf bound_ctrl:1
	ds_read_b128 v[176:179], v174 offset:17024
	ds_read_b128 v[180:183], v174 offset:17040
	ds_read_b128 v[184:187], v174 offset:8832
	ds_read_b128 v[188:191], v174 offset:8848
	ds_read_b32 v200, v173 offset:25856
	ds_read_b128 v[192:195], v174 offset:640
	ds_read_b128 v[196:199], v174 offset:656
	s_waitcnt lgkmcnt(8)
; #define GLA_LD(t_, aq, kq, qq, vq) do { const int tt_ = (t_); vq = Bs[6144 + tt_ * 64 + pp]; \
;             _Pragma("unroll") for (int u = 0; u < 2; ++u) { aq[u] = *(const LAS f32x4*)(Bs + 4096 + tt_ * 32 + k0 + 4 * u); kq[u] = *(const LAS f32x4*)(Bs + 2048 + tt_ * 32 + k0 + 4 * u); qq[u] = *(const LAS f32x4*)(Bs + tt_ * 32 + k0 + 4 * u); } } while (0)
; #define GLA_STEP(t_, aq, kq, qq, vq) do { float y = 0.f; \
;             _Pragma("unroll") for (int u = 0; u < 2; ++u) _Pragma("unroll") for (int j = 0; j < 4; ++j) { S[4 * u + j] = aq[u][j] * S[4 * u + j] + kq[u][j] * vq; y += qq[u][j] * S[4 * u + j]; } \
;             y += dpp_f(y, 0xB1); y += dpp_f(y, 0x4E); ydst[(t_) * ystride] = y; } while (0)
; __device__ __forceinline__ void gla_job(const bf16_t* P, bf16_t* Y, int l, int b, int h, LAS float* lds, int wave_s) {
;     ...
;             GLA_LD(0, a0_, k0_, q0_, v0_);
;             for (int t = 0; t < TC; t += 2) {
;                 GLA_LD(t + 1, a1_, k1_, q1_, v1_);
;                 GLA_STEP(t, a0_, k0_, q0_, v0_);
;                 GLA_LD(t + 2 < TC ? t + 2 : t + 1, a0_, k0_, q0_, v0_);
;                 GLA_STEP(t + 1, a1_, k1_, q1_, v1_);
	v_mul_f32_e32 v26, v0, v26
	v_mul_f32_e32 v27, v1, v27
	v_mul_f32_e32 v28, v2, v28
	v_mul_f32_e32 v29, v3, v29
	v_mul_f32_e32 v30, v4, v30
	v_mul_f32_e32 v31, v5, v31
	v_mul_f32_e32 v32, v6, v32
	v_mul_f32_e32 v34, v7, v34
	v_add_f32_dpp v35, v35, v35 quad_perm:[2,3,0,1] row_mask:0xf bank_mask:0xf bound_ctrl:1
	ds_write_b32 v175, v35
	v_add_u32_e32 v175, v175, v162
	v_fmac_f32_e32 v26, v8, v33
	v_fmac_f32_e32 v27, v9, v33
	v_fmac_f32_e32 v28, v10, v33
	v_fmac_f32_e32 v29, v11, v33
	v_fmac_f32_e32 v30, v12, v33
	v_fmac_f32_e32 v31, v13, v33
	v_fmac_f32_e32 v32, v14, v33
	v_fmac_f32_e32 v34, v15, v33
	v_mul_f32_e32 v40, v16, v26
	v_mul_f32_e32 v41, v17, v27
	v_fmac_f32_e32 v40, v18, v28
	v_fmac_f32_e32 v41, v19, v29
	v_fmac_f32_e32 v40, v20, v30
	v_fmac_f32_e32 v41, v21, v31
	v_fmac_f32_e32 v40, v22, v32
	v_fmac_f32_e32 v41, v23, v34
	v_add_f32_e32 v35, v40, v41
	s_nop 1
	v_add_f32_dpp v35, v35, v35 quad_perm:[1,0,3,2] row_mask:0xf bank_mask:0xf bound_ctrl:1
	ds_read_b128 v[0:3], v174 offset:17152
	ds_read_b128 v[4:7], v174 offset:17168
	ds_read_b128 v[8:11], v174 offset:8960
	ds_read_b128 v[12:15], v174 offset:8976
	ds_read_b32 v33, v173 offset:26112
	ds_read_b128 v[16:19], v174 offset:768
	ds_read_b128 v[20:23], v174 offset:784
	s_waitcnt lgkmcnt(8)
	v_mul_f32_e32 v26, v176, v26
	v_mul_f32_e32 v27, v177, v27
	v_mul_f32_e32 v28, v178, v28
	v_mul_f32_e32 v29, v179, v29
	v_mul_f32_e32 v30, v180, v30
	v_mul_f32_e32 v31, v181, v31
	v_mul_f32_e32 v32, v182, v32
	v_mul_f32_e32 v34, v183, v34
	v_add_f32_dpp v35, v35, v35 quad_perm:[2,3,0,1] row_mask:0xf bank_mask:0xf bound_ctrl:1
	ds_write_b32 v175, v35
	v_add_u32_e32 v175, v175, v162
	v_fmac_f32_e32 v26, v184, v200
	v_fmac_f32_e32 v27, v185, v200
	v_fmac_f32_e32 v28, v186, v200
	v_fmac_f32_e32 v29, v187, v200
	v_fmac_f32_e32 v30, v188, v200
	v_fmac_f32_e32 v31, v189, v200
	v_fmac_f32_e32 v32, v190, v200
	v_fmac_f32_e32 v34, v191, v200
	v_mul_f32_e32 v40, v192, v26
	v_mul_f32_e32 v41, v193, v27
	v_fmac_f32_e32 v40, v194, v28
	v_fmac_f32_e32 v41, v195, v29
	v_fmac_f32_e32 v40, v196, v30
	v_fmac_f32_e32 v41, v197, v31
	v_fmac_f32_e32 v40, v198, v32
	v_fmac_f32_e32 v41, v199, v34
	v_add_f32_e32 v35, v40, v41
	s_nop 1
	v_add_f32_dpp v35, v35, v35 quad_perm:[1,0,3,2] row_mask:0xf bank_mask:0xf bound_ctrl:1
	ds_read_b128 v[176:179], v174 offset:17280
	ds_read_b128 v[180:183], v174 offset:17296
	ds_read_b128 v[184:187], v174 offset:9088
	ds_read_b128 v[188:191], v174 offset:9104
	ds_read_b32 v200, v173 offset:26368
	ds_read_b128 v[192:195], v174 offset:896
	ds_read_b128 v[196:199], v174 offset:912
	s_waitcnt lgkmcnt(8)
	v_mul_f32_e32 v26, v0, v26
	v_mul_f32_e32 v27, v1, v27
	v_mul_f32_e32 v28, v2, v28
	v_mul_f32_e32 v29, v3, v29
	v_mul_f32_e32 v30, v4, v30
	v_mul_f32_e32 v31, v5, v31
	v_mul_f32_e32 v32, v6, v32
	v_mul_f32_e32 v34, v7, v34
	v_add_f32_dpp v35, v35, v35 quad_perm:[2,3,0,1] row_mask:0xf bank_mask:0xf bound_ctrl:1
	ds_write_b32 v175, v35
	v_add_u32_e32 v175, v175, v162
	v_fmac_f32_e32 v26, v8, v33
	v_fmac_f32_e32 v27, v9, v33
	v_fmac_f32_e32 v28, v10, v33
	v_fmac_f32_e32 v29, v11, v33
	v_fmac_f32_e32 v30, v12, v33
	v_fmac_f32_e32 v31, v13, v33
	v_fmac_f32_e32 v32, v14, v33
	v_fmac_f32_e32 v34, v15, v33
	v_mul_f32_e32 v40, v16, v26
	v_mul_f32_e32 v41, v17, v27
	v_fmac_f32_e32 v40, v18, v28
	v_fmac_f32_e32 v41, v19, v29
	v_fmac_f32_e32 v40, v20, v30
	v_fmac_f32_e32 v41, v21, v31
	v_fmac_f32_e32 v40, v22, v32
	v_fmac_f32_e32 v41, v23, v34
	v_add_f32_e32 v35, v40, v41
	s_nop 1
	v_add_f32_dpp v35, v35, v35 quad_perm:[1,0,3,2] row_mask:0xf bank_mask:0xf bound_ctrl:1
	ds_read_b128 v[0:3], v174 offset:17408
	ds_read_b128 v[4:7], v174 offset:17424
	ds_read_b128 v[8:11], v174 offset:9216
	ds_read_b128 v[12:15], v174 offset:9232
	ds_read_b32 v33, v173 offset:26624
	ds_read_b128 v[16:19], v174 offset:1024
	ds_read_b128 v[20:23], v174 offset:1040
	s_waitcnt lgkmcnt(8)
	v_mul_f32_e32 v26, v176, v26
	v_mul_f32_e32 v27, v177, v27
	v_mul_f32_e32 v28, v178, v28
	v_mul_f32_e32 v29, v179, v29
	v_mul_f32_e32 v30, v180, v30
	v_mul_f32_e32 v31, v181, v31
	v_mul_f32_e32 v32, v182, v32
	v_mul_f32_e32 v34, v183, v34
	v_add_f32_dpp v35, v35, v35 quad_perm:[2,3,0,1] row_mask:0xf bank_mask:0xf bound_ctrl:1
	ds_write_b32 v175, v35
	v_add_u32_e32 v175, v175, v162
	v_fmac_f32_e32 v26, v184, v200
	v_fmac_f32_e32 v27, v185, v200
	v_fmac_f32_e32 v28, v186, v200
	v_fmac_f32_e32 v29, v187, v200
	v_fmac_f32_e32 v30, v188, v200
	v_fmac_f32_e32 v31, v189, v200
	v_fmac_f32_e32 v32, v190, v200
	v_fmac_f32_e32 v34, v191, v200
	v_mul_f32_e32 v40, v192, v26
	v_mul_f32_e32 v41, v193, v27
	v_fmac_f32_e32 v40, v194, v28
	v_fmac_f32_e32 v41, v195, v29
	v_fmac_f32_e32 v40, v196, v30
	v_fmac_f32_e32 v41, v197, v31
	v_fmac_f32_e32 v40, v198, v32
	v_fmac_f32_e32 v41, v199, v34
	v_add_f32_e32 v35, v40, v41
	s_nop 1
	v_add_f32_dpp v35, v35, v35 quad_perm:[1,0,3,2] row_mask:0xf bank_mask:0xf bound_ctrl:1
	ds_read_b128 v[176:179], v174 offset:17536
	ds_read_b128 v[180:183], v174 offset:17552
	ds_read_b128 v[184:187], v174 offset:9344
	ds_read_b128 v[188:191], v174 offset:9360
	ds_read_b32 v200, v173 offset:26880
	ds_read_b128 v[192:195], v174 offset:1152
	ds_read_b128 v[196:199], v174 offset:1168
	s_waitcnt lgkmcnt(8)
; #define GLA_LD(t_, aq, kq, qq, vq) do { const int tt_ = (t_); vq = Bs[6144 + tt_ * 64 + pp]; \
;             _Pragma("unroll") for (int u = 0; u < 2; ++u) { aq[u] = *(const LAS f32x4*)(Bs + 4096 + tt_ * 32 + k0 + 4 * u); kq[u] = *(const LAS f32x4*)(Bs + 2048 + tt_ * 32 + k0 + 4 * u); qq[u] = *(const LAS f32x4*)(Bs + tt_ * 32 + k0 + 4 * u); } } while (0)
; #define GLA_STEP(t_, aq, kq, qq, vq) do { float y = 0.f; \
;             _Pragma("unroll") for (int u = 0; u < 2; ++u) _Pragma("unroll") for (int j = 0; j < 4; ++j) { S[4 * u + j] = aq[u][j] * S[4 * u + j] + kq[u][j] * vq; y += qq[u][j] * S[4 * u + j]; } \
;             y += dpp_f(y, 0xB1); y += dpp_f(y, 0x4E); ydst[(t_) * ystride] = y; } while (0)
; __device__ __forceinline__ void gla_job(const bf16_t* P, bf16_t* Y, int l, int b, int h, LAS float* lds, int wave_s) {
;     ...
;             GLA_LD(0, a0_, k0_, q0_, v0_);
;             for (int t = 0; t < TC; t += 2) {
;                 GLA_LD(t + 1, a1_, k1_, q1_, v1_);
;                 GLA_STEP(t, a0_, k0_, q0_, v0_);
;                 GLA_LD(t + 2 < TC ? t + 2 : t + 1, a0_, k0_, q0_, v0_);
;                 GLA_STEP(t + 1, a1_, k1_, q1_, v1_);
	v_mul_f32_e32 v26, v0, v26
	v_mul_f32_e32 v27, v1, v27
	v_mul_f32_e32 v28, v2, v28
	v_mul_f32_e32 v29, v3, v29
	v_mul_f32_e32 v30, v4, v30
	v_mul_f32_e32 v31, v5, v31
	v_mul_f32_e32 v32, v6, v32
	v_mul_f32_e32 v34, v7, v34
	v_add_f32_dpp v35, v35, v35 quad_perm:[2,3,0,1] row_mask:0xf bank_mask:0xf bound_ctrl:1
	ds_write_b32 v175, v35
	v_add_u32_e32 v175, v175, v162
	v_fmac_f32_e32 v26, v8, v33
	v_fmac_f32_e32 v27, v9, v33
	v_fmac_f32_e32 v28, v10, v33
	v_fmac_f32_e32 v29, v11, v33
	v_fmac_f32_e32 v30, v12, v33
	v_fmac_f32_e32 v31, v13, v33
	v_fmac_f32_e32 v32, v14, v33
	v_fmac_f32_e32 v34, v15, v33
	v_mul_f32_e32 v40, v16, v26
	v_mul_f32_e32 v41, v17, v27
	v_fmac_f32_e32 v40, v18, v28
	v_fmac_f32_e32 v41, v19, v29
	v_fmac_f32_e32 v40, v20, v30
	v_fmac_f32_e32 v41, v21, v31
	v_fmac_f32_e32 v40, v22, v32
	v_fmac_f32_e32 v41, v23, v34
	v_add_f32_e32 v35, v40, v41
	s_nop 1
	v_add_f32_dpp v35, v35, v35 quad_perm:[1,0,3,2] row_mask:0xf bank_mask:0xf bound_ctrl:1
	ds_read_b128 v[0:3], v174 offset:17664
	ds_read_b128 v[4:7], v174 offset:17680
	ds_read_b128 v[8:11], v174 offset:9472
	ds_read_b128 v[12:15], v174 offset:9488
	ds_read_b32 v33, v173 offset:27136
	ds_read_b128 v[16:19], v174 offset:1280
	ds_read_b128 v[20:23], v174 offset:1296
	s_waitcnt lgkmcnt(8)
	v_mul_f32_e32 v26, v176, v26
	v_mul_f32_e32 v27, v177, v27
	v_mul_f32_e32 v28, v178, v28
	v_mul_f32_e32 v29, v179, v29
	v_mul_f32_e32 v30, v180, v30
	v_mul_f32_e32 v31, v181, v31
	v_mul_f32_e32 v32, v182, v32
	v_mul_f32_e32 v34, v183, v34
	v_add_f32_dpp v35, v35, v35 quad_perm:[2,3,0,1] row_mask:0xf bank_mask:0xf bound_ctrl:1
	ds_write_b32 v175, v35
	v_add_u32_e32 v175, v175, v162
	v_fmac_f32_e32 v26, v184, v200
	v_fmac_f32_e32 v27, v185, v200
	v_fmac_f32_e32 v28, v186, v200
	v_fmac_f32_e32 v29, v187, v200
	v_fmac_f32_e32 v30, v188, v200
	v_fmac_f32_e32 v31, v189, v200
	v_fmac_f32_e32 v32, v190, v200
	v_fmac_f32_e32 v34, v191, v200
	v_mul_f32_e32 v40, v192, v26
	v_mul_f32_e32 v41, v193, v27
	v_fmac_f32_e32 v40, v194, v28
	v_fmac_f32_e32 v41, v195, v29
	v_fmac_f32_e32 v40, v196, v30
	v_fmac_f32_e32 v41, v197, v31
	v_fmac_f32_e32 v40, v198, v32
	v_fmac_f32_e32 v41, v199, v34
	v_add_f32_e32 v35, v40, v41
	s_nop 1
	v_add_f32_dpp v35, v35, v35 quad_perm:[1,0,3,2] row_mask:0xf bank_mask:0xf bound_ctrl:1
	ds_read_b128 v[176:179], v174 offset:17792
	ds_read_b128 v[180:183], v174 offset:17808
	ds_read_b128 v[184:187], v174 offset:9600
	ds_read_b128 v[188:191], v174 offset:9616
	ds_read_b32 v200, v173 offset:27392
	ds_read_b128 v[192:195], v174 offset:1408
	ds_read_b128 v[196:199], v174 offset:1424
	s_waitcnt lgkmcnt(8)
	v_mul_f32_e32 v26, v0, v26
	v_mul_f32_e32 v27, v1, v27
	v_mul_f32_e32 v28, v2, v28
	v_mul_f32_e32 v29, v3, v29
	v_mul_f32_e32 v30, v4, v30
	v_mul_f32_e32 v31, v5, v31
	v_mul_f32_e32 v32, v6, v32
	v_mul_f32_e32 v34, v7, v34
	v_add_f32_dpp v35, v35, v35 quad_perm:[2,3,0,1] row_mask:0xf bank_mask:0xf bound_ctrl:1
	ds_write_b32 v175, v35
	v_add_u32_e32 v175, v175, v162
	v_fmac_f32_e32 v26, v8, v33
	v_fmac_f32_e32 v27, v9, v33
	v_fmac_f32_e32 v28, v10, v33
	v_fmac_f32_e32 v29, v11, v33
	v_fmac_f32_e32 v30, v12, v33
	v_fmac_f32_e32 v31, v13, v33
	v_fmac_f32_e32 v32, v14, v33
	v_fmac_f32_e32 v34, v15, v33
	v_mul_f32_e32 v40, v16, v26
	v_mul_f32_e32 v41, v17, v27
	v_fmac_f32_e32 v40, v18, v28
	v_fmac_f32_e32 v41, v19, v29
	v_fmac_f32_e32 v40, v20, v30
	v_fmac_f32_e32 v41, v21, v31
	v_fmac_f32_e32 v40, v22, v32
	v_fmac_f32_e32 v41, v23, v34
	v_add_f32_e32 v35, v40, v41
	s_nop 1
	v_add_f32_dpp v35, v35, v35 quad_perm:[1,0,3,2] row_mask:0xf bank_mask:0xf bound_ctrl:1
	ds_read_b128 v[0:3], v174 offset:17920
	ds_read_b128 v[4:7], v174 offset:17936
	ds_read_b128 v[8:11], v174 offset:9728
	ds_read_b128 v[12:15], v174 offset:9744
	ds_read_b32 v33, v173 offset:27648
	ds_read_b128 v[16:19], v174 offset:1536
	ds_read_b128 v[20:23], v174 offset:1552
	s_waitcnt lgkmcnt(8)
	v_mul_f32_e32 v26, v176, v26
	v_mul_f32_e32 v27, v177, v27
	v_mul_f32_e32 v28, v178, v28
	v_mul_f32_e32 v29, v179, v29
	v_mul_f32_e32 v30, v180, v30
	v_mul_f32_e32 v31, v181, v31
	v_mul_f32_e32 v32, v182, v32
	v_mul_f32_e32 v34, v183, v34
	v_add_f32_dpp v35, v35, v35 quad_perm:[2,3,0,1] row_mask:0xf bank_mask:0xf bound_ctrl:1
	ds_write_b32 v175, v35
	v_add_u32_e32 v175, v175, v162
	v_fmac_f32_e32 v26, v184, v200
	v_fmac_f32_e32 v27, v185, v200
	v_fmac_f32_e32 v28, v186, v200
	v_fmac_f32_e32 v29, v187, v200
	v_fmac_f32_e32 v30, v188, v200
	v_fmac_f32_e32 v31, v189, v200
	v_fmac_f32_e32 v32, v190, v200
	v_fmac_f32_e32 v34, v191, v200
	v_mul_f32_e32 v40, v192, v26
	v_mul_f32_e32 v41, v193, v27
	v_fmac_f32_e32 v40, v194, v28
	v_fmac_f32_e32 v41, v195, v29
	v_fmac_f32_e32 v40, v196, v30
	v_fmac_f32_e32 v41, v197, v31
	v_fmac_f32_e32 v40, v198, v32
	v_fmac_f32_e32 v41, v199, v34
	v_add_f32_e32 v35, v40, v41
	s_nop 1
	v_add_f32_dpp v35, v35, v35 quad_perm:[1,0,3,2] row_mask:0xf bank_mask:0xf bound_ctrl:1
	ds_read_b128 v[176:179], v174 offset:18048
	ds_read_b128 v[180:183], v174 offset:18064
	ds_read_b128 v[184:187], v174 offset:9856
	ds_read_b128 v[188:191], v174 offset:9872
	ds_read_b32 v200, v173 offset:27904
	ds_read_b128 v[192:195], v174 offset:1664
	ds_read_b128 v[196:199], v174 offset:1680
	s_waitcnt lgkmcnt(8)
; #define GLA_LD(t_, aq, kq, qq, vq) do { const int tt_ = (t_); vq = Bs[6144 + tt_ * 64 + pp]; \
;             _Pragma("unroll") for (int u = 0; u < 2; ++u) { aq[u] = *(const LAS f32x4*)(Bs + 4096 + tt_ * 32 + k0 + 4 * u); kq[u] = *(const LAS f32x4*)(Bs + 2048 + tt_ * 32 + k0 + 4 * u); qq[u] = *(const LAS f32x4*)(Bs + tt_ * 32 + k0 + 4 * u); } } while (0)
; #define GLA_STEP(t_, aq, kq, qq, vq) do { float y = 0.f; \
;             _Pragma("unroll") for (int u = 0; u < 2; ++u) _Pragma("unroll") for (int j = 0; j < 4; ++j) { S[4 * u + j] = aq[u][j] * S[4 * u + j] + kq[u][j] * vq; y += qq[u][j] * S[4 * u + j]; } \
;             y += dpp_f(y, 0xB1); y += dpp_f(y, 0x4E); ydst[(t_) * ystride] = y; } while (0)
; __device__ __forceinline__ void gla_job(const bf16_t* P, bf16_t* Y, int l, int b, int h, LAS float* lds, int wave_s) {
;     ...
;             GLA_LD(0, a0_, k0_, q0_, v0_);
;             for (int t = 0; t < TC; t += 2) {
;                 GLA_LD(t + 1, a1_, k1_, q1_, v1_);
;                 GLA_STEP(t, a0_, k0_, q0_, v0_);
;                 GLA_LD(t + 2 < TC ? t + 2 : t + 1, a0_, k0_, q0_, v0_);
;                 GLA_STEP(t + 1, a1_, k1_, q1_, v1_);
	v_mul_f32_e32 v26, v0, v26
	v_mul_f32_e32 v27, v1, v27
	v_mul_f32_e32 v28, v2, v28
	v_mul_f32_e32 v29, v3, v29
	v_mul_f32_e32 v30, v4, v30
	v_mul_f32_e32 v31, v5, v31
	v_mul_f32_e32 v32, v6, v32
	v_mul_f32_e32 v34, v7, v34
	v_add_f32_dpp v35, v35, v35 quad_perm:[2,3,0,1] row_mask:0xf bank_mask:0xf bound_ctrl:1
	ds_write_b32 v175, v35
	v_add_u32_e32 v175, v175, v162
	v_fmac_f32_e32 v26, v8, v33
	v_fmac_f32_e32 v27, v9, v33
	v_fmac_f32_e32 v28, v10, v33
	v_fmac_f32_e32 v29, v11, v33
	v_fmac_f32_e32 v30, v12, v33
	v_fmac_f32_e32 v31, v13, v33
	v_fmac_f32_e32 v32, v14, v33
	v_fmac_f32_e32 v34, v15, v33
	v_mul_f32_e32 v40, v16, v26
	v_mul_f32_e32 v41, v17, v27
	v_fmac_f32_e32 v40, v18, v28
	v_fmac_f32_e32 v41, v19, v29
	v_fmac_f32_e32 v40, v20, v30
	v_fmac_f32_e32 v41, v21, v31
	v_fmac_f32_e32 v40, v22, v32
	v_fmac_f32_e32 v41, v23, v34
	v_add_f32_e32 v35, v40, v41
	s_nop 1
	v_add_f32_dpp v35, v35, v35 quad_perm:[1,0,3,2] row_mask:0xf bank_mask:0xf bound_ctrl:1
	ds_read_b128 v[0:3], v174 offset:18176
	ds_read_b128 v[4:7], v174 offset:18192
	ds_read_b128 v[8:11], v174 offset:9984
	ds_read_b128 v[12:15], v174 offset:10000
	ds_read_b32 v33, v173 offset:28160
	ds_read_b128 v[16:19], v174 offset:1792
	ds_read_b128 v[20:23], v174 offset:1808
	s_waitcnt lgkmcnt(8)
	v_mul_f32_e32 v26, v176, v26
	v_mul_f32_e32 v27, v177, v27
	v_mul_f32_e32 v28, v178, v28
	v_mul_f32_e32 v29, v179, v29
	v_mul_f32_e32 v30, v180, v30
	v_mul_f32_e32 v31, v181, v31
	v_mul_f32_e32 v32, v182, v32
	v_mul_f32_e32 v34, v183, v34
	v_add_f32_dpp v35, v35, v35 quad_perm:[2,3,0,1] row_mask:0xf bank_mask:0xf bound_ctrl:1
	ds_write_b32 v175, v35
	v_add_u32_e32 v175, v175, v162
	v_fmac_f32_e32 v26, v184, v200
	v_fmac_f32_e32 v27, v185, v200
	v_fmac_f32_e32 v28, v186, v200
	v_fmac_f32_e32 v29, v187, v200
	v_fmac_f32_e32 v30, v188, v200
	v_fmac_f32_e32 v31, v189, v200
	v_fmac_f32_e32 v32, v190, v200
	v_fmac_f32_e32 v34, v191, v200
	v_mul_f32_e32 v40, v192, v26
	v_mul_f32_e32 v41, v193, v27
	v_fmac_f32_e32 v40, v194, v28
	v_fmac_f32_e32 v41, v195, v29
	v_fmac_f32_e32 v40, v196, v30
	v_fmac_f32_e32 v41, v197, v31
	v_fmac_f32_e32 v40, v198, v32
	v_fmac_f32_e32 v41, v199, v34
	v_add_f32_e32 v35, v40, v41
	s_nop 1
	v_add_f32_dpp v35, v35, v35 quad_perm:[1,0,3,2] row_mask:0xf bank_mask:0xf bound_ctrl:1
	ds_read_b128 v[176:179], v174 offset:18304
	ds_read_b128 v[180:183], v174 offset:18320
	ds_read_b128 v[184:187], v174 offset:10112
	ds_read_b128 v[188:191], v174 offset:10128
	ds_read_b32 v200, v173 offset:28416
	ds_read_b128 v[192:195], v174 offset:1920
	ds_read_b128 v[196:199], v174 offset:1936
	s_waitcnt lgkmcnt(8)
	v_mul_f32_e32 v26, v0, v26
	v_mul_f32_e32 v27, v1, v27
	v_mul_f32_e32 v28, v2, v28
	v_mul_f32_e32 v29, v3, v29
	v_mul_f32_e32 v30, v4, v30
	v_mul_f32_e32 v31, v5, v31
	v_mul_f32_e32 v32, v6, v32
	v_mul_f32_e32 v34, v7, v34
	v_add_f32_dpp v35, v35, v35 quad_perm:[2,3,0,1] row_mask:0xf bank_mask:0xf bound_ctrl:1
	ds_write_b32 v175, v35
	v_add_u32_e32 v175, v175, v162
	v_fmac_f32_e32 v26, v8, v33
	v_fmac_f32_e32 v27, v9, v33
	v_fmac_f32_e32 v28, v10, v33
	v_fmac_f32_e32 v29, v11, v33
	v_fmac_f32_e32 v30, v12, v33
	v_fmac_f32_e32 v31, v13, v33
	v_fmac_f32_e32 v32, v14, v33
	v_fmac_f32_e32 v34, v15, v33
	v_mul_f32_e32 v40, v16, v26
	v_mul_f32_e32 v41, v17, v27
	v_fmac_f32_e32 v40, v18, v28
	v_fmac_f32_e32 v41, v19, v29
	v_fmac_f32_e32 v40, v20, v30
	v_fmac_f32_e32 v41, v21, v31
	v_fmac_f32_e32 v40, v22, v32
	v_fmac_f32_e32 v41, v23, v34
	v_add_f32_e32 v35, v40, v41
	s_nop 1
	v_add_f32_dpp v35, v35, v35 quad_perm:[1,0,3,2] row_mask:0xf bank_mask:0xf bound_ctrl:1
	ds_read_b128 v[0:3], v174 offset:18432
	ds_read_b128 v[4:7], v174 offset:18448
	ds_read_b128 v[8:11], v174 offset:10240
	ds_read_b128 v[12:15], v174 offset:10256
	ds_read_b32 v33, v173 offset:28672
	ds_read_b128 v[16:19], v174 offset:2048
	ds_read_b128 v[20:23], v174 offset:2064
	s_waitcnt lgkmcnt(8)
	v_mul_f32_e32 v26, v176, v26
	v_mul_f32_e32 v27, v177, v27
	v_mul_f32_e32 v28, v178, v28
	v_mul_f32_e32 v29, v179, v29
	v_mul_f32_e32 v30, v180, v30
	v_mul_f32_e32 v31, v181, v31
	v_mul_f32_e32 v32, v182, v32
	v_mul_f32_e32 v34, v183, v34
	v_add_f32_dpp v35, v35, v35 quad_perm:[2,3,0,1] row_mask:0xf bank_mask:0xf bound_ctrl:1
	ds_write_b32 v175, v35
	v_add_u32_e32 v175, v175, v162
	v_fmac_f32_e32 v26, v184, v200
	v_fmac_f32_e32 v27, v185, v200
	v_fmac_f32_e32 v28, v186, v200
	v_fmac_f32_e32 v29, v187, v200
	v_fmac_f32_e32 v30, v188, v200
	v_fmac_f32_e32 v31, v189, v200
	v_fmac_f32_e32 v32, v190, v200
	v_fmac_f32_e32 v34, v191, v200
	v_mul_f32_e32 v40, v192, v26
	v_mul_f32_e32 v41, v193, v27
	v_fmac_f32_e32 v40, v194, v28
	v_fmac_f32_e32 v41, v195, v29
	v_fmac_f32_e32 v40, v196, v30
	v_fmac_f32_e32 v41, v197, v31
	v_fmac_f32_e32 v40, v198, v32
	v_fmac_f32_e32 v41, v199, v34
	v_add_f32_e32 v35, v40, v41
	s_nop 1
	v_add_f32_dpp v35, v35, v35 quad_perm:[1,0,3,2] row_mask:0xf bank_mask:0xf bound_ctrl:1
	ds_read_b128 v[176:179], v174 offset:18560
	ds_read_b128 v[180:183], v174 offset:18576
	ds_read_b128 v[184:187], v174 offset:10368
	ds_read_b128 v[188:191], v174 offset:10384
	ds_read_b32 v200, v173 offset:28928
	ds_read_b128 v[192:195], v174 offset:2176
	ds_read_b128 v[196:199], v174 offset:2192
	s_waitcnt lgkmcnt(8)
; #define GLA_LD(t_, aq, kq, qq, vq) do { const int tt_ = (t_); vq = Bs[6144 + tt_ * 64 + pp]; \
;             _Pragma("unroll") for (int u = 0; u < 2; ++u) { aq[u] = *(const LAS f32x4*)(Bs + 4096 + tt_ * 32 + k0 + 4 * u); kq[u] = *(const LAS f32x4*)(Bs + 2048 + tt_ * 32 + k0 + 4 * u); qq[u] = *(const LAS f32x4*)(Bs + tt_ * 32 + k0 + 4 * u); } } while (0)
; #define GLA_STEP(t_, aq, kq, qq, vq) do { float y = 0.f; \
;             _Pragma("unroll") for (int u = 0; u < 2; ++u) _Pragma("unroll") for (int j = 0; j < 4; ++j) { S[4 * u + j] = aq[u][j] * S[4 * u + j] + kq[u][j] * vq; y += qq[u][j] * S[4 * u + j]; } \
;             y += dpp_f(y, 0xB1); y += dpp_f(y, 0x4E); ydst[(t_) * ystride] = y; } while (0)
; __device__ __forceinline__ void gla_job(const bf16_t* P, bf16_t* Y, int l, int b, int h, LAS float* lds, int wave_s) {
;     ...
;             GLA_LD(0, a0_, k0_, q0_, v0_);
;             for (int t = 0; t < TC; t += 2) {
;                 GLA_LD(t + 1, a1_, k1_, q1_, v1_);
;                 GLA_STEP(t, a0_, k0_, q0_, v0_);
;                 GLA_LD(t + 2 < TC ? t + 2 : t + 1, a0_, k0_, q0_, v0_);
;                 GLA_STEP(t + 1, a1_, k1_, q1_, v1_);
	v_mul_f32_e32 v26, v0, v26
	v_mul_f32_e32 v27, v1, v27
	v_mul_f32_e32 v28, v2, v28
	v_mul_f32_e32 v29, v3, v29
	v_mul_f32_e32 v30, v4, v30
	v_mul_f32_e32 v31, v5, v31
	v_mul_f32_e32 v32, v6, v32
	v_mul_f32_e32 v34, v7, v34
	v_add_f32_dpp v35, v35, v35 quad_perm:[2,3,0,1] row_mask:0xf bank_mask:0xf bound_ctrl:1
	ds_write_b32 v175, v35
	v_add_u32_e32 v175, v175, v162
	v_fmac_f32_e32 v26, v8, v33
	v_fmac_f32_e32 v27, v9, v33
	v_fmac_f32_e32 v28, v10, v33
	v_fmac_f32_e32 v29, v11, v33
	v_fmac_f32_e32 v30, v12, v33
	v_fmac_f32_e32 v31, v13, v33
	v_fmac_f32_e32 v32, v14, v33
	v_fmac_f32_e32 v34, v15, v33
	v_mul_f32_e32 v40, v16, v26
	v_mul_f32_e32 v41, v17, v27
	v_fmac_f32_e32 v40, v18, v28
	v_fmac_f32_e32 v41, v19, v29
	v_fmac_f32_e32 v40, v20, v30
	v_fmac_f32_e32 v41, v21, v31
	v_fmac_f32_e32 v40, v22, v32
	v_fmac_f32_e32 v41, v23, v34
	v_add_f32_e32 v35, v40, v41
	s_nop 1
	v_add_f32_dpp v35, v35, v35 quad_perm:[1,0,3,2] row_mask:0xf bank_mask:0xf bound_ctrl:1
	ds_read_b128 v[0:3], v174 offset:18688
	ds_read_b128 v[4:7], v174 offset:18704
	ds_read_b128 v[8:11], v174 offset:10496
	ds_read_b128 v[12:15], v174 offset:10512
	ds_read_b32 v33, v173 offset:29184
	ds_read_b128 v[16:19], v174 offset:2304
	ds_read_b128 v[20:23], v174 offset:2320
	s_waitcnt lgkmcnt(8)
	v_mul_f32_e32 v26, v176, v26
	v_mul_f32_e32 v27, v177, v27
	v_mul_f32_e32 v28, v178, v28
	v_mul_f32_e32 v29, v179, v29
	v_mul_f32_e32 v30, v180, v30
	v_mul_f32_e32 v31, v181, v31
	v_mul_f32_e32 v32, v182, v32
	v_mul_f32_e32 v34, v183, v34
	v_add_f32_dpp v35, v35, v35 quad_perm:[2,3,0,1] row_mask:0xf bank_mask:0xf bound_ctrl:1
	ds_write_b32 v175, v35
	v_add_u32_e32 v175, v175, v162
	v_fmac_f32_e32 v26, v184, v200
	v_fmac_f32_e32 v27, v185, v200
	v_fmac_f32_e32 v28, v186, v200
	v_fmac_f32_e32 v29, v187, v200
	v_fmac_f32_e32 v30, v188, v200
	v_fmac_f32_e32 v31, v189, v200
	v_fmac_f32_e32 v32, v190, v200
	v_fmac_f32_e32 v34, v191, v200
	v_mul_f32_e32 v40, v192, v26
	v_mul_f32_e32 v41, v193, v27
	v_fmac_f32_e32 v40, v194, v28
	v_fmac_f32_e32 v41, v195, v29
	v_fmac_f32_e32 v40, v196, v30
	v_fmac_f32_e32 v41, v197, v31
	v_fmac_f32_e32 v40, v198, v32
	v_fmac_f32_e32 v41, v199, v34
	v_add_f32_e32 v35, v40, v41
	s_nop 1
	v_add_f32_dpp v35, v35, v35 quad_perm:[1,0,3,2] row_mask:0xf bank_mask:0xf bound_ctrl:1
	ds_read_b128 v[176:179], v174 offset:18816
	ds_read_b128 v[180:183], v174 offset:18832
	ds_read_b128 v[184:187], v174 offset:10624
	ds_read_b128 v[188:191], v174 offset:10640
	ds_read_b32 v200, v173 offset:29440
	ds_read_b128 v[192:195], v174 offset:2432
	ds_read_b128 v[196:199], v174 offset:2448
	s_waitcnt lgkmcnt(8)
	v_mul_f32_e32 v26, v0, v26
	v_mul_f32_e32 v27, v1, v27
	v_mul_f32_e32 v28, v2, v28
	v_mul_f32_e32 v29, v3, v29
	v_mul_f32_e32 v30, v4, v30
	v_mul_f32_e32 v31, v5, v31
	v_mul_f32_e32 v32, v6, v32
	v_mul_f32_e32 v34, v7, v34
	v_add_f32_dpp v35, v35, v35 quad_perm:[2,3,0,1] row_mask:0xf bank_mask:0xf bound_ctrl:1
	ds_write_b32 v175, v35
	v_add_u32_e32 v175, v175, v162
	v_fmac_f32_e32 v26, v8, v33
	v_fmac_f32_e32 v27, v9, v33
	v_fmac_f32_e32 v28, v10, v33
	v_fmac_f32_e32 v29, v11, v33
	v_fmac_f32_e32 v30, v12, v33
	v_fmac_f32_e32 v31, v13, v33
	v_fmac_f32_e32 v32, v14, v33
	v_fmac_f32_e32 v34, v15, v33
	v_mul_f32_e32 v40, v16, v26
	v_mul_f32_e32 v41, v17, v27
	v_fmac_f32_e32 v40, v18, v28
	v_fmac_f32_e32 v41, v19, v29
	v_fmac_f32_e32 v40, v20, v30
	v_fmac_f32_e32 v41, v21, v31
	v_fmac_f32_e32 v40, v22, v32
	v_fmac_f32_e32 v41, v23, v34
	v_add_f32_e32 v35, v40, v41
	s_nop 1
	v_add_f32_dpp v35, v35, v35 quad_perm:[1,0,3,2] row_mask:0xf bank_mask:0xf bound_ctrl:1
	ds_read_b128 v[0:3], v174 offset:18944
	ds_read_b128 v[4:7], v174 offset:18960
	ds_read_b128 v[8:11], v174 offset:10752
	ds_read_b128 v[12:15], v174 offset:10768
	ds_read_b32 v33, v173 offset:29696
	ds_read_b128 v[16:19], v174 offset:2560
	ds_read_b128 v[20:23], v174 offset:2576
	s_waitcnt lgkmcnt(8)
	v_mul_f32_e32 v26, v176, v26
	v_mul_f32_e32 v27, v177, v27
	v_mul_f32_e32 v28, v178, v28
	v_mul_f32_e32 v29, v179, v29
	v_mul_f32_e32 v30, v180, v30
	v_mul_f32_e32 v31, v181, v31
	v_mul_f32_e32 v32, v182, v32
	v_mul_f32_e32 v34, v183, v34
	v_add_f32_dpp v35, v35, v35 quad_perm:[2,3,0,1] row_mask:0xf bank_mask:0xf bound_ctrl:1
	ds_write_b32 v175, v35
	v_add_u32_e32 v175, v175, v162
	v_fmac_f32_e32 v26, v184, v200
	v_fmac_f32_e32 v27, v185, v200
	v_fmac_f32_e32 v28, v186, v200
	v_fmac_f32_e32 v29, v187, v200
	v_fmac_f32_e32 v30, v188, v200
	v_fmac_f32_e32 v31, v189, v200
	v_fmac_f32_e32 v32, v190, v200
	v_fmac_f32_e32 v34, v191, v200
	v_mul_f32_e32 v40, v192, v26
	v_mul_f32_e32 v41, v193, v27
	v_fmac_f32_e32 v40, v194, v28
	v_fmac_f32_e32 v41, v195, v29
	v_fmac_f32_e32 v40, v196, v30
	v_fmac_f32_e32 v41, v197, v31
	v_fmac_f32_e32 v40, v198, v32
	v_fmac_f32_e32 v41, v199, v34
	v_add_f32_e32 v35, v40, v41
	s_nop 1
	v_add_f32_dpp v35, v35, v35 quad_perm:[1,0,3,2] row_mask:0xf bank_mask:0xf bound_ctrl:1
	ds_read_b128 v[176:179], v174 offset:19072
	ds_read_b128 v[180:183], v174 offset:19088
	ds_read_b128 v[184:187], v174 offset:10880
	ds_read_b128 v[188:191], v174 offset:10896
	ds_read_b32 v200, v173 offset:29952
	ds_read_b128 v[192:195], v174 offset:2688
	ds_read_b128 v[196:199], v174 offset:2704
	s_waitcnt lgkmcnt(8)
; #define GLA_LD(t_, aq, kq, qq, vq) do { const int tt_ = (t_); vq = Bs[6144 + tt_ * 64 + pp]; \
;             _Pragma("unroll") for (int u = 0; u < 2; ++u) { aq[u] = *(const LAS f32x4*)(Bs + 4096 + tt_ * 32 + k0 + 4 * u); kq[u] = *(const LAS f32x4*)(Bs + 2048 + tt_ * 32 + k0 + 4 * u); qq[u] = *(const LAS f32x4*)(Bs + tt_ * 32 + k0 + 4 * u); } } while (0)
; #define GLA_STEP(t_, aq, kq, qq, vq) do { float y = 0.f; \
;             _Pragma("unroll") for (int u = 0; u < 2; ++u) _Pragma("unroll") for (int j = 0; j < 4; ++j) { S[4 * u + j] = aq[u][j] * S[4 * u + j] + kq[u][j] * vq; y += qq[u][j] * S[4 * u + j]; } \
;             y += dpp_f(y, 0xB1); y += dpp_f(y, 0x4E); ydst[(t_) * ystride] = y; } while (0)
; __device__ __forceinline__ void gla_job(const bf16_t* P, bf16_t* Y, int l, int b, int h, LAS float* lds, int wave_s) {
;     ...
;             GLA_LD(0, a0_, k0_, q0_, v0_);
;             for (int t = 0; t < TC; t += 2) {
;                 GLA_LD(t + 1, a1_, k1_, q1_, v1_);
;                 GLA_STEP(t, a0_, k0_, q0_, v0_);
;                 GLA_LD(t + 2 < TC ? t + 2 : t + 1, a0_, k0_, q0_, v0_);
;                 GLA_STEP(t + 1, a1_, k1_, q1_, v1_);
	v_mul_f32_e32 v26, v0, v26
	v_mul_f32_e32 v27, v1, v27
	v_mul_f32_e32 v28, v2, v28
	v_mul_f32_e32 v29, v3, v29
	v_mul_f32_e32 v30, v4, v30
	v_mul_f32_e32 v31, v5, v31
	v_mul_f32_e32 v32, v6, v32
	v_mul_f32_e32 v34, v7, v34
	v_add_f32_dpp v35, v35, v35 quad_perm:[2,3,0,1] row_mask:0xf bank_mask:0xf bound_ctrl:1
	ds_write_b32 v175, v35
	v_add_u32_e32 v175, v175, v162
	v_fmac_f32_e32 v26, v8, v33
	v_fmac_f32_e32 v27, v9, v33
	v_fmac_f32_e32 v28, v10, v33
	v_fmac_f32_e32 v29, v11, v33
	v_fmac_f32_e32 v30, v12, v33
	v_fmac_f32_e32 v31, v13, v33
	v_fmac_f32_e32 v32, v14, v33
	v_fmac_f32_e32 v34, v15, v33
	v_mul_f32_e32 v40, v16, v26
	v_mul_f32_e32 v41, v17, v27
	v_fmac_f32_e32 v40, v18, v28
	v_fmac_f32_e32 v41, v19, v29
	v_fmac_f32_e32 v40, v20, v30
	v_fmac_f32_e32 v41, v21, v31
	v_fmac_f32_e32 v40, v22, v32
	v_fmac_f32_e32 v41, v23, v34
	v_add_f32_e32 v35, v40, v41
	s_nop 1
	v_add_f32_dpp v35, v35, v35 quad_perm:[1,0,3,2] row_mask:0xf bank_mask:0xf bound_ctrl:1
	ds_read_b128 v[0:3], v174 offset:19200
	ds_read_b128 v[4:7], v174 offset:19216
	ds_read_b128 v[8:11], v174 offset:11008
	ds_read_b128 v[12:15], v174 offset:11024
	ds_read_b32 v33, v173 offset:30208
	ds_read_b128 v[16:19], v174 offset:2816
	ds_read_b128 v[20:23], v174 offset:2832
	s_waitcnt lgkmcnt(8)
	v_mul_f32_e32 v26, v176, v26
	v_mul_f32_e32 v27, v177, v27
	v_mul_f32_e32 v28, v178, v28
	v_mul_f32_e32 v29, v179, v29
	v_mul_f32_e32 v30, v180, v30
	v_mul_f32_e32 v31, v181, v31
	v_mul_f32_e32 v32, v182, v32
	v_mul_f32_e32 v34, v183, v34
	v_add_f32_dpp v35, v35, v35 quad_perm:[2,3,0,1] row_mask:0xf bank_mask:0xf bound_ctrl:1
	ds_write_b32 v175, v35
	v_add_u32_e32 v175, v175, v162
	v_fmac_f32_e32 v26, v184, v200
	v_fmac_f32_e32 v27, v185, v200
	v_fmac_f32_e32 v28, v186, v200
	v_fmac_f32_e32 v29, v187, v200
	v_fmac_f32_e32 v30, v188, v200
	v_fmac_f32_e32 v31, v189, v200
	v_fmac_f32_e32 v32, v190, v200
	v_fmac_f32_e32 v34, v191, v200
	v_mul_f32_e32 v40, v192, v26
	v_mul_f32_e32 v41, v193, v27
	v_fmac_f32_e32 v40, v194, v28
	v_fmac_f32_e32 v41, v195, v29
	v_fmac_f32_e32 v40, v196, v30
	v_fmac_f32_e32 v41, v197, v31
	v_fmac_f32_e32 v40, v198, v32
	v_fmac_f32_e32 v41, v199, v34
	v_add_f32_e32 v35, v40, v41
	s_nop 1
	v_add_f32_dpp v35, v35, v35 quad_perm:[1,0,3,2] row_mask:0xf bank_mask:0xf bound_ctrl:1
	ds_read_b128 v[176:179], v174 offset:19328
	ds_read_b128 v[180:183], v174 offset:19344
	ds_read_b128 v[184:187], v174 offset:11136
	ds_read_b128 v[188:191], v174 offset:11152
	ds_read_b32 v200, v173 offset:30464
	ds_read_b128 v[192:195], v174 offset:2944
	ds_read_b128 v[196:199], v174 offset:2960
	s_waitcnt lgkmcnt(8)
	v_mul_f32_e32 v26, v0, v26
	v_mul_f32_e32 v27, v1, v27
	v_mul_f32_e32 v28, v2, v28
	v_mul_f32_e32 v29, v3, v29
	v_mul_f32_e32 v30, v4, v30
	v_mul_f32_e32 v31, v5, v31
	v_mul_f32_e32 v32, v6, v32
	v_mul_f32_e32 v34, v7, v34
	v_add_f32_dpp v35, v35, v35 quad_perm:[2,3,0,1] row_mask:0xf bank_mask:0xf bound_ctrl:1
	ds_write_b32 v175, v35
	v_add_u32_e32 v175, v175, v162
	v_fmac_f32_e32 v26, v8, v33
	v_fmac_f32_e32 v27, v9, v33
	v_fmac_f32_e32 v28, v10, v33
	v_fmac_f32_e32 v29, v11, v33
	v_fmac_f32_e32 v30, v12, v33
	v_fmac_f32_e32 v31, v13, v33
	v_fmac_f32_e32 v32, v14, v33
	v_fmac_f32_e32 v34, v15, v33
	v_mul_f32_e32 v40, v16, v26
	v_mul_f32_e32 v41, v17, v27
	v_fmac_f32_e32 v40, v18, v28
	v_fmac_f32_e32 v41, v19, v29
	v_fmac_f32_e32 v40, v20, v30
	v_fmac_f32_e32 v41, v21, v31
	v_fmac_f32_e32 v40, v22, v32
	v_fmac_f32_e32 v41, v23, v34
	v_add_f32_e32 v35, v40, v41
	s_nop 1
	v_add_f32_dpp v35, v35, v35 quad_perm:[1,0,3,2] row_mask:0xf bank_mask:0xf bound_ctrl:1
	ds_read_b128 v[0:3], v174 offset:19456
	ds_read_b128 v[4:7], v174 offset:19472
	ds_read_b128 v[8:11], v174 offset:11264
	ds_read_b128 v[12:15], v174 offset:11280
	ds_read_b32 v33, v173 offset:30720
	ds_read_b128 v[16:19], v174 offset:3072
	ds_read_b128 v[20:23], v174 offset:3088
	s_waitcnt lgkmcnt(8)
	v_mul_f32_e32 v26, v176, v26
	v_mul_f32_e32 v27, v177, v27
	v_mul_f32_e32 v28, v178, v28
	v_mul_f32_e32 v29, v179, v29
	v_mul_f32_e32 v30, v180, v30
	v_mul_f32_e32 v31, v181, v31
	v_mul_f32_e32 v32, v182, v32
	v_mul_f32_e32 v34, v183, v34
	v_add_f32_dpp v35, v35, v35 quad_perm:[2,3,0,1] row_mask:0xf bank_mask:0xf bound_ctrl:1
	ds_write_b32 v175, v35
	v_add_u32_e32 v175, v175, v162
	v_fmac_f32_e32 v26, v184, v200
	v_fmac_f32_e32 v27, v185, v200
	v_fmac_f32_e32 v28, v186, v200
	v_fmac_f32_e32 v29, v187, v200
	v_fmac_f32_e32 v30, v188, v200
	v_fmac_f32_e32 v31, v189, v200
	v_fmac_f32_e32 v32, v190, v200
	v_fmac_f32_e32 v34, v191, v200
	v_mul_f32_e32 v40, v192, v26
	v_mul_f32_e32 v41, v193, v27
	v_fmac_f32_e32 v40, v194, v28
	v_fmac_f32_e32 v41, v195, v29
	v_fmac_f32_e32 v40, v196, v30
	v_fmac_f32_e32 v41, v197, v31
	v_fmac_f32_e32 v40, v198, v32
	v_fmac_f32_e32 v41, v199, v34
	v_add_f32_e32 v35, v40, v41
	s_nop 1
	v_add_f32_dpp v35, v35, v35 quad_perm:[1,0,3,2] row_mask:0xf bank_mask:0xf bound_ctrl:1
	ds_read_b128 v[176:179], v174 offset:19584
	ds_read_b128 v[180:183], v174 offset:19600
	ds_read_b128 v[184:187], v174 offset:11392
	ds_read_b128 v[188:191], v174 offset:11408
	ds_read_b32 v200, v173 offset:30976
	ds_read_b128 v[192:195], v174 offset:3200
	ds_read_b128 v[196:199], v174 offset:3216
	s_waitcnt lgkmcnt(8)
; #define GLA_LD(t_, aq, kq, qq, vq) do { const int tt_ = (t_); vq = Bs[6144 + tt_ * 64 + pp]; \
;             _Pragma("unroll") for (int u = 0; u < 2; ++u) { aq[u] = *(const LAS f32x4*)(Bs + 4096 + tt_ * 32 + k0 + 4 * u); kq[u] = *(const LAS f32x4*)(Bs + 2048 + tt_ * 32 + k0 + 4 * u); qq[u] = *(const LAS f32x4*)(Bs + tt_ * 32 + k0 + 4 * u); } } while (0)
; #define GLA_STEP(t_, aq, kq, qq, vq) do { float y = 0.f; \
;             _Pragma("unroll") for (int u = 0; u < 2; ++u) _Pragma("unroll") for (int j = 0; j < 4; ++j) { S[4 * u + j] = aq[u][j] * S[4 * u + j] + kq[u][j] * vq; y += qq[u][j] * S[4 * u + j]; } \
;             y += dpp_f(y, 0xB1); y += dpp_f(y, 0x4E); ydst[(t_) * ystride] = y; } while (0)
; __device__ __forceinline__ void gla_job(const bf16_t* P, bf16_t* Y, int l, int b, int h, LAS float* lds, int wave_s) {
;     ...
;             GLA_LD(0, a0_, k0_, q0_, v0_);
;             for (int t = 0; t < TC; t += 2) {
;                 GLA_LD(t + 1, a1_, k1_, q1_, v1_);
;                 GLA_STEP(t, a0_, k0_, q0_, v0_);
;                 GLA_LD(t + 2 < TC ? t + 2 : t + 1, a0_, k0_, q0_, v0_);
;                 GLA_STEP(t + 1, a1_, k1_, q1_, v1_);
	v_mul_f32_e32 v26, v0, v26
	v_mul_f32_e32 v27, v1, v27
	v_mul_f32_e32 v28, v2, v28
	v_mul_f32_e32 v29, v3, v29
	v_mul_f32_e32 v30, v4, v30
	v_mul_f32_e32 v31, v5, v31
	v_mul_f32_e32 v32, v6, v32
	v_mul_f32_e32 v34, v7, v34
	v_add_f32_dpp v35, v35, v35 quad_perm:[2,3,0,1] row_mask:0xf bank_mask:0xf bound_ctrl:1
	ds_write_b32 v175, v35
	v_add_u32_e32 v175, v175, v162
	v_fmac_f32_e32 v26, v8, v33
	v_fmac_f32_e32 v27, v9, v33
	v_fmac_f32_e32 v28, v10, v33
	v_fmac_f32_e32 v29, v11, v33
	v_fmac_f32_e32 v30, v12, v33
	v_fmac_f32_e32 v31, v13, v33
	v_fmac_f32_e32 v32, v14, v33
	v_fmac_f32_e32 v34, v15, v33
	v_mul_f32_e32 v40, v16, v26
	v_mul_f32_e32 v41, v17, v27
	v_fmac_f32_e32 v40, v18, v28
	v_fmac_f32_e32 v41, v19, v29
	v_fmac_f32_e32 v40, v20, v30
	v_fmac_f32_e32 v41, v21, v31
	v_fmac_f32_e32 v40, v22, v32
	v_fmac_f32_e32 v41, v23, v34
	v_add_f32_e32 v35, v40, v41
	s_nop 1
	v_add_f32_dpp v35, v35, v35 quad_perm:[1,0,3,2] row_mask:0xf bank_mask:0xf bound_ctrl:1
	ds_read_b128 v[0:3], v174 offset:19712
	ds_read_b128 v[4:7], v174 offset:19728
	ds_read_b128 v[8:11], v174 offset:11520
	ds_read_b128 v[12:15], v174 offset:11536
	ds_read_b32 v33, v173 offset:31232
	ds_read_b128 v[16:19], v174 offset:3328
	ds_read_b128 v[20:23], v174 offset:3344
	s_waitcnt lgkmcnt(8)
	v_mul_f32_e32 v26, v176, v26
	v_mul_f32_e32 v27, v177, v27
	v_mul_f32_e32 v28, v178, v28
	v_mul_f32_e32 v29, v179, v29
	v_mul_f32_e32 v30, v180, v30
	v_mul_f32_e32 v31, v181, v31
	v_mul_f32_e32 v32, v182, v32
	v_mul_f32_e32 v34, v183, v34
	v_add_f32_dpp v35, v35, v35 quad_perm:[2,3,0,1] row_mask:0xf bank_mask:0xf bound_ctrl:1
	ds_write_b32 v175, v35
	v_add_u32_e32 v175, v175, v162
	v_fmac_f32_e32 v26, v184, v200
	v_fmac_f32_e32 v27, v185, v200
	v_fmac_f32_e32 v28, v186, v200
	v_fmac_f32_e32 v29, v187, v200
	v_fmac_f32_e32 v30, v188, v200
	v_fmac_f32_e32 v31, v189, v200
	v_fmac_f32_e32 v32, v190, v200
	v_fmac_f32_e32 v34, v191, v200
	v_mul_f32_e32 v40, v192, v26
	v_mul_f32_e32 v41, v193, v27
	v_fmac_f32_e32 v40, v194, v28
	v_fmac_f32_e32 v41, v195, v29
	v_fmac_f32_e32 v40, v196, v30
	v_fmac_f32_e32 v41, v197, v31
	v_fmac_f32_e32 v40, v198, v32
	v_fmac_f32_e32 v41, v199, v34
	v_add_f32_e32 v35, v40, v41
	s_nop 1
	v_add_f32_dpp v35, v35, v35 quad_perm:[1,0,3,2] row_mask:0xf bank_mask:0xf bound_ctrl:1
	ds_read_b128 v[176:179], v174 offset:19840
	ds_read_b128 v[180:183], v174 offset:19856
	ds_read_b128 v[184:187], v174 offset:11648
	ds_read_b128 v[188:191], v174 offset:11664
	ds_read_b32 v200, v173 offset:31488
	ds_read_b128 v[192:195], v174 offset:3456
	ds_read_b128 v[196:199], v174 offset:3472
	s_waitcnt lgkmcnt(8)
	v_mul_f32_e32 v26, v0, v26
	v_mul_f32_e32 v27, v1, v27
	v_mul_f32_e32 v28, v2, v28
	v_mul_f32_e32 v29, v3, v29
	v_mul_f32_e32 v30, v4, v30
	v_mul_f32_e32 v31, v5, v31
	v_mul_f32_e32 v32, v6, v32
	v_mul_f32_e32 v34, v7, v34
	v_add_f32_dpp v35, v35, v35 quad_perm:[2,3,0,1] row_mask:0xf bank_mask:0xf bound_ctrl:1
	ds_write_b32 v175, v35
	v_add_u32_e32 v175, v175, v162
	v_fmac_f32_e32 v26, v8, v33
	v_fmac_f32_e32 v27, v9, v33
	v_fmac_f32_e32 v28, v10, v33
	v_fmac_f32_e32 v29, v11, v33
	v_fmac_f32_e32 v30, v12, v33
	v_fmac_f32_e32 v31, v13, v33
	v_fmac_f32_e32 v32, v14, v33
	v_fmac_f32_e32 v34, v15, v33
	v_mul_f32_e32 v40, v16, v26
	v_mul_f32_e32 v41, v17, v27
	v_fmac_f32_e32 v40, v18, v28
	v_fmac_f32_e32 v41, v19, v29
	v_fmac_f32_e32 v40, v20, v30
	v_fmac_f32_e32 v41, v21, v31
	v_fmac_f32_e32 v40, v22, v32
	v_fmac_f32_e32 v41, v23, v34
	v_add_f32_e32 v35, v40, v41
	s_nop 1
	v_add_f32_dpp v35, v35, v35 quad_perm:[1,0,3,2] row_mask:0xf bank_mask:0xf bound_ctrl:1
	ds_read_b128 v[0:3], v174 offset:19968
	ds_read_b128 v[4:7], v174 offset:19984
	ds_read_b128 v[8:11], v174 offset:11776
	ds_read_b128 v[12:15], v174 offset:11792
	ds_read_b32 v33, v173 offset:31744
	ds_read_b128 v[16:19], v174 offset:3584
	ds_read_b128 v[20:23], v174 offset:3600
	s_waitcnt lgkmcnt(8)
	v_mul_f32_e32 v26, v176, v26
	v_mul_f32_e32 v27, v177, v27
	v_mul_f32_e32 v28, v178, v28
	v_mul_f32_e32 v29, v179, v29
	v_mul_f32_e32 v30, v180, v30
	v_mul_f32_e32 v31, v181, v31
	v_mul_f32_e32 v32, v182, v32
	v_mul_f32_e32 v34, v183, v34
	v_add_f32_dpp v35, v35, v35 quad_perm:[2,3,0,1] row_mask:0xf bank_mask:0xf bound_ctrl:1
	ds_write_b32 v175, v35
	v_add_u32_e32 v175, v175, v162
	v_fmac_f32_e32 v26, v184, v200
	v_fmac_f32_e32 v27, v185, v200
	v_fmac_f32_e32 v28, v186, v200
	v_fmac_f32_e32 v29, v187, v200
	v_fmac_f32_e32 v30, v188, v200
	v_fmac_f32_e32 v31, v189, v200
	v_fmac_f32_e32 v32, v190, v200
	v_fmac_f32_e32 v34, v191, v200
	v_mul_f32_e32 v40, v192, v26
	v_mul_f32_e32 v41, v193, v27
	v_fmac_f32_e32 v40, v194, v28
	v_fmac_f32_e32 v41, v195, v29
	v_fmac_f32_e32 v40, v196, v30
	v_fmac_f32_e32 v41, v197, v31
	v_fmac_f32_e32 v40, v198, v32
	v_fmac_f32_e32 v41, v199, v34
	v_add_f32_e32 v35, v40, v41
	s_nop 1
	v_add_f32_dpp v35, v35, v35 quad_perm:[1,0,3,2] row_mask:0xf bank_mask:0xf bound_ctrl:1
	ds_read_b128 v[176:179], v174 offset:20096
	ds_read_b128 v[180:183], v174 offset:20112
	ds_read_b128 v[184:187], v174 offset:11904
	ds_read_b128 v[188:191], v174 offset:11920
	ds_read_b32 v200, v173 offset:32000
	ds_read_b128 v[192:195], v174 offset:3712
	ds_read_b128 v[196:199], v174 offset:3728
	s_waitcnt lgkmcnt(8)
; #define GLA_LD(t_, aq, kq, qq, vq) do { const int tt_ = (t_); vq = Bs[6144 + tt_ * 64 + pp]; \
;             _Pragma("unroll") for (int u = 0; u < 2; ++u) { aq[u] = *(const LAS f32x4*)(Bs + 4096 + tt_ * 32 + k0 + 4 * u); kq[u] = *(const LAS f32x4*)(Bs + 2048 + tt_ * 32 + k0 + 4 * u); qq[u] = *(const LAS f32x4*)(Bs + tt_ * 32 + k0 + 4 * u); } } while (0)
; #define GLA_STEP(t_, aq, kq, qq, vq) do { float y = 0.f; \
;             _Pragma("unroll") for (int u = 0; u < 2; ++u) _Pragma("unroll") for (int j = 0; j < 4; ++j) { S[4 * u + j] = aq[u][j] * S[4 * u + j] + kq[u][j] * vq; y += qq[u][j] * S[4 * u + j]; } \
;             y += dpp_f(y, 0xB1); y += dpp_f(y, 0x4E); ydst[(t_) * ystride] = y; } while (0)
; __device__ __forceinline__ void gla_job(const bf16_t* P, bf16_t* Y, int l, int b, int h, LAS float* lds, int wave_s) {
;     ...
;             GLA_LD(0, a0_, k0_, q0_, v0_);
;             for (int t = 0; t < TC; t += 2) {
;                 GLA_LD(t + 1, a1_, k1_, q1_, v1_);
;                 GLA_STEP(t, a0_, k0_, q0_, v0_);
;                 GLA_LD(t + 2 < TC ? t + 2 : t + 1, a0_, k0_, q0_, v0_);
;                 GLA_STEP(t + 1, a1_, k1_, q1_, v1_);
	v_mul_f32_e32 v26, v0, v26
	v_mul_f32_e32 v27, v1, v27
	v_mul_f32_e32 v28, v2, v28
	v_mul_f32_e32 v29, v3, v29
	v_mul_f32_e32 v30, v4, v30
	v_mul_f32_e32 v31, v5, v31
	v_mul_f32_e32 v32, v6, v32
	v_mul_f32_e32 v34, v7, v34
	v_add_f32_dpp v35, v35, v35 quad_perm:[2,3,0,1] row_mask:0xf bank_mask:0xf bound_ctrl:1
	ds_write_b32 v175, v35
	v_add_u32_e32 v175, v175, v162
	v_fmac_f32_e32 v26, v8, v33
	v_fmac_f32_e32 v27, v9, v33
	v_fmac_f32_e32 v28, v10, v33
	v_fmac_f32_e32 v29, v11, v33
	v_fmac_f32_e32 v30, v12, v33
	v_fmac_f32_e32 v31, v13, v33
	v_fmac_f32_e32 v32, v14, v33
	v_fmac_f32_e32 v34, v15, v33
	v_mul_f32_e32 v40, v16, v26
	v_mul_f32_e32 v41, v17, v27
	v_fmac_f32_e32 v40, v18, v28
	v_fmac_f32_e32 v41, v19, v29
	v_fmac_f32_e32 v40, v20, v30
	v_fmac_f32_e32 v41, v21, v31
	v_fmac_f32_e32 v40, v22, v32
	v_fmac_f32_e32 v41, v23, v34
	v_add_f32_e32 v35, v40, v41
	s_nop 1
	v_add_f32_dpp v35, v35, v35 quad_perm:[1,0,3,2] row_mask:0xf bank_mask:0xf bound_ctrl:1
	ds_read_b128 v[0:3], v174 offset:20224
	ds_read_b128 v[4:7], v174 offset:20240
	ds_read_b128 v[8:11], v174 offset:12032
	ds_read_b128 v[12:15], v174 offset:12048
	ds_read_b32 v33, v173 offset:32256
	ds_read_b128 v[16:19], v174 offset:3840
	ds_read_b128 v[20:23], v174 offset:3856
	s_waitcnt lgkmcnt(8)
	v_mul_f32_e32 v26, v176, v26
	v_mul_f32_e32 v27, v177, v27
	v_mul_f32_e32 v28, v178, v28
	v_mul_f32_e32 v29, v179, v29
	v_mul_f32_e32 v30, v180, v30
	v_mul_f32_e32 v31, v181, v31
	v_mul_f32_e32 v32, v182, v32
	v_mul_f32_e32 v34, v183, v34
	v_add_f32_dpp v35, v35, v35 quad_perm:[2,3,0,1] row_mask:0xf bank_mask:0xf bound_ctrl:1
	ds_write_b32 v175, v35
	v_add_u32_e32 v175, v175, v162
	v_fmac_f32_e32 v26, v184, v200
	v_fmac_f32_e32 v27, v185, v200
	v_fmac_f32_e32 v28, v186, v200
	v_fmac_f32_e32 v29, v187, v200
	v_fmac_f32_e32 v30, v188, v200
	v_fmac_f32_e32 v31, v189, v200
	v_fmac_f32_e32 v32, v190, v200
	v_fmac_f32_e32 v34, v191, v200
	v_mul_f32_e32 v40, v192, v26
	v_mul_f32_e32 v41, v193, v27
	v_fmac_f32_e32 v40, v194, v28
	v_fmac_f32_e32 v41, v195, v29
	v_fmac_f32_e32 v40, v196, v30
	v_fmac_f32_e32 v41, v197, v31
	v_fmac_f32_e32 v40, v198, v32
	v_fmac_f32_e32 v41, v199, v34
	v_add_f32_e32 v35, v40, v41
	s_nop 1
	v_add_f32_dpp v35, v35, v35 quad_perm:[1,0,3,2] row_mask:0xf bank_mask:0xf bound_ctrl:1
	ds_read_b128 v[176:179], v174 offset:20352
	ds_read_b128 v[180:183], v174 offset:20368
	ds_read_b128 v[184:187], v174 offset:12160
	ds_read_b128 v[188:191], v174 offset:12176
	ds_read_b32 v200, v173 offset:32512
	ds_read_b128 v[192:195], v174 offset:3968
	ds_read_b128 v[196:199], v174 offset:3984
	s_waitcnt lgkmcnt(8)
	v_mul_f32_e32 v26, v0, v26
	v_mul_f32_e32 v27, v1, v27
	v_mul_f32_e32 v28, v2, v28
	v_mul_f32_e32 v29, v3, v29
	v_mul_f32_e32 v30, v4, v30
	v_mul_f32_e32 v31, v5, v31
	v_mul_f32_e32 v32, v6, v32
	v_mul_f32_e32 v34, v7, v34
	v_add_f32_dpp v35, v35, v35 quad_perm:[2,3,0,1] row_mask:0xf bank_mask:0xf bound_ctrl:1
	ds_write_b32 v175, v35
	v_add_u32_e32 v175, v175, v162
	v_fmac_f32_e32 v26, v8, v33
	v_fmac_f32_e32 v27, v9, v33
	v_fmac_f32_e32 v28, v10, v33
	v_fmac_f32_e32 v29, v11, v33
	v_fmac_f32_e32 v30, v12, v33
	v_fmac_f32_e32 v31, v13, v33
	v_fmac_f32_e32 v32, v14, v33
	v_fmac_f32_e32 v34, v15, v33
	v_mul_f32_e32 v40, v16, v26
	v_mul_f32_e32 v41, v17, v27
	v_fmac_f32_e32 v40, v18, v28
	v_fmac_f32_e32 v41, v19, v29
	v_fmac_f32_e32 v40, v20, v30
	v_fmac_f32_e32 v41, v21, v31
	v_fmac_f32_e32 v40, v22, v32
	v_fmac_f32_e32 v41, v23, v34
	v_add_f32_e32 v35, v40, v41
	s_nop 1
	v_add_f32_dpp v35, v35, v35 quad_perm:[1,0,3,2] row_mask:0xf bank_mask:0xf bound_ctrl:1
	ds_read_b128 v[0:3], v174 offset:20480
	ds_read_b128 v[4:7], v174 offset:20496
	ds_read_b128 v[8:11], v174 offset:12288
	ds_read_b128 v[12:15], v174 offset:12304
	ds_read_b32 v33, v173 offset:32768
	ds_read_b128 v[16:19], v174 offset:4096
	ds_read_b128 v[20:23], v174 offset:4112
	s_waitcnt lgkmcnt(8)
	v_mul_f32_e32 v26, v176, v26
	v_mul_f32_e32 v27, v177, v27
	v_mul_f32_e32 v28, v178, v28
	v_mul_f32_e32 v29, v179, v29
	v_mul_f32_e32 v30, v180, v30
	v_mul_f32_e32 v31, v181, v31
	v_mul_f32_e32 v32, v182, v32
	v_mul_f32_e32 v34, v183, v34
	v_add_f32_dpp v35, v35, v35 quad_perm:[2,3,0,1] row_mask:0xf bank_mask:0xf bound_ctrl:1
	ds_write_b32 v175, v35
	v_add_u32_e32 v175, v175, v162
	v_fmac_f32_e32 v26, v184, v200
	v_fmac_f32_e32 v27, v185, v200
	v_fmac_f32_e32 v28, v186, v200
	v_fmac_f32_e32 v29, v187, v200
	v_fmac_f32_e32 v30, v188, v200
	v_fmac_f32_e32 v31, v189, v200
	v_fmac_f32_e32 v32, v190, v200
	v_fmac_f32_e32 v34, v191, v200
	v_mul_f32_e32 v40, v192, v26
	v_mul_f32_e32 v41, v193, v27
	v_fmac_f32_e32 v40, v194, v28
	v_fmac_f32_e32 v41, v195, v29
	v_fmac_f32_e32 v40, v196, v30
	v_fmac_f32_e32 v41, v197, v31
	v_fmac_f32_e32 v40, v198, v32
	v_fmac_f32_e32 v41, v199, v34
	v_add_f32_e32 v35, v40, v41
	s_nop 1
	v_add_f32_dpp v35, v35, v35 quad_perm:[1,0,3,2] row_mask:0xf bank_mask:0xf bound_ctrl:1
	ds_read_b128 v[176:179], v174 offset:20608
	ds_read_b128 v[180:183], v174 offset:20624
	ds_read_b128 v[184:187], v174 offset:12416
	ds_read_b128 v[188:191], v174 offset:12432
	ds_read_b32 v200, v173 offset:33024
	ds_read_b128 v[192:195], v174 offset:4224
	ds_read_b128 v[196:199], v174 offset:4240
	s_waitcnt lgkmcnt(8)
; #define GLA_LD(t_, aq, kq, qq, vq) do { const int tt_ = (t_); vq = Bs[6144 + tt_ * 64 + pp]; \
;             _Pragma("unroll") for (int u = 0; u < 2; ++u) { aq[u] = *(const LAS f32x4*)(Bs + 4096 + tt_ * 32 + k0 + 4 * u); kq[u] = *(const LAS f32x4*)(Bs + 2048 + tt_ * 32 + k0 + 4 * u); qq[u] = *(const LAS f32x4*)(Bs + tt_ * 32 + k0 + 4 * u); } } while (0)
; #define GLA_STEP(t_, aq, kq, qq, vq) do { float y = 0.f; \
;             _Pragma("unroll") for (int u = 0; u < 2; ++u) _Pragma("unroll") for (int j = 0; j < 4; ++j) { S[4 * u + j] = aq[u][j] * S[4 * u + j] + kq[u][j] * vq; y += qq[u][j] * S[4 * u + j]; } \
;             y += dpp_f(y, 0xB1); y += dpp_f(y, 0x4E); ydst[(t_) * ystride] = y; } while (0)
; __device__ __forceinline__ void gla_job(const bf16_t* P, bf16_t* Y, int l, int b, int h, LAS float* lds, int wave_s) {
;     ...
;             GLA_LD(0, a0_, k0_, q0_, v0_);
;             for (int t = 0; t < TC; t += 2) {
;                 GLA_LD(t + 1, a1_, k1_, q1_, v1_);
;                 GLA_STEP(t, a0_, k0_, q0_, v0_);
;                 GLA_LD(t + 2 < TC ? t + 2 : t + 1, a0_, k0_, q0_, v0_);
;                 GLA_STEP(t + 1, a1_, k1_, q1_, v1_);
	v_mul_f32_e32 v26, v0, v26
	v_mul_f32_e32 v27, v1, v27
	v_mul_f32_e32 v28, v2, v28
	v_mul_f32_e32 v29, v3, v29
	v_mul_f32_e32 v30, v4, v30
	v_mul_f32_e32 v31, v5, v31
	v_mul_f32_e32 v32, v6, v32
	v_mul_f32_e32 v34, v7, v34
	v_add_f32_dpp v35, v35, v35 quad_perm:[2,3,0,1] row_mask:0xf bank_mask:0xf bound_ctrl:1
	ds_write_b32 v175, v35
	v_add_u32_e32 v175, v175, v162
	v_fmac_f32_e32 v26, v8, v33
	v_fmac_f32_e32 v27, v9, v33
	v_fmac_f32_e32 v28, v10, v33
	v_fmac_f32_e32 v29, v11, v33
	v_fmac_f32_e32 v30, v12, v33
	v_fmac_f32_e32 v31, v13, v33
	v_fmac_f32_e32 v32, v14, v33
	v_fmac_f32_e32 v34, v15, v33
	v_mul_f32_e32 v40, v16, v26
	v_mul_f32_e32 v41, v17, v27
	v_fmac_f32_e32 v40, v18, v28
	v_fmac_f32_e32 v41, v19, v29
	v_fmac_f32_e32 v40, v20, v30
	v_fmac_f32_e32 v41, v21, v31
	v_fmac_f32_e32 v40, v22, v32
	v_fmac_f32_e32 v41, v23, v34
	v_add_f32_e32 v35, v40, v41
	s_nop 1
	v_add_f32_dpp v35, v35, v35 quad_perm:[1,0,3,2] row_mask:0xf bank_mask:0xf bound_ctrl:1
	ds_read_b128 v[0:3], v174 offset:20736
	ds_read_b128 v[4:7], v174 offset:20752
	ds_read_b128 v[8:11], v174 offset:12544
	ds_read_b128 v[12:15], v174 offset:12560
	ds_read_b32 v33, v173 offset:33280
	ds_read_b128 v[16:19], v174 offset:4352
	ds_read_b128 v[20:23], v174 offset:4368
	s_waitcnt lgkmcnt(8)
	v_mul_f32_e32 v26, v176, v26
	v_mul_f32_e32 v27, v177, v27
	v_mul_f32_e32 v28, v178, v28
	v_mul_f32_e32 v29, v179, v29
	v_mul_f32_e32 v30, v180, v30
	v_mul_f32_e32 v31, v181, v31
	v_mul_f32_e32 v32, v182, v32
	v_mul_f32_e32 v34, v183, v34
	v_add_f32_dpp v35, v35, v35 quad_perm:[2,3,0,1] row_mask:0xf bank_mask:0xf bound_ctrl:1
	ds_write_b32 v175, v35
	v_add_u32_e32 v175, v175, v162
	v_fmac_f32_e32 v26, v184, v200
	v_fmac_f32_e32 v27, v185, v200
	v_fmac_f32_e32 v28, v186, v200
	v_fmac_f32_e32 v29, v187, v200
	v_fmac_f32_e32 v30, v188, v200
	v_fmac_f32_e32 v31, v189, v200
	v_fmac_f32_e32 v32, v190, v200
	v_fmac_f32_e32 v34, v191, v200
	v_mul_f32_e32 v40, v192, v26
	v_mul_f32_e32 v41, v193, v27
	v_fmac_f32_e32 v40, v194, v28
	v_fmac_f32_e32 v41, v195, v29
	v_fmac_f32_e32 v40, v196, v30
	v_fmac_f32_e32 v41, v197, v31
	v_fmac_f32_e32 v40, v198, v32
	v_fmac_f32_e32 v41, v199, v34
	v_add_f32_e32 v35, v40, v41
	s_nop 1
	v_add_f32_dpp v35, v35, v35 quad_perm:[1,0,3,2] row_mask:0xf bank_mask:0xf bound_ctrl:1
	ds_read_b128 v[176:179], v174 offset:20864
	ds_read_b128 v[180:183], v174 offset:20880
	ds_read_b128 v[184:187], v174 offset:12672
	ds_read_b128 v[188:191], v174 offset:12688
	ds_read_b32 v200, v173 offset:33536
	ds_read_b128 v[192:195], v174 offset:4480
	ds_read_b128 v[196:199], v174 offset:4496
	s_waitcnt lgkmcnt(8)
	v_mul_f32_e32 v26, v0, v26
	v_mul_f32_e32 v27, v1, v27
	v_mul_f32_e32 v28, v2, v28
	v_mul_f32_e32 v29, v3, v29
	v_mul_f32_e32 v30, v4, v30
	v_mul_f32_e32 v31, v5, v31
	v_mul_f32_e32 v32, v6, v32
	v_mul_f32_e32 v34, v7, v34
	v_add_f32_dpp v35, v35, v35 quad_perm:[2,3,0,1] row_mask:0xf bank_mask:0xf bound_ctrl:1
	ds_write_b32 v175, v35
	v_add_u32_e32 v175, v175, v162
	v_fmac_f32_e32 v26, v8, v33
	v_fmac_f32_e32 v27, v9, v33
	v_fmac_f32_e32 v28, v10, v33
	v_fmac_f32_e32 v29, v11, v33
	v_fmac_f32_e32 v30, v12, v33
	v_fmac_f32_e32 v31, v13, v33
	v_fmac_f32_e32 v32, v14, v33
	v_fmac_f32_e32 v34, v15, v33
	v_mul_f32_e32 v40, v16, v26
	v_mul_f32_e32 v41, v17, v27
	v_fmac_f32_e32 v40, v18, v28
	v_fmac_f32_e32 v41, v19, v29
	v_fmac_f32_e32 v40, v20, v30
	v_fmac_f32_e32 v41, v21, v31
	v_fmac_f32_e32 v40, v22, v32
	v_fmac_f32_e32 v41, v23, v34
	v_add_f32_e32 v35, v40, v41
	s_nop 1
	v_add_f32_dpp v35, v35, v35 quad_perm:[1,0,3,2] row_mask:0xf bank_mask:0xf bound_ctrl:1
	ds_read_b128 v[0:3], v174 offset:20992
	ds_read_b128 v[4:7], v174 offset:21008
	ds_read_b128 v[8:11], v174 offset:12800
	ds_read_b128 v[12:15], v174 offset:12816
	ds_read_b32 v33, v173 offset:33792
	ds_read_b128 v[16:19], v174 offset:4608
	ds_read_b128 v[20:23], v174 offset:4624
	s_waitcnt lgkmcnt(8)
	v_mul_f32_e32 v26, v176, v26
	v_mul_f32_e32 v27, v177, v27
	v_mul_f32_e32 v28, v178, v28
	v_mul_f32_e32 v29, v179, v29
	v_mul_f32_e32 v30, v180, v30
	v_mul_f32_e32 v31, v181, v31
	v_mul_f32_e32 v32, v182, v32
	v_mul_f32_e32 v34, v183, v34
	v_add_f32_dpp v35, v35, v35 quad_perm:[2,3,0,1] row_mask:0xf bank_mask:0xf bound_ctrl:1
	ds_write_b32 v175, v35
	v_add_u32_e32 v175, v175, v162
	v_fmac_f32_e32 v26, v184, v200
	v_fmac_f32_e32 v27, v185, v200
	v_fmac_f32_e32 v28, v186, v200
	v_fmac_f32_e32 v29, v187, v200
	v_fmac_f32_e32 v30, v188, v200
	v_fmac_f32_e32 v31, v189, v200
	v_fmac_f32_e32 v32, v190, v200
	v_fmac_f32_e32 v34, v191, v200
	v_mul_f32_e32 v40, v192, v26
	v_mul_f32_e32 v41, v193, v27
	v_fmac_f32_e32 v40, v194, v28
	v_fmac_f32_e32 v41, v195, v29
	v_fmac_f32_e32 v40, v196, v30
	v_fmac_f32_e32 v41, v197, v31
	v_fmac_f32_e32 v40, v198, v32
	v_fmac_f32_e32 v41, v199, v34
	v_add_f32_e32 v35, v40, v41
	s_nop 1
	v_add_f32_dpp v35, v35, v35 quad_perm:[1,0,3,2] row_mask:0xf bank_mask:0xf bound_ctrl:1
	ds_read_b128 v[176:179], v174 offset:21120
	ds_read_b128 v[180:183], v174 offset:21136
	ds_read_b128 v[184:187], v174 offset:12928
	ds_read_b128 v[188:191], v174 offset:12944
	ds_read_b32 v200, v173 offset:34048
	ds_read_b128 v[192:195], v174 offset:4736
	ds_read_b128 v[196:199], v174 offset:4752
	s_waitcnt lgkmcnt(8)
; #define GLA_LD(t_, aq, kq, qq, vq) do { const int tt_ = (t_); vq = Bs[6144 + tt_ * 64 + pp]; \
;             _Pragma("unroll") for (int u = 0; u < 2; ++u) { aq[u] = *(const LAS f32x4*)(Bs + 4096 + tt_ * 32 + k0 + 4 * u); kq[u] = *(const LAS f32x4*)(Bs + 2048 + tt_ * 32 + k0 + 4 * u); qq[u] = *(const LAS f32x4*)(Bs + tt_ * 32 + k0 + 4 * u); } } while (0)
; #define GLA_STEP(t_, aq, kq, qq, vq) do { float y = 0.f; \
;             _Pragma("unroll") for (int u = 0; u < 2; ++u) _Pragma("unroll") for (int j = 0; j < 4; ++j) { S[4 * u + j] = aq[u][j] * S[4 * u + j] + kq[u][j] * vq; y += qq[u][j] * S[4 * u + j]; } \
;             y += dpp_f(y, 0xB1); y += dpp_f(y, 0x4E); ydst[(t_) * ystride] = y; } while (0)
; __device__ __forceinline__ void gla_job(const bf16_t* P, bf16_t* Y, int l, int b, int h, LAS float* lds, int wave_s) {
;     ...
;             GLA_LD(0, a0_, k0_, q0_, v0_);
;             for (int t = 0; t < TC; t += 2) {
;                 GLA_LD(t + 1, a1_, k1_, q1_, v1_);
;                 GLA_STEP(t, a0_, k0_, q0_, v0_);
;                 GLA_LD(t + 2 < TC ? t + 2 : t + 1, a0_, k0_, q0_, v0_);
;                 GLA_STEP(t + 1, a1_, k1_, q1_, v1_);
;             }
	v_mul_f32_e32 v26, v0, v26
	v_mul_f32_e32 v27, v1, v27
	v_mul_f32_e32 v28, v2, v28
	v_mul_f32_e32 v29, v3, v29
	v_mul_f32_e32 v30, v4, v30
	v_mul_f32_e32 v31, v5, v31
	v_mul_f32_e32 v32, v6, v32
	v_mul_f32_e32 v34, v7, v34
	v_add_f32_dpp v35, v35, v35 quad_perm:[2,3,0,1] row_mask:0xf bank_mask:0xf bound_ctrl:1
	ds_write_b32 v175, v35
	v_add_u32_e32 v175, v175, v162
	v_fmac_f32_e32 v26, v8, v33
	v_fmac_f32_e32 v27, v9, v33
	v_fmac_f32_e32 v28, v10, v33
	v_fmac_f32_e32 v29, v11, v33
	v_fmac_f32_e32 v30, v12, v33
	v_fmac_f32_e32 v31, v13, v33
	v_fmac_f32_e32 v32, v14, v33
	v_fmac_f32_e32 v34, v15, v33
	v_mul_f32_e32 v40, v16, v26
	v_mul_f32_e32 v41, v17, v27
	v_fmac_f32_e32 v40, v18, v28
	v_fmac_f32_e32 v41, v19, v29
	v_fmac_f32_e32 v40, v20, v30
	v_fmac_f32_e32 v41, v21, v31
	v_fmac_f32_e32 v40, v22, v32
	v_fmac_f32_e32 v41, v23, v34
	v_add_f32_e32 v35, v40, v41
	s_nop 1
	v_add_f32_dpp v35, v35, v35 quad_perm:[1,0,3,2] row_mask:0xf bank_mask:0xf bound_ctrl:1
	ds_read_b128 v[0:3], v174 offset:21248
	ds_read_b128 v[4:7], v174 offset:21264
	ds_read_b128 v[8:11], v174 offset:13056
	ds_read_b128 v[12:15], v174 offset:13072
	ds_read_b32 v33, v173 offset:34304
	ds_read_b128 v[16:19], v174 offset:4864
	ds_read_b128 v[20:23], v174 offset:4880
	s_waitcnt lgkmcnt(8)
	v_mul_f32_e32 v26, v176, v26
	v_mul_f32_e32 v27, v177, v27
	v_mul_f32_e32 v28, v178, v28
	v_mul_f32_e32 v29, v179, v29
	v_mul_f32_e32 v30, v180, v30
	v_mul_f32_e32 v31, v181, v31
	v_mul_f32_e32 v32, v182, v32
	v_mul_f32_e32 v34, v183, v34
	v_add_f32_dpp v35, v35, v35 quad_perm:[2,3,0,1] row_mask:0xf bank_mask:0xf bound_ctrl:1
	ds_write_b32 v175, v35
	v_add_u32_e32 v175, v175, v162
	v_fmac_f32_e32 v26, v184, v200
	v_fmac_f32_e32 v27, v185, v200
	v_fmac_f32_e32 v28, v186, v200
	v_fmac_f32_e32 v29, v187, v200
	v_fmac_f32_e32 v30, v188, v200
	v_fmac_f32_e32 v31, v189, v200
	v_fmac_f32_e32 v32, v190, v200
	v_fmac_f32_e32 v34, v191, v200
	v_mul_f32_e32 v40, v192, v26
	v_mul_f32_e32 v41, v193, v27
	v_fmac_f32_e32 v40, v194, v28
	v_fmac_f32_e32 v41, v195, v29
	v_fmac_f32_e32 v40, v196, v30
	v_fmac_f32_e32 v41, v197, v31
	v_fmac_f32_e32 v40, v198, v32
	v_fmac_f32_e32 v41, v199, v34
	v_add_f32_e32 v35, v40, v41
	s_nop 1
	v_add_f32_dpp v35, v35, v35 quad_perm:[1,0,3,2] row_mask:0xf bank_mask:0xf bound_ctrl:1
	ds_read_b128 v[176:179], v174 offset:21376
	ds_read_b128 v[180:183], v174 offset:21392
	ds_read_b128 v[184:187], v174 offset:13184
	ds_read_b128 v[188:191], v174 offset:13200
	ds_read_b32 v200, v173 offset:34560
	ds_read_b128 v[192:195], v174 offset:4992
	ds_read_b128 v[196:199], v174 offset:5008
	s_waitcnt lgkmcnt(8)
	v_mul_f32_e32 v26, v0, v26
	v_mul_f32_e32 v27, v1, v27
	v_mul_f32_e32 v28, v2, v28
	v_mul_f32_e32 v29, v3, v29
	v_mul_f32_e32 v30, v4, v30
	v_mul_f32_e32 v31, v5, v31
	v_mul_f32_e32 v32, v6, v32
	v_mul_f32_e32 v34, v7, v34
	v_add_f32_dpp v35, v35, v35 quad_perm:[2,3,0,1] row_mask:0xf bank_mask:0xf bound_ctrl:1
	ds_write_b32 v175, v35
	v_add_u32_e32 v175, v175, v162
	v_fmac_f32_e32 v26, v8, v33
	v_fmac_f32_e32 v27, v9, v33
	v_fmac_f32_e32 v28, v10, v33
	v_fmac_f32_e32 v29, v11, v33
	v_fmac_f32_e32 v30, v12, v33
	v_fmac_f32_e32 v31, v13, v33
	v_fmac_f32_e32 v32, v14, v33
	v_fmac_f32_e32 v34, v15, v33
	v_mul_f32_e32 v40, v16, v26
	v_mul_f32_e32 v41, v17, v27
	v_fmac_f32_e32 v40, v18, v28
	v_fmac_f32_e32 v41, v19, v29
	v_fmac_f32_e32 v40, v20, v30
	v_fmac_f32_e32 v41, v21, v31
	v_fmac_f32_e32 v40, v22, v32
	v_fmac_f32_e32 v41, v23, v34
	v_add_f32_e32 v35, v40, v41
	s_nop 1
	v_add_f32_dpp v35, v35, v35 quad_perm:[1,0,3,2] row_mask:0xf bank_mask:0xf bound_ctrl:1
	ds_read_b128 v[0:3], v174 offset:21504
	ds_read_b128 v[4:7], v174 offset:21520
	ds_read_b128 v[8:11], v174 offset:13312
	ds_read_b128 v[12:15], v174 offset:13328
	ds_read_b32 v33, v173 offset:34816
	ds_read_b128 v[16:19], v174 offset:5120
	ds_read_b128 v[20:23], v174 offset:5136
	s_waitcnt lgkmcnt(8)
	v_mul_f32_e32 v26, v176, v26
	v_mul_f32_e32 v27, v177, v27
	v_mul_f32_e32 v28, v178, v28
	v_mul_f32_e32 v29, v179, v29
	v_mul_f32_e32 v30, v180, v30
	v_mul_f32_e32 v31, v181, v31
	v_mul_f32_e32 v32, v182, v32
	v_mul_f32_e32 v34, v183, v34
	v_add_f32_dpp v35, v35, v35 quad_perm:[2,3,0,1] row_mask:0xf bank_mask:0xf bound_ctrl:1
	ds_write_b32 v175, v35
	v_add_u32_e32 v175, v175, v162
	v_fmac_f32_e32 v26, v184, v200
	v_fmac_f32_e32 v27, v185, v200
	v_fmac_f32_e32 v28, v186, v200
	v_fmac_f32_e32 v29, v187, v200
	v_fmac_f32_e32 v30, v188, v200
	v_fmac_f32_e32 v31, v189, v200
	v_fmac_f32_e32 v32, v190, v200
	v_fmac_f32_e32 v34, v191, v200
	v_mul_f32_e32 v40, v192, v26
	v_mul_f32_e32 v41, v193, v27
	v_fmac_f32_e32 v40, v194, v28
	v_fmac_f32_e32 v41, v195, v29
	v_fmac_f32_e32 v40, v196, v30
	v_fmac_f32_e32 v41, v197, v31
	v_fmac_f32_e32 v40, v198, v32
	v_fmac_f32_e32 v41, v199, v34
	v_add_f32_e32 v35, v40, v41
	s_nop 1
	v_add_f32_dpp v35, v35, v35 quad_perm:[1,0,3,2] row_mask:0xf bank_mask:0xf bound_ctrl:1
	ds_read_b128 v[176:179], v174 offset:21632
	ds_read_b128 v[180:183], v174 offset:21648
	ds_read_b128 v[184:187], v174 offset:13440
	ds_read_b128 v[188:191], v174 offset:13456
	ds_read_b32 v200, v173 offset:35072
	ds_read_b128 v[192:195], v174 offset:5248
	ds_read_b128 v[196:199], v174 offset:5264
	s_waitcnt lgkmcnt(8)
; #define GLA_LD(t_, aq, kq, qq, vq) do { const int tt_ = (t_); vq = Bs[6144 + tt_ * 64 + pp]; \
;             _Pragma("unroll") for (int u = 0; u < 2; ++u) { aq[u] = *(const LAS f32x4*)(Bs + 4096 + tt_ * 32 + k0 + 4 * u); kq[u] = *(const LAS f32x4*)(Bs + 2048 + tt_ * 32 + k0 + 4 * u); qq[u] = *(const LAS f32x4*)(Bs + tt_ * 32 + k0 + 4 * u); } } while (0)
; #define GLA_STEP(t_, aq, kq, qq, vq) do { float y = 0.f; \
;             _Pragma("unroll") for (int u = 0; u < 2; ++u) _Pragma("unroll") for (int j = 0; j < 4; ++j) { S[4 * u + j] = aq[u][j] * S[4 * u + j] + kq[u][j] * vq; y += qq[u][j] * S[4 * u + j]; } \
;             y += dpp_f(y, 0xB1); y += dpp_f(y, 0x4E); ydst[(t_) * ystride] = y; } while (0)
; __device__ __forceinline__ void gla_job(const bf16_t* P, bf16_t* Y, int l, int b, int h, LAS float* lds, int wave_s) {
;     ...
;             GLA_LD(0, a0_, k0_, q0_, v0_);
;             for (int t = 0; t < TC; t += 2) {
;                 GLA_LD(t + 1, a1_, k1_, q1_, v1_);
;                 GLA_STEP(t, a0_, k0_, q0_, v0_);
;                 GLA_LD(t + 2 < TC ? t + 2 : t + 1, a0_, k0_, q0_, v0_);
;                 GLA_STEP(t + 1, a1_, k1_, q1_, v1_);
;             }
	v_mul_f32_e32 v26, v0, v26
	v_mul_f32_e32 v27, v1, v27
	v_mul_f32_e32 v28, v2, v28
	v_mul_f32_e32 v29, v3, v29
	v_mul_f32_e32 v30, v4, v30
	v_mul_f32_e32 v31, v5, v31
	v_mul_f32_e32 v32, v6, v32
	v_mul_f32_e32 v34, v7, v34
	v_add_f32_dpp v35, v35, v35 quad_perm:[2,3,0,1] row_mask:0xf bank_mask:0xf bound_ctrl:1
	ds_write_b32 v175, v35
	v_add_u32_e32 v175, v175, v162
	v_fmac_f32_e32 v26, v8, v33
	v_fmac_f32_e32 v27, v9, v33
	v_fmac_f32_e32 v28, v10, v33
	v_fmac_f32_e32 v29, v11, v33
	v_fmac_f32_e32 v30, v12, v33
	v_fmac_f32_e32 v31, v13, v33
	v_fmac_f32_e32 v32, v14, v33
	v_fmac_f32_e32 v34, v15, v33
	v_mul_f32_e32 v40, v16, v26
	v_mul_f32_e32 v41, v17, v27
	v_fmac_f32_e32 v40, v18, v28
	v_fmac_f32_e32 v41, v19, v29
	v_fmac_f32_e32 v40, v20, v30
	v_fmac_f32_e32 v41, v21, v31
	v_fmac_f32_e32 v40, v22, v32
	v_fmac_f32_e32 v41, v23, v34
	v_add_f32_e32 v35, v40, v41
	s_nop 1
	v_add_f32_dpp v35, v35, v35 quad_perm:[1,0,3,2] row_mask:0xf bank_mask:0xf bound_ctrl:1
	ds_read_b128 v[0:3], v174 offset:21760
	ds_read_b128 v[4:7], v174 offset:21776
	ds_read_b128 v[8:11], v174 offset:13568
	ds_read_b128 v[12:15], v174 offset:13584
	ds_read_b32 v33, v173 offset:35328
	ds_read_b128 v[16:19], v174 offset:5376
	ds_read_b128 v[20:23], v174 offset:5392
	s_waitcnt lgkmcnt(8)
	v_mul_f32_e32 v26, v176, v26
	v_mul_f32_e32 v27, v177, v27
	v_mul_f32_e32 v28, v178, v28
	v_mul_f32_e32 v29, v179, v29
	v_mul_f32_e32 v30, v180, v30
	v_mul_f32_e32 v31, v181, v31
	v_mul_f32_e32 v32, v182, v32
	v_mul_f32_e32 v34, v183, v34
	v_add_f32_dpp v35, v35, v35 quad_perm:[2,3,0,1] row_mask:0xf bank_mask:0xf bound_ctrl:1
	ds_write_b32 v175, v35
	v_add_u32_e32 v175, v175, v162
	v_fmac_f32_e32 v26, v184, v200
	v_fmac_f32_e32 v27, v185, v200
	v_fmac_f32_e32 v28, v186, v200
	v_fmac_f32_e32 v29, v187, v200
	v_fmac_f32_e32 v30, v188, v200
	v_fmac_f32_e32 v31, v189, v200
	v_fmac_f32_e32 v32, v190, v200
	v_fmac_f32_e32 v34, v191, v200
	v_mul_f32_e32 v40, v192, v26
	v_mul_f32_e32 v41, v193, v27
	v_fmac_f32_e32 v40, v194, v28
	v_fmac_f32_e32 v41, v195, v29
	v_fmac_f32_e32 v40, v196, v30
	v_fmac_f32_e32 v41, v197, v31
	v_fmac_f32_e32 v40, v198, v32
	v_fmac_f32_e32 v41, v199, v34
	v_add_f32_e32 v35, v40, v41
	s_nop 1
	v_add_f32_dpp v35, v35, v35 quad_perm:[1,0,3,2] row_mask:0xf bank_mask:0xf bound_ctrl:1
	ds_read_b128 v[176:179], v174 offset:21888
	ds_read_b128 v[180:183], v174 offset:21904
	ds_read_b128 v[184:187], v174 offset:13696
	ds_read_b128 v[188:191], v174 offset:13712
	ds_read_b32 v200, v173 offset:35584
	ds_read_b128 v[192:195], v174 offset:5504
	ds_read_b128 v[196:199], v174 offset:5520
	s_waitcnt lgkmcnt(8)
	v_mul_f32_e32 v26, v0, v26
	v_mul_f32_e32 v27, v1, v27
	v_mul_f32_e32 v28, v2, v28
	v_mul_f32_e32 v29, v3, v29
	v_mul_f32_e32 v30, v4, v30
	v_mul_f32_e32 v31, v5, v31
	v_mul_f32_e32 v32, v6, v32
	v_mul_f32_e32 v34, v7, v34
	v_add_f32_dpp v35, v35, v35 quad_perm:[2,3,0,1] row_mask:0xf bank_mask:0xf bound_ctrl:1
	ds_write_b32 v175, v35
	v_add_u32_e32 v175, v175, v162
	v_fmac_f32_e32 v26, v8, v33
	v_fmac_f32_e32 v27, v9, v33
	v_fmac_f32_e32 v28, v10, v33
	v_fmac_f32_e32 v29, v11, v33
	v_fmac_f32_e32 v30, v12, v33
	v_fmac_f32_e32 v31, v13, v33
	v_fmac_f32_e32 v32, v14, v33
	v_fmac_f32_e32 v34, v15, v33
	v_mul_f32_e32 v40, v16, v26
	v_mul_f32_e32 v41, v17, v27
	v_fmac_f32_e32 v40, v18, v28
	v_fmac_f32_e32 v41, v19, v29
	v_fmac_f32_e32 v40, v20, v30
	v_fmac_f32_e32 v41, v21, v31
	v_fmac_f32_e32 v40, v22, v32
	v_fmac_f32_e32 v41, v23, v34
	v_add_f32_e32 v35, v40, v41
	s_nop 1
	v_add_f32_dpp v35, v35, v35 quad_perm:[1,0,3,2] row_mask:0xf bank_mask:0xf bound_ctrl:1
	ds_read_b128 v[0:3], v174 offset:22016
	ds_read_b128 v[4:7], v174 offset:22032
	ds_read_b128 v[8:11], v174 offset:13824
	ds_read_b128 v[12:15], v174 offset:13840
	ds_read_b32 v33, v173 offset:35840
	ds_read_b128 v[16:19], v174 offset:5632
	ds_read_b128 v[20:23], v174 offset:5648
	s_waitcnt lgkmcnt(8)
	v_mul_f32_e32 v26, v176, v26
	v_mul_f32_e32 v27, v177, v27
	v_mul_f32_e32 v28, v178, v28
	v_mul_f32_e32 v29, v179, v29
	v_mul_f32_e32 v30, v180, v30
	v_mul_f32_e32 v31, v181, v31
	v_mul_f32_e32 v32, v182, v32
	v_mul_f32_e32 v34, v183, v34
	v_add_f32_dpp v35, v35, v35 quad_perm:[2,3,0,1] row_mask:0xf bank_mask:0xf bound_ctrl:1
	ds_write_b32 v175, v35
	v_add_u32_e32 v175, v175, v162
	v_fmac_f32_e32 v26, v184, v200
	v_fmac_f32_e32 v27, v185, v200
	v_fmac_f32_e32 v28, v186, v200
	v_fmac_f32_e32 v29, v187, v200
	v_fmac_f32_e32 v30, v188, v200
	v_fmac_f32_e32 v31, v189, v200
	v_fmac_f32_e32 v32, v190, v200
	v_fmac_f32_e32 v34, v191, v200
	v_mul_f32_e32 v40, v192, v26
	v_mul_f32_e32 v41, v193, v27
	v_fmac_f32_e32 v40, v194, v28
	v_fmac_f32_e32 v41, v195, v29
	v_fmac_f32_e32 v40, v196, v30
	v_fmac_f32_e32 v41, v197, v31
	v_fmac_f32_e32 v40, v198, v32
	v_fmac_f32_e32 v41, v199, v34
	v_add_f32_e32 v35, v40, v41
	s_nop 1
	v_add_f32_dpp v35, v35, v35 quad_perm:[1,0,3,2] row_mask:0xf bank_mask:0xf bound_ctrl:1
	ds_read_b128 v[176:179], v174 offset:22144
	ds_read_b128 v[180:183], v174 offset:22160
	ds_read_b128 v[184:187], v174 offset:13952
	ds_read_b128 v[188:191], v174 offset:13968
	ds_read_b32 v200, v173 offset:36096
	ds_read_b128 v[192:195], v174 offset:5760
	ds_read_b128 v[196:199], v174 offset:5776
	s_waitcnt lgkmcnt(8)
; #define GLA_LD(t_, aq, kq, qq, vq) do { const int tt_ = (t_); vq = Bs[6144 + tt_ * 64 + pp]; \
;             _Pragma("unroll") for (int u = 0; u < 2; ++u) { aq[u] = *(const LAS f32x4*)(Bs + 4096 + tt_ * 32 + k0 + 4 * u); kq[u] = *(const LAS f32x4*)(Bs + 2048 + tt_ * 32 + k0 + 4 * u); qq[u] = *(const LAS f32x4*)(Bs + tt_ * 32 + k0 + 4 * u); } } while (0)
; #define GLA_STEP(t_, aq, kq, qq, vq) do { float y = 0.f; \
;             _Pragma("unroll") for (int u = 0; u < 2; ++u) _Pragma("unroll") for (int j = 0; j < 4; ++j) { S[4 * u + j] = aq[u][j] * S[4 * u + j] + kq[u][j] * vq; y += qq[u][j] * S[4 * u + j]; } \
;             y += dpp_f(y, 0xB1); y += dpp_f(y, 0x4E); ydst[(t_) * ystride] = y; } while (0)
; __device__ __forceinline__ void gla_job(const bf16_t* P, bf16_t* Y, int l, int b, int h, LAS float* lds, int wave_s) {
;     ...
;             GLA_LD(0, a0_, k0_, q0_, v0_);
;             for (int t = 0; t < TC; t += 2) {
;                 GLA_LD(t + 1, a1_, k1_, q1_, v1_);
;                 GLA_STEP(t, a0_, k0_, q0_, v0_);
;                 GLA_LD(t + 2 < TC ? t + 2 : t + 1, a0_, k0_, q0_, v0_);
;                 GLA_STEP(t + 1, a1_, k1_, q1_, v1_);
;             }
	v_mul_f32_e32 v26, v0, v26
	v_mul_f32_e32 v27, v1, v27
	v_mul_f32_e32 v28, v2, v28
	v_mul_f32_e32 v29, v3, v29
	v_mul_f32_e32 v30, v4, v30
	v_mul_f32_e32 v31, v5, v31
	v_mul_f32_e32 v32, v6, v32
	v_mul_f32_e32 v34, v7, v34
	v_add_f32_dpp v35, v35, v35 quad_perm:[2,3,0,1] row_mask:0xf bank_mask:0xf bound_ctrl:1
	ds_write_b32 v175, v35
	v_add_u32_e32 v175, v175, v162
	v_fmac_f32_e32 v26, v8, v33
	v_fmac_f32_e32 v27, v9, v33
	v_fmac_f32_e32 v28, v10, v33
	v_fmac_f32_e32 v29, v11, v33
	v_fmac_f32_e32 v30, v12, v33
	v_fmac_f32_e32 v31, v13, v33
	v_fmac_f32_e32 v32, v14, v33
	v_fmac_f32_e32 v34, v15, v33
	v_mul_f32_e32 v40, v16, v26
	v_mul_f32_e32 v41, v17, v27
	v_fmac_f32_e32 v40, v18, v28
	v_fmac_f32_e32 v41, v19, v29
	v_fmac_f32_e32 v40, v20, v30
	v_fmac_f32_e32 v41, v21, v31
	v_fmac_f32_e32 v40, v22, v32
	v_fmac_f32_e32 v41, v23, v34
	v_add_f32_e32 v35, v40, v41
	s_nop 1
	v_add_f32_dpp v35, v35, v35 quad_perm:[1,0,3,2] row_mask:0xf bank_mask:0xf bound_ctrl:1
	ds_read_b128 v[0:3], v174 offset:22272
	ds_read_b128 v[4:7], v174 offset:22288
	ds_read_b128 v[8:11], v174 offset:14080
	ds_read_b128 v[12:15], v174 offset:14096
	ds_read_b32 v33, v173 offset:36352
	ds_read_b128 v[16:19], v174 offset:5888
	ds_read_b128 v[20:23], v174 offset:5904
	s_waitcnt lgkmcnt(8)
	v_mul_f32_e32 v26, v176, v26
	v_mul_f32_e32 v27, v177, v27
	v_mul_f32_e32 v28, v178, v28
	v_mul_f32_e32 v29, v179, v29
	v_mul_f32_e32 v30, v180, v30
	v_mul_f32_e32 v31, v181, v31
	v_mul_f32_e32 v32, v182, v32
	v_mul_f32_e32 v34, v183, v34
	v_add_f32_dpp v35, v35, v35 quad_perm:[2,3,0,1] row_mask:0xf bank_mask:0xf bound_ctrl:1
	ds_write_b32 v175, v35
	v_add_u32_e32 v175, v175, v162
	v_fmac_f32_e32 v26, v184, v200
	v_fmac_f32_e32 v27, v185, v200
	v_fmac_f32_e32 v28, v186, v200
	v_fmac_f32_e32 v29, v187, v200
	v_fmac_f32_e32 v30, v188, v200
	v_fmac_f32_e32 v31, v189, v200
	v_fmac_f32_e32 v32, v190, v200
	v_fmac_f32_e32 v34, v191, v200
	v_mul_f32_e32 v40, v192, v26
	v_mul_f32_e32 v41, v193, v27
	v_fmac_f32_e32 v40, v194, v28
	v_fmac_f32_e32 v41, v195, v29
	v_fmac_f32_e32 v40, v196, v30
	v_fmac_f32_e32 v41, v197, v31
	v_fmac_f32_e32 v40, v198, v32
	v_fmac_f32_e32 v41, v199, v34
	v_add_f32_e32 v35, v40, v41
	s_nop 1
	v_add_f32_dpp v35, v35, v35 quad_perm:[1,0,3,2] row_mask:0xf bank_mask:0xf bound_ctrl:1
	ds_read_b128 v[176:179], v174 offset:22400
	ds_read_b128 v[180:183], v174 offset:22416
	ds_read_b128 v[184:187], v174 offset:14208
	ds_read_b128 v[188:191], v174 offset:14224
	ds_read_b32 v200, v173 offset:36608
	ds_read_b128 v[192:195], v174 offset:6016
	ds_read_b128 v[196:199], v174 offset:6032
	s_waitcnt lgkmcnt(8)
	v_mul_f32_e32 v26, v0, v26
	v_mul_f32_e32 v27, v1, v27
	v_mul_f32_e32 v28, v2, v28
	v_mul_f32_e32 v29, v3, v29
	v_mul_f32_e32 v30, v4, v30
	v_mul_f32_e32 v31, v5, v31
	v_mul_f32_e32 v32, v6, v32
	v_mul_f32_e32 v34, v7, v34
	v_add_f32_dpp v35, v35, v35 quad_perm:[2,3,0,1] row_mask:0xf bank_mask:0xf bound_ctrl:1
	ds_write_b32 v175, v35
	v_add_u32_e32 v175, v175, v162
	v_fmac_f32_e32 v26, v8, v33
	v_fmac_f32_e32 v27, v9, v33
	v_fmac_f32_e32 v28, v10, v33
	v_fmac_f32_e32 v29, v11, v33
	v_fmac_f32_e32 v30, v12, v33
	v_fmac_f32_e32 v31, v13, v33
	v_fmac_f32_e32 v32, v14, v33
	v_fmac_f32_e32 v34, v15, v33
	v_mul_f32_e32 v40, v16, v26
	v_mul_f32_e32 v41, v17, v27
	v_fmac_f32_e32 v40, v18, v28
	v_fmac_f32_e32 v41, v19, v29
	v_fmac_f32_e32 v40, v20, v30
	v_fmac_f32_e32 v41, v21, v31
	v_fmac_f32_e32 v40, v22, v32
	v_fmac_f32_e32 v41, v23, v34
	v_add_f32_e32 v35, v40, v41
	s_nop 1
	v_add_f32_dpp v35, v35, v35 quad_perm:[1,0,3,2] row_mask:0xf bank_mask:0xf bound_ctrl:1
	ds_read_b128 v[0:3], v174 offset:22528
	ds_read_b128 v[4:7], v174 offset:22544
	ds_read_b128 v[8:11], v174 offset:14336
	ds_read_b128 v[12:15], v174 offset:14352
	ds_read_b32 v33, v173 offset:36864
	ds_read_b128 v[16:19], v174 offset:6144
	ds_read_b128 v[20:23], v174 offset:6160
	s_waitcnt lgkmcnt(8)
	v_mul_f32_e32 v26, v176, v26
	v_mul_f32_e32 v27, v177, v27
	v_mul_f32_e32 v28, v178, v28
	v_mul_f32_e32 v29, v179, v29
	v_mul_f32_e32 v30, v180, v30
	v_mul_f32_e32 v31, v181, v31
	v_mul_f32_e32 v32, v182, v32
	v_mul_f32_e32 v34, v183, v34
	v_add_f32_dpp v35, v35, v35 quad_perm:[2,3,0,1] row_mask:0xf bank_mask:0xf bound_ctrl:1
	ds_write_b32 v175, v35
	v_add_u32_e32 v175, v175, v162
	v_fmac_f32_e32 v26, v184, v200
	v_fmac_f32_e32 v27, v185, v200
	v_fmac_f32_e32 v28, v186, v200
	v_fmac_f32_e32 v29, v187, v200
	v_fmac_f32_e32 v30, v188, v200
	v_fmac_f32_e32 v31, v189, v200
	v_fmac_f32_e32 v32, v190, v200
	v_fmac_f32_e32 v34, v191, v200
	v_mul_f32_e32 v40, v192, v26
	v_mul_f32_e32 v41, v193, v27
	v_fmac_f32_e32 v40, v194, v28
	v_fmac_f32_e32 v41, v195, v29
	v_fmac_f32_e32 v40, v196, v30
	v_fmac_f32_e32 v41, v197, v31
	v_fmac_f32_e32 v40, v198, v32
	v_fmac_f32_e32 v41, v199, v34
	v_add_f32_e32 v35, v40, v41
	s_nop 1
	v_add_f32_dpp v35, v35, v35 quad_perm:[1,0,3,2] row_mask:0xf bank_mask:0xf bound_ctrl:1
	ds_read_b128 v[176:179], v174 offset:22656
	ds_read_b128 v[180:183], v174 offset:22672
	ds_read_b128 v[184:187], v174 offset:14464
	ds_read_b128 v[188:191], v174 offset:14480
	ds_read_b32 v200, v173 offset:37120
	ds_read_b128 v[192:195], v174 offset:6272
	ds_read_b128 v[196:199], v174 offset:6288
	s_waitcnt lgkmcnt(8)
; #define GLA_LD(t_, aq, kq, qq, vq) do { const int tt_ = (t_); vq = Bs[6144 + tt_ * 64 + pp]; \
;             _Pragma("unroll") for (int u = 0; u < 2; ++u) { aq[u] = *(const LAS f32x4*)(Bs + 4096 + tt_ * 32 + k0 + 4 * u); kq[u] = *(const LAS f32x4*)(Bs + 2048 + tt_ * 32 + k0 + 4 * u); qq[u] = *(const LAS f32x4*)(Bs + tt_ * 32 + k0 + 4 * u); } } while (0)
; #define GLA_STEP(t_, aq, kq, qq, vq) do { float y = 0.f; \
;             _Pragma("unroll") for (int u = 0; u < 2; ++u) _Pragma("unroll") for (int j = 0; j < 4; ++j) { S[4 * u + j] = aq[u][j] * S[4 * u + j] + kq[u][j] * vq; y += qq[u][j] * S[4 * u + j]; } \
;             y += dpp_f(y, 0xB1); y += dpp_f(y, 0x4E); ydst[(t_) * ystride] = y; } while (0)
; __device__ __forceinline__ void gla_job(const bf16_t* P, bf16_t* Y, int l, int b, int h, LAS float* lds, int wave_s) {
;     ...
;             GLA_LD(0, a0_, k0_, q0_, v0_);
;             for (int t = 0; t < TC; t += 2) {
;                 GLA_LD(t + 1, a1_, k1_, q1_, v1_);
;                 GLA_STEP(t, a0_, k0_, q0_, v0_);
;                 GLA_LD(t + 2 < TC ? t + 2 : t + 1, a0_, k0_, q0_, v0_);
;                 GLA_STEP(t + 1, a1_, k1_, q1_, v1_);
;             }
	v_mul_f32_e32 v26, v0, v26
	v_mul_f32_e32 v27, v1, v27
	v_mul_f32_e32 v28, v2, v28
	v_mul_f32_e32 v29, v3, v29
	v_mul_f32_e32 v30, v4, v30
	v_mul_f32_e32 v31, v5, v31
	v_mul_f32_e32 v32, v6, v32
	v_mul_f32_e32 v34, v7, v34
	v_add_f32_dpp v35, v35, v35 quad_perm:[2,3,0,1] row_mask:0xf bank_mask:0xf bound_ctrl:1
	ds_write_b32 v175, v35
	v_add_u32_e32 v175, v175, v162
	v_fmac_f32_e32 v26, v8, v33
	v_fmac_f32_e32 v27, v9, v33
	v_fmac_f32_e32 v28, v10, v33
	v_fmac_f32_e32 v29, v11, v33
	v_fmac_f32_e32 v30, v12, v33
	v_fmac_f32_e32 v31, v13, v33
	v_fmac_f32_e32 v32, v14, v33
	v_fmac_f32_e32 v34, v15, v33
	v_mul_f32_e32 v40, v16, v26
	v_mul_f32_e32 v41, v17, v27
	v_fmac_f32_e32 v40, v18, v28
	v_fmac_f32_e32 v41, v19, v29
	v_fmac_f32_e32 v40, v20, v30
	v_fmac_f32_e32 v41, v21, v31
	v_fmac_f32_e32 v40, v22, v32
	v_fmac_f32_e32 v41, v23, v34
	v_add_f32_e32 v35, v40, v41
	s_nop 1
	v_add_f32_dpp v35, v35, v35 quad_perm:[1,0,3,2] row_mask:0xf bank_mask:0xf bound_ctrl:1
	ds_read_b128 v[0:3], v174 offset:22784
	ds_read_b128 v[4:7], v174 offset:22800
	ds_read_b128 v[8:11], v174 offset:14592
	ds_read_b128 v[12:15], v174 offset:14608
	ds_read_b32 v33, v173 offset:37376
	ds_read_b128 v[16:19], v174 offset:6400
	ds_read_b128 v[20:23], v174 offset:6416
	s_waitcnt lgkmcnt(8)
	v_mul_f32_e32 v26, v176, v26
	v_mul_f32_e32 v27, v177, v27
	v_mul_f32_e32 v28, v178, v28
	v_mul_f32_e32 v29, v179, v29
	v_mul_f32_e32 v30, v180, v30
	v_mul_f32_e32 v31, v181, v31
	v_mul_f32_e32 v32, v182, v32
	v_mul_f32_e32 v34, v183, v34
	v_add_f32_dpp v35, v35, v35 quad_perm:[2,3,0,1] row_mask:0xf bank_mask:0xf bound_ctrl:1
	ds_write_b32 v175, v35
	v_add_u32_e32 v175, v175, v162
	v_fmac_f32_e32 v26, v184, v200
	v_fmac_f32_e32 v27, v185, v200
	v_fmac_f32_e32 v28, v186, v200
	v_fmac_f32_e32 v29, v187, v200
	v_fmac_f32_e32 v30, v188, v200
	v_fmac_f32_e32 v31, v189, v200
	v_fmac_f32_e32 v32, v190, v200
	v_fmac_f32_e32 v34, v191, v200
	v_mul_f32_e32 v40, v192, v26
	v_mul_f32_e32 v41, v193, v27
	v_fmac_f32_e32 v40, v194, v28
	v_fmac_f32_e32 v41, v195, v29
	v_fmac_f32_e32 v40, v196, v30
	v_fmac_f32_e32 v41, v197, v31
	v_fmac_f32_e32 v40, v198, v32
	v_fmac_f32_e32 v41, v199, v34
	v_add_f32_e32 v35, v40, v41
	s_nop 1
	v_add_f32_dpp v35, v35, v35 quad_perm:[1,0,3,2] row_mask:0xf bank_mask:0xf bound_ctrl:1
	ds_read_b128 v[176:179], v174 offset:22912
	ds_read_b128 v[180:183], v174 offset:22928
	ds_read_b128 v[184:187], v174 offset:14720
	ds_read_b128 v[188:191], v174 offset:14736
	ds_read_b32 v200, v173 offset:37632
	ds_read_b128 v[192:195], v174 offset:6528
	ds_read_b128 v[196:199], v174 offset:6544
	s_waitcnt lgkmcnt(8)
	v_mul_f32_e32 v26, v0, v26
	v_mul_f32_e32 v27, v1, v27
	v_mul_f32_e32 v28, v2, v28
	v_mul_f32_e32 v29, v3, v29
	v_mul_f32_e32 v30, v4, v30
	v_mul_f32_e32 v31, v5, v31
	v_mul_f32_e32 v32, v6, v32
	v_mul_f32_e32 v34, v7, v34
	v_add_f32_dpp v35, v35, v35 quad_perm:[2,3,0,1] row_mask:0xf bank_mask:0xf bound_ctrl:1
	ds_write_b32 v175, v35
	v_add_u32_e32 v175, v175, v162
	v_fmac_f32_e32 v26, v8, v33
	v_fmac_f32_e32 v27, v9, v33
	v_fmac_f32_e32 v28, v10, v33
	v_fmac_f32_e32 v29, v11, v33
	v_fmac_f32_e32 v30, v12, v33
	v_fmac_f32_e32 v31, v13, v33
	v_fmac_f32_e32 v32, v14, v33
	v_fmac_f32_e32 v34, v15, v33
	v_mul_f32_e32 v40, v16, v26
	v_mul_f32_e32 v41, v17, v27
	v_fmac_f32_e32 v40, v18, v28
	v_fmac_f32_e32 v41, v19, v29
	v_fmac_f32_e32 v40, v20, v30
	v_fmac_f32_e32 v41, v21, v31
	v_fmac_f32_e32 v40, v22, v32
	v_fmac_f32_e32 v41, v23, v34
	v_add_f32_e32 v35, v40, v41
	s_nop 1
	v_add_f32_dpp v35, v35, v35 quad_perm:[1,0,3,2] row_mask:0xf bank_mask:0xf bound_ctrl:1
	ds_read_b128 v[0:3], v174 offset:23040
	ds_read_b128 v[4:7], v174 offset:23056
	ds_read_b128 v[8:11], v174 offset:14848
	ds_read_b128 v[12:15], v174 offset:14864
	ds_read_b32 v33, v173 offset:37888
	ds_read_b128 v[16:19], v174 offset:6656
	ds_read_b128 v[20:23], v174 offset:6672
	s_waitcnt lgkmcnt(8)
	v_mul_f32_e32 v26, v176, v26
	v_mul_f32_e32 v27, v177, v27
	v_mul_f32_e32 v28, v178, v28
	v_mul_f32_e32 v29, v179, v29
	v_mul_f32_e32 v30, v180, v30
	v_mul_f32_e32 v31, v181, v31
	v_mul_f32_e32 v32, v182, v32
	v_mul_f32_e32 v34, v183, v34
	v_add_f32_dpp v35, v35, v35 quad_perm:[2,3,0,1] row_mask:0xf bank_mask:0xf bound_ctrl:1
	ds_write_b32 v175, v35
	v_add_u32_e32 v175, v175, v162
	v_fmac_f32_e32 v26, v184, v200
	v_fmac_f32_e32 v27, v185, v200
	v_fmac_f32_e32 v28, v186, v200
	v_fmac_f32_e32 v29, v187, v200
	v_fmac_f32_e32 v30, v188, v200
	v_fmac_f32_e32 v31, v189, v200
	v_fmac_f32_e32 v32, v190, v200
	v_fmac_f32_e32 v34, v191, v200
	v_mul_f32_e32 v40, v192, v26
	v_mul_f32_e32 v41, v193, v27
	v_fmac_f32_e32 v40, v194, v28
	v_fmac_f32_e32 v41, v195, v29
	v_fmac_f32_e32 v40, v196, v30
	v_fmac_f32_e32 v41, v197, v31
	v_fmac_f32_e32 v40, v198, v32
	v_fmac_f32_e32 v41, v199, v34
	v_add_f32_e32 v35, v40, v41
	s_nop 1
	v_add_f32_dpp v35, v35, v35 quad_perm:[1,0,3,2] row_mask:0xf bank_mask:0xf bound_ctrl:1
	ds_read_b128 v[176:179], v174 offset:23168
	ds_read_b128 v[180:183], v174 offset:23184
	ds_read_b128 v[184:187], v174 offset:14976
	ds_read_b128 v[188:191], v174 offset:14992
	ds_read_b32 v200, v173 offset:38144
	ds_read_b128 v[192:195], v174 offset:6784
	ds_read_b128 v[196:199], v174 offset:6800
	s_waitcnt lgkmcnt(8)
; #define GLA_LD(t_, aq, kq, qq, vq) do { const int tt_ = (t_); vq = Bs[6144 + tt_ * 64 + pp]; \
;             _Pragma("unroll") for (int u = 0; u < 2; ++u) { aq[u] = *(const LAS f32x4*)(Bs + 4096 + tt_ * 32 + k0 + 4 * u); kq[u] = *(const LAS f32x4*)(Bs + 2048 + tt_ * 32 + k0 + 4 * u); qq[u] = *(const LAS f32x4*)(Bs + tt_ * 32 + k0 + 4 * u); } } while (0)
; #define GLA_STEP(t_, aq, kq, qq, vq) do { float y = 0.f; \
;             _Pragma("unroll") for (int u = 0; u < 2; ++u) _Pragma("unroll") for (int j = 0; j < 4; ++j) { S[4 * u + j] = aq[u][j] * S[4 * u + j] + kq[u][j] * vq; y += qq[u][j] * S[4 * u + j]; } \
;             y += dpp_f(y, 0xB1); y += dpp_f(y, 0x4E); ydst[(t_) * ystride] = y; } while (0)
; __device__ __forceinline__ void gla_job(const bf16_t* P, bf16_t* Y, int l, int b, int h, LAS float* lds, int wave_s) {
;     ...
;             GLA_LD(0, a0_, k0_, q0_, v0_);
;             for (int t = 0; t < TC; t += 2) {
;                 GLA_LD(t + 1, a1_, k1_, q1_, v1_);
;                 GLA_STEP(t, a0_, k0_, q0_, v0_);
;                 GLA_LD(t + 2 < TC ? t + 2 : t + 1, a0_, k0_, q0_, v0_);
;                 GLA_STEP(t + 1, a1_, k1_, q1_, v1_);
;             }
	v_mul_f32_e32 v26, v0, v26
	v_mul_f32_e32 v27, v1, v27
	v_mul_f32_e32 v28, v2, v28
	v_mul_f32_e32 v29, v3, v29
	v_mul_f32_e32 v30, v4, v30
	v_mul_f32_e32 v31, v5, v31
	v_mul_f32_e32 v32, v6, v32
	v_mul_f32_e32 v34, v7, v34
	v_add_f32_dpp v35, v35, v35 quad_perm:[2,3,0,1] row_mask:0xf bank_mask:0xf bound_ctrl:1
	ds_write_b32 v175, v35
	v_add_u32_e32 v175, v175, v162
	v_fmac_f32_e32 v26, v8, v33
	v_fmac_f32_e32 v27, v9, v33
	v_fmac_f32_e32 v28, v10, v33
	v_fmac_f32_e32 v29, v11, v33
	v_fmac_f32_e32 v30, v12, v33
	v_fmac_f32_e32 v31, v13, v33
	v_fmac_f32_e32 v32, v14, v33
	v_fmac_f32_e32 v34, v15, v33
	v_mul_f32_e32 v40, v16, v26
	v_mul_f32_e32 v41, v17, v27
	v_fmac_f32_e32 v40, v18, v28
	v_fmac_f32_e32 v41, v19, v29
	v_fmac_f32_e32 v40, v20, v30
	v_fmac_f32_e32 v41, v21, v31
	v_fmac_f32_e32 v40, v22, v32
	v_fmac_f32_e32 v41, v23, v34
	v_add_f32_e32 v35, v40, v41
	s_nop 1
	v_add_f32_dpp v35, v35, v35 quad_perm:[1,0,3,2] row_mask:0xf bank_mask:0xf bound_ctrl:1
	ds_read_b128 v[0:3], v174 offset:23296
	ds_read_b128 v[4:7], v174 offset:23312
	ds_read_b128 v[8:11], v174 offset:15104
	ds_read_b128 v[12:15], v174 offset:15120
	ds_read_b32 v33, v173 offset:38400
	ds_read_b128 v[16:19], v174 offset:6912
	ds_read_b128 v[20:23], v174 offset:6928
	s_waitcnt lgkmcnt(8)
	v_mul_f32_e32 v26, v176, v26
	v_mul_f32_e32 v27, v177, v27
	v_mul_f32_e32 v28, v178, v28
	v_mul_f32_e32 v29, v179, v29
	v_mul_f32_e32 v30, v180, v30
	v_mul_f32_e32 v31, v181, v31
	v_mul_f32_e32 v32, v182, v32
	v_mul_f32_e32 v34, v183, v34
	v_add_f32_dpp v35, v35, v35 quad_perm:[2,3,0,1] row_mask:0xf bank_mask:0xf bound_ctrl:1
	ds_write_b32 v175, v35
	v_add_u32_e32 v175, v175, v162
	v_fmac_f32_e32 v26, v184, v200
	v_fmac_f32_e32 v27, v185, v200
	v_fmac_f32_e32 v28, v186, v200
	v_fmac_f32_e32 v29, v187, v200
	v_fmac_f32_e32 v30, v188, v200
	v_fmac_f32_e32 v31, v189, v200
	v_fmac_f32_e32 v32, v190, v200
	v_fmac_f32_e32 v34, v191, v200
	v_mul_f32_e32 v40, v192, v26
	v_mul_f32_e32 v41, v193, v27
	v_fmac_f32_e32 v40, v194, v28
	v_fmac_f32_e32 v41, v195, v29
	v_fmac_f32_e32 v40, v196, v30
	v_fmac_f32_e32 v41, v197, v31
	v_fmac_f32_e32 v40, v198, v32
	v_fmac_f32_e32 v41, v199, v34
	v_add_f32_e32 v35, v40, v41
	s_nop 1
	v_add_f32_dpp v35, v35, v35 quad_perm:[1,0,3,2] row_mask:0xf bank_mask:0xf bound_ctrl:1
	ds_read_b128 v[176:179], v174 offset:23424
	ds_read_b128 v[180:183], v174 offset:23440
	ds_read_b128 v[184:187], v174 offset:15232
	ds_read_b128 v[188:191], v174 offset:15248
	ds_read_b32 v200, v173 offset:38656
	ds_read_b128 v[192:195], v174 offset:7040
	ds_read_b128 v[196:199], v174 offset:7056
	s_waitcnt lgkmcnt(8)
	v_mul_f32_e32 v26, v0, v26
	v_mul_f32_e32 v27, v1, v27
	v_mul_f32_e32 v28, v2, v28
	v_mul_f32_e32 v29, v3, v29
	v_mul_f32_e32 v30, v4, v30
	v_mul_f32_e32 v31, v5, v31
	v_mul_f32_e32 v32, v6, v32
	v_mul_f32_e32 v34, v7, v34
	v_add_f32_dpp v35, v35, v35 quad_perm:[2,3,0,1] row_mask:0xf bank_mask:0xf bound_ctrl:1
	ds_write_b32 v175, v35
	v_add_u32_e32 v175, v175, v162
	v_fmac_f32_e32 v26, v8, v33
	v_fmac_f32_e32 v27, v9, v33
	v_fmac_f32_e32 v28, v10, v33
	v_fmac_f32_e32 v29, v11, v33
	v_fmac_f32_e32 v30, v12, v33
	v_fmac_f32_e32 v31, v13, v33
	v_fmac_f32_e32 v32, v14, v33
	v_fmac_f32_e32 v34, v15, v33
	v_mul_f32_e32 v40, v16, v26
	v_mul_f32_e32 v41, v17, v27
	v_fmac_f32_e32 v40, v18, v28
	v_fmac_f32_e32 v41, v19, v29
	v_fmac_f32_e32 v40, v20, v30
	v_fmac_f32_e32 v41, v21, v31
	v_fmac_f32_e32 v40, v22, v32
	v_fmac_f32_e32 v41, v23, v34
	v_add_f32_e32 v35, v40, v41
	s_nop 1
	v_add_f32_dpp v35, v35, v35 quad_perm:[1,0,3,2] row_mask:0xf bank_mask:0xf bound_ctrl:1
	ds_read_b128 v[0:3], v174 offset:23552
	ds_read_b128 v[4:7], v174 offset:23568
	ds_read_b128 v[8:11], v174 offset:15360
	ds_read_b128 v[12:15], v174 offset:15376
	ds_read_b32 v33, v173 offset:38912
	ds_read_b128 v[16:19], v174 offset:7168
	ds_read_b128 v[20:23], v174 offset:7184
	s_waitcnt lgkmcnt(8)
	v_mul_f32_e32 v26, v176, v26
	v_mul_f32_e32 v27, v177, v27
	v_mul_f32_e32 v28, v178, v28
	v_mul_f32_e32 v29, v179, v29
	v_mul_f32_e32 v30, v180, v30
	v_mul_f32_e32 v31, v181, v31
	v_mul_f32_e32 v32, v182, v32
	v_mul_f32_e32 v34, v183, v34
	v_add_f32_dpp v35, v35, v35 quad_perm:[2,3,0,1] row_mask:0xf bank_mask:0xf bound_ctrl:1
	ds_write_b32 v175, v35
	v_add_u32_e32 v175, v175, v162
	v_fmac_f32_e32 v26, v184, v200
	v_fmac_f32_e32 v27, v185, v200
	v_fmac_f32_e32 v28, v186, v200
	v_fmac_f32_e32 v29, v187, v200
	v_fmac_f32_e32 v30, v188, v200
	v_fmac_f32_e32 v31, v189, v200
	v_fmac_f32_e32 v32, v190, v200
	v_fmac_f32_e32 v34, v191, v200
	v_mul_f32_e32 v40, v192, v26
	v_mul_f32_e32 v41, v193, v27
	v_fmac_f32_e32 v40, v194, v28
	v_fmac_f32_e32 v41, v195, v29
	v_fmac_f32_e32 v40, v196, v30
	v_fmac_f32_e32 v41, v197, v31
	v_fmac_f32_e32 v40, v198, v32
	v_fmac_f32_e32 v41, v199, v34
	v_add_f32_e32 v35, v40, v41
	s_nop 1
	v_add_f32_dpp v35, v35, v35 quad_perm:[1,0,3,2] row_mask:0xf bank_mask:0xf bound_ctrl:1
	ds_read_b128 v[176:179], v174 offset:23680
	ds_read_b128 v[180:183], v174 offset:23696
	ds_read_b128 v[184:187], v174 offset:15488
	ds_read_b128 v[188:191], v174 offset:15504
	ds_read_b32 v200, v173 offset:39168
	ds_read_b128 v[192:195], v174 offset:7296
	ds_read_b128 v[196:199], v174 offset:7312
	s_waitcnt lgkmcnt(8)
; #define GLA_LD(t_, aq, kq, qq, vq) do { const int tt_ = (t_); vq = Bs[6144 + tt_ * 64 + pp]; \
;             _Pragma("unroll") for (int u = 0; u < 2; ++u) { aq[u] = *(const LAS f32x4*)(Bs + 4096 + tt_ * 32 + k0 + 4 * u); kq[u] = *(const LAS f32x4*)(Bs + 2048 + tt_ * 32 + k0 + 4 * u); qq[u] = *(const LAS f32x4*)(Bs + tt_ * 32 + k0 + 4 * u); } } while (0)
; #define GLA_STEP(t_, aq, kq, qq, vq) do { float y = 0.f; \
;             _Pragma("unroll") for (int u = 0; u < 2; ++u) _Pragma("unroll") for (int j = 0; j < 4; ++j) { S[4 * u + j] = aq[u][j] * S[4 * u + j] + kq[u][j] * vq; y += qq[u][j] * S[4 * u + j]; } \
;             y += dpp_f(y, 0xB1); y += dpp_f(y, 0x4E); ydst[(t_) * ystride] = y; } while (0)
; __device__ __forceinline__ void gla_job(const bf16_t* P, bf16_t* Y, int l, int b, int h, LAS float* lds, int wave_s) {
;     ...
;             GLA_LD(0, a0_, k0_, q0_, v0_);
;             for (int t = 0; t < TC; t += 2) {
;                 GLA_LD(t + 1, a1_, k1_, q1_, v1_);
;                 GLA_STEP(t, a0_, k0_, q0_, v0_);
;                 GLA_LD(t + 2 < TC ? t + 2 : t + 1, a0_, k0_, q0_, v0_);
;                 GLA_STEP(t + 1, a1_, k1_, q1_, v1_);
;             }
	v_mul_f32_e32 v26, v0, v26
	v_mul_f32_e32 v27, v1, v27
	v_mul_f32_e32 v28, v2, v28
	v_mul_f32_e32 v29, v3, v29
	v_mul_f32_e32 v30, v4, v30
	v_mul_f32_e32 v31, v5, v31
	v_mul_f32_e32 v32, v6, v32
	v_mul_f32_e32 v34, v7, v34
	v_add_f32_dpp v35, v35, v35 quad_perm:[2,3,0,1] row_mask:0xf bank_mask:0xf bound_ctrl:1
	ds_write_b32 v175, v35
	v_add_u32_e32 v175, v175, v162
	v_fmac_f32_e32 v26, v8, v33
	v_fmac_f32_e32 v27, v9, v33
	v_fmac_f32_e32 v28, v10, v33
	v_fmac_f32_e32 v29, v11, v33
	v_fmac_f32_e32 v30, v12, v33
	v_fmac_f32_e32 v31, v13, v33
	v_fmac_f32_e32 v32, v14, v33
	v_fmac_f32_e32 v34, v15, v33
	v_mul_f32_e32 v40, v16, v26
	v_mul_f32_e32 v41, v17, v27
	v_fmac_f32_e32 v40, v18, v28
	v_fmac_f32_e32 v41, v19, v29
	v_fmac_f32_e32 v40, v20, v30
	v_fmac_f32_e32 v41, v21, v31
	v_fmac_f32_e32 v40, v22, v32
	v_fmac_f32_e32 v41, v23, v34
	v_add_f32_e32 v35, v40, v41
	s_nop 1
	v_add_f32_dpp v35, v35, v35 quad_perm:[1,0,3,2] row_mask:0xf bank_mask:0xf bound_ctrl:1
	ds_read_b128 v[0:3], v174 offset:23808
	ds_read_b128 v[4:7], v174 offset:23824
	ds_read_b128 v[8:11], v174 offset:15616
	ds_read_b128 v[12:15], v174 offset:15632
	ds_read_b32 v33, v173 offset:39424
	ds_read_b128 v[16:19], v174 offset:7424
	ds_read_b128 v[20:23], v174 offset:7440
	s_waitcnt lgkmcnt(8)
	v_mul_f32_e32 v26, v176, v26
	v_mul_f32_e32 v27, v177, v27
	v_mul_f32_e32 v28, v178, v28
	v_mul_f32_e32 v29, v179, v29
	v_mul_f32_e32 v30, v180, v30
	v_mul_f32_e32 v31, v181, v31
	v_mul_f32_e32 v32, v182, v32
	v_mul_f32_e32 v34, v183, v34
	v_add_f32_dpp v35, v35, v35 quad_perm:[2,3,0,1] row_mask:0xf bank_mask:0xf bound_ctrl:1
	ds_write_b32 v175, v35
	v_add_u32_e32 v175, v175, v162
	v_fmac_f32_e32 v26, v184, v200
	v_fmac_f32_e32 v27, v185, v200
	v_fmac_f32_e32 v28, v186, v200
	v_fmac_f32_e32 v29, v187, v200
	v_fmac_f32_e32 v30, v188, v200
	v_fmac_f32_e32 v31, v189, v200
	v_fmac_f32_e32 v32, v190, v200
	v_fmac_f32_e32 v34, v191, v200
	v_mul_f32_e32 v40, v192, v26
	v_mul_f32_e32 v41, v193, v27
	v_fmac_f32_e32 v40, v194, v28
	v_fmac_f32_e32 v41, v195, v29
	v_fmac_f32_e32 v40, v196, v30
	v_fmac_f32_e32 v41, v197, v31
	v_fmac_f32_e32 v40, v198, v32
	v_fmac_f32_e32 v41, v199, v34
	v_add_f32_e32 v35, v40, v41
	s_nop 1
	v_add_f32_dpp v35, v35, v35 quad_perm:[1,0,3,2] row_mask:0xf bank_mask:0xf bound_ctrl:1
	ds_read_b128 v[176:179], v174 offset:23936
	ds_read_b128 v[180:183], v174 offset:23952
	ds_read_b128 v[184:187], v174 offset:15744
	ds_read_b128 v[188:191], v174 offset:15760
	ds_read_b32 v200, v173 offset:39680
	ds_read_b128 v[192:195], v174 offset:7552
	ds_read_b128 v[196:199], v174 offset:7568
	s_waitcnt lgkmcnt(8)
	v_mul_f32_e32 v26, v0, v26
	v_mul_f32_e32 v27, v1, v27
	v_mul_f32_e32 v28, v2, v28
	v_mul_f32_e32 v29, v3, v29
	v_mul_f32_e32 v30, v4, v30
	v_mul_f32_e32 v31, v5, v31
	v_mul_f32_e32 v32, v6, v32
	v_mul_f32_e32 v34, v7, v34
	v_add_f32_dpp v35, v35, v35 quad_perm:[2,3,0,1] row_mask:0xf bank_mask:0xf bound_ctrl:1
	ds_write_b32 v175, v35
	v_add_u32_e32 v175, v175, v162
	v_fmac_f32_e32 v26, v8, v33
	v_fmac_f32_e32 v27, v9, v33
	v_fmac_f32_e32 v28, v10, v33
	v_fmac_f32_e32 v29, v11, v33
	v_fmac_f32_e32 v30, v12, v33
	v_fmac_f32_e32 v31, v13, v33
	v_fmac_f32_e32 v32, v14, v33
	v_fmac_f32_e32 v34, v15, v33
	v_mul_f32_e32 v40, v16, v26
	v_mul_f32_e32 v41, v17, v27
	v_fmac_f32_e32 v40, v18, v28
	v_fmac_f32_e32 v41, v19, v29
	v_fmac_f32_e32 v40, v20, v30
	v_fmac_f32_e32 v41, v21, v31
	v_fmac_f32_e32 v40, v22, v32
	v_fmac_f32_e32 v41, v23, v34
	v_add_f32_e32 v35, v40, v41
	s_nop 1
	v_add_f32_dpp v35, v35, v35 quad_perm:[1,0,3,2] row_mask:0xf bank_mask:0xf bound_ctrl:1
	ds_read_b128 v[0:3], v174 offset:24064
	ds_read_b128 v[4:7], v174 offset:24080
	ds_read_b128 v[8:11], v174 offset:15872
	ds_read_b128 v[12:15], v174 offset:15888
	ds_read_b32 v33, v173 offset:39936
	ds_read_b128 v[16:19], v174 offset:7680
	ds_read_b128 v[20:23], v174 offset:7696
	s_waitcnt lgkmcnt(8)
	v_mul_f32_e32 v26, v176, v26
	v_mul_f32_e32 v27, v177, v27
	v_mul_f32_e32 v28, v178, v28
	v_mul_f32_e32 v29, v179, v29
	v_mul_f32_e32 v30, v180, v30
	v_mul_f32_e32 v31, v181, v31
	v_mul_f32_e32 v32, v182, v32
	v_mul_f32_e32 v34, v183, v34
	v_add_f32_dpp v35, v35, v35 quad_perm:[2,3,0,1] row_mask:0xf bank_mask:0xf bound_ctrl:1
	ds_write_b32 v175, v35
	v_add_u32_e32 v175, v175, v162
	v_fmac_f32_e32 v26, v184, v200
	v_fmac_f32_e32 v27, v185, v200
	v_fmac_f32_e32 v28, v186, v200
	v_fmac_f32_e32 v29, v187, v200
	v_fmac_f32_e32 v30, v188, v200
	v_fmac_f32_e32 v31, v189, v200
	v_fmac_f32_e32 v32, v190, v200
	v_fmac_f32_e32 v34, v191, v200
	v_mul_f32_e32 v40, v192, v26
	v_mul_f32_e32 v41, v193, v27
	v_fmac_f32_e32 v40, v194, v28
	v_fmac_f32_e32 v41, v195, v29
	v_fmac_f32_e32 v40, v196, v30
	v_fmac_f32_e32 v41, v197, v31
	v_fmac_f32_e32 v40, v198, v32
	v_fmac_f32_e32 v41, v199, v34
	v_add_f32_e32 v35, v40, v41
	s_nop 1
	v_add_f32_dpp v35, v35, v35 quad_perm:[1,0,3,2] row_mask:0xf bank_mask:0xf bound_ctrl:1
	ds_read_b128 v[176:179], v174 offset:24192
	ds_read_b128 v[180:183], v174 offset:24208
	ds_read_b128 v[184:187], v174 offset:16000
	ds_read_b128 v[188:191], v174 offset:16016
	ds_read_b32 v200, v173 offset:40192
	ds_read_b128 v[192:195], v174 offset:7808
	ds_read_b128 v[196:199], v174 offset:7824
	s_waitcnt lgkmcnt(8)
; #define GLA_LD(t_, aq, kq, qq, vq) do { const int tt_ = (t_); vq = Bs[6144 + tt_ * 64 + pp]; \
;             _Pragma("unroll") for (int u = 0; u < 2; ++u) { aq[u] = *(const LAS f32x4*)(Bs + 4096 + tt_ * 32 + k0 + 4 * u); kq[u] = *(const LAS f32x4*)(Bs + 2048 + tt_ * 32 + k0 + 4 * u); qq[u] = *(const LAS f32x4*)(Bs + tt_ * 32 + k0 + 4 * u); } } while (0)
; #define GLA_STEP(t_, aq, kq, qq, vq) do { float y = 0.f; \
;             _Pragma("unroll") for (int u = 0; u < 2; ++u) _Pragma("unroll") for (int j = 0; j < 4; ++j) { S[4 * u + j] = aq[u][j] * S[4 * u + j] + kq[u][j] * vq; y += qq[u][j] * S[4 * u + j]; } \
;             y += dpp_f(y, 0xB1); y += dpp_f(y, 0x4E); ydst[(t_) * ystride] = y; } while (0)
; __device__ __forceinline__ void gla_job(const bf16_t* P, bf16_t* Y, int l, int b, int h, LAS float* lds, int wave_s) {
;     ...
;             GLA_LD(0, a0_, k0_, q0_, v0_);
;             for (int t = 0; t < TC; t += 2) {
;                 GLA_LD(t + 1, a1_, k1_, q1_, v1_);
;                 GLA_STEP(t, a0_, k0_, q0_, v0_);
;                 GLA_LD(t + 2 < TC ? t + 2 : t + 1, a0_, k0_, q0_, v0_);
;                 GLA_STEP(t + 1, a1_, k1_, q1_, v1_);
;             }
	v_mul_f32_e32 v26, v0, v26
	v_mul_f32_e32 v27, v1, v27
	v_mul_f32_e32 v28, v2, v28
	v_mul_f32_e32 v29, v3, v29
	v_mul_f32_e32 v30, v4, v30
	v_mul_f32_e32 v31, v5, v31
	v_mul_f32_e32 v32, v6, v32
	v_mul_f32_e32 v34, v7, v34
	v_add_f32_dpp v35, v35, v35 quad_perm:[2,3,0,1] row_mask:0xf bank_mask:0xf bound_ctrl:1
	ds_write_b32 v175, v35
	v_add_u32_e32 v175, v175, v162
	v_fmac_f32_e32 v26, v8, v33
	v_fmac_f32_e32 v27, v9, v33
	v_fmac_f32_e32 v28, v10, v33
	v_fmac_f32_e32 v29, v11, v33
	v_fmac_f32_e32 v30, v12, v33
	v_fmac_f32_e32 v31, v13, v33
	v_fmac_f32_e32 v32, v14, v33
	v_fmac_f32_e32 v34, v15, v33
	v_mul_f32_e32 v40, v16, v26
	v_mul_f32_e32 v41, v17, v27
	v_fmac_f32_e32 v40, v18, v28
	v_fmac_f32_e32 v41, v19, v29
	v_fmac_f32_e32 v40, v20, v30
	v_fmac_f32_e32 v41, v21, v31
	v_fmac_f32_e32 v40, v22, v32
	v_fmac_f32_e32 v41, v23, v34
	v_add_f32_e32 v35, v40, v41
	s_nop 1
	v_add_f32_dpp v35, v35, v35 quad_perm:[1,0,3,2] row_mask:0xf bank_mask:0xf bound_ctrl:1
	ds_read_b128 v[0:3], v174 offset:24320
	ds_read_b128 v[4:7], v174 offset:24336
	ds_read_b128 v[8:11], v174 offset:16128
	ds_read_b128 v[12:15], v174 offset:16144
	ds_read_b32 v33, v173 offset:40448
	ds_read_b128 v[16:19], v174 offset:7936
	ds_read_b128 v[20:23], v174 offset:7952
	s_waitcnt lgkmcnt(8)
	v_mul_f32_e32 v26, v176, v26
	v_mul_f32_e32 v27, v177, v27
	v_mul_f32_e32 v28, v178, v28
	v_mul_f32_e32 v29, v179, v29
	v_mul_f32_e32 v30, v180, v30
	v_mul_f32_e32 v31, v181, v31
	v_mul_f32_e32 v32, v182, v32
	v_mul_f32_e32 v34, v183, v34
	v_add_f32_dpp v35, v35, v35 quad_perm:[2,3,0,1] row_mask:0xf bank_mask:0xf bound_ctrl:1
	ds_write_b32 v175, v35
	v_add_u32_e32 v175, v175, v162
	v_fmac_f32_e32 v26, v184, v200
	v_fmac_f32_e32 v27, v185, v200
	v_fmac_f32_e32 v28, v186, v200
	v_fmac_f32_e32 v29, v187, v200
	v_fmac_f32_e32 v30, v188, v200
	v_fmac_f32_e32 v31, v189, v200
	v_fmac_f32_e32 v32, v190, v200
	v_fmac_f32_e32 v34, v191, v200
	v_mul_f32_e32 v40, v192, v26
	v_mul_f32_e32 v41, v193, v27
	v_fmac_f32_e32 v40, v194, v28
	v_fmac_f32_e32 v41, v195, v29
	v_fmac_f32_e32 v40, v196, v30
	v_fmac_f32_e32 v41, v197, v31
	v_fmac_f32_e32 v40, v198, v32
	v_fmac_f32_e32 v41, v199, v34
	v_add_f32_e32 v35, v40, v41
	s_nop 1
	v_add_f32_dpp v35, v35, v35 quad_perm:[1,0,3,2] row_mask:0xf bank_mask:0xf bound_ctrl:1
	ds_read_b128 v[176:179], v174 offset:24448
	ds_read_b128 v[180:183], v174 offset:24464
	ds_read_b128 v[184:187], v174 offset:16256
	ds_read_b128 v[188:191], v174 offset:16272
	ds_read_b32 v200, v173 offset:40704
	ds_read_b128 v[192:195], v174 offset:8064
	ds_read_b128 v[196:199], v174 offset:8080
	s_waitcnt lgkmcnt(8)
	v_mul_f32_e32 v26, v0, v26
	v_mul_f32_e32 v27, v1, v27
	v_mul_f32_e32 v28, v2, v28
	v_mul_f32_e32 v29, v3, v29
	v_mul_f32_e32 v30, v4, v30
	v_mul_f32_e32 v31, v5, v31
	v_mul_f32_e32 v32, v6, v32
	v_mul_f32_e32 v34, v7, v34
	v_add_f32_dpp v35, v35, v35 quad_perm:[2,3,0,1] row_mask:0xf bank_mask:0xf bound_ctrl:1
	ds_write_b32 v175, v35
	v_add_u32_e32 v175, v175, v162
	v_fmac_f32_e32 v26, v8, v33
	v_fmac_f32_e32 v27, v9, v33
	v_fmac_f32_e32 v28, v10, v33
	v_fmac_f32_e32 v29, v11, v33
	v_fmac_f32_e32 v30, v12, v33
	v_fmac_f32_e32 v31, v13, v33
	v_fmac_f32_e32 v32, v14, v33
	v_fmac_f32_e32 v34, v15, v33
	v_mul_f32_e32 v40, v16, v26
	v_mul_f32_e32 v41, v17, v27
	v_fmac_f32_e32 v40, v18, v28
	v_fmac_f32_e32 v41, v19, v29
	v_fmac_f32_e32 v40, v20, v30
	v_fmac_f32_e32 v41, v21, v31
	v_fmac_f32_e32 v40, v22, v32
	v_fmac_f32_e32 v41, v23, v34
	v_add_f32_e32 v35, v40, v41
	s_nop 1
	v_add_f32_dpp v35, v35, v35 quad_perm:[1,0,3,2] row_mask:0xf bank_mask:0xf bound_ctrl:1
	s_waitcnt lgkmcnt(1)
	v_mul_f32_e32 v26, v176, v26
	v_mul_f32_e32 v27, v177, v27
	v_mul_f32_e32 v28, v178, v28
	v_mul_f32_e32 v29, v179, v29
	v_mul_f32_e32 v30, v180, v30
	v_mul_f32_e32 v31, v181, v31
	v_mul_f32_e32 v32, v182, v32
	v_mul_f32_e32 v34, v183, v34
	v_add_f32_dpp v35, v35, v35 quad_perm:[2,3,0,1] row_mask:0xf bank_mask:0xf bound_ctrl:1
	ds_write_b32 v175, v35
	v_add_u32_e32 v175, v175, v162
	v_fmac_f32_e32 v26, v184, v200
	v_fmac_f32_e32 v27, v185, v200
	v_fmac_f32_e32 v28, v186, v200
	v_fmac_f32_e32 v29, v187, v200
	v_fmac_f32_e32 v30, v188, v200
	v_fmac_f32_e32 v31, v189, v200
	v_fmac_f32_e32 v32, v190, v200
	v_fmac_f32_e32 v34, v191, v200
	v_mul_f32_e32 v40, v192, v26
	v_mul_f32_e32 v41, v193, v27
	v_fmac_f32_e32 v40, v194, v28
	v_fmac_f32_e32 v41, v195, v29
	v_fmac_f32_e32 v40, v196, v30
	v_fmac_f32_e32 v41, v197, v31
	v_fmac_f32_e32 v40, v198, v32
	v_fmac_f32_e32 v41, v199, v34
	v_add_f32_e32 v35, v40, v41
	s_nop 1
	v_add_f32_dpp v35, v35, v35 quad_perm:[1,0,3,2] row_mask:0xf bank_mask:0xf bound_ctrl:1
	s_nop 1
	v_add_f32_dpp v35, v35, v35 quad_perm:[2,3,0,1] row_mask:0xf bank_mask:0xf bound_ctrl:1
	ds_write_b32 v175, v35
	s_setprio 0
	s_branch .LBB0_1037
